# GEMM K loops: first-half fragment reads issued in the order the MFMAs consume them, per-MFMA counted lgkmcnt
# speedup vs baseline: 1.0356x; 1.0057x over previous
; #define MFMA(a, b, c) __builtin_amdgcn_mfma_f32_32x32x16_bf16((a), (b), (c), 0, 0, 0)
; template <class Epi, class ColV>
; DI void gemm_tile(const bf16_t* __restrict__ A, int lda, const bf16_t* __restrict__ Bt, int ldb, int K, int m0, int n0, unsigned char* smem, Epi epi, ColV colv, const bf16_t* __restrict__ HYT = nullptr) {
;     ...
;     auto step = [&](int kt, u32x4 (&ldset)[8], const u32x4 (&stset)[8]) {
;         const int buf = kt & 1;
;         if (kt + 2 < nk) gload(ldset, kt + 2);
;         const bf16_t* Ab = As + (buf * 128 + 64 * wr + li) * LS + 8 * lh;
;         const bf16_t* Bb = Bs + (buf * 128 + 64 * wc + li) * LS + 8 * lh;
;         bf16x8 fa[2][2], fb[2][2], ga[2][2], gb[2][2];
; #pragma unroll
;         for (int k2 = 0; k2 < 2; ++k2) { fa[k2][0] = ld8(Ab + 16 * k2); fa[k2][1] = ld8(Ab + 32 * LS + 16 * k2); fb[k2][0] = ld8(Bb + 16 * k2); fb[k2][1] = ld8(Bb + 32 * LS + 16 * k2); }
;         __builtin_amdgcn_sched_barrier(0);
; #pragma unroll
;         for (int k2 = 0; k2 < 2; ++k2) {
;             acc[0][0] = MFMA(fa[k2][0], fb[k2][0], acc[0][0]); acc[0][1] = MFMA(fa[k2][0], fb[k2][1], acc[0][1]);
;             acc[1][0] = MFMA(fa[k2][1], fb[k2][0], acc[1][0]); acc[1][1] = MFMA(fa[k2][1], fb[k2][1], acc[1][1]);
;         }
; #pragma unroll
;         for (int k2 = 0; k2 < 2; ++k2) { const int ks = 2 + k2; ga[k2][0] = ld8(Ab + 16 * ks); ga[k2][1] = ld8(Ab + 32 * LS + 16 * ks); gb[k2][0] = ld8(Bb + 16 * ks); gb[k2][1] = ld8(Bb + 32 * LS + 16 * ks); }
; #pragma unroll
;         for (int k2 = 0; k2 < 2; ++k2) {
;             acc[0][0] = MFMA(ga[k2][0], gb[k2][0], acc[0][0]); acc[0][1] = MFMA(ga[k2][0], gb[k2][1], acc[0][1]);
;             acc[1][0] = MFMA(ga[k2][1], gb[k2][0], acc[1][0]); acc[1][1] = MFMA(ga[k2][1], gb[k2][1], acc[1][1]);
;         }
;         if (kt + 1 < nk) sstore(stset, buf ^ 1, kt + 1);
; #pragma unroll
;         for (int i = 0; i < 8; ++i) { __builtin_amdgcn_sched_group_barrier(0x008, 1, 0); __builtin_amdgcn_sched_group_barrier(0x100, 1, 0); }
; #pragma unroll
;         for (int i = 0; i < 8; ++i) { __builtin_amdgcn_sched_group_barrier(0x008, 1, 0); __builtin_amdgcn_sched_group_barrier(0x200, 1, 0); }
;         __builtin_amdgcn_sched_barrier(0);
;         __syncthreads();
;     };
.Lg3_phase11:
	ds_read_b128 v[174:177], v194
	ds_read_b128 v[210:213], v195 offset:36864
	ds_read_b128 v[218:221], v195 offset:41472
	ds_read_b128 v[202:205], v194 offset:4608
	ds_read_b128 v[178:181], v194 offset:32
	ds_read_b128 v[222:225], v195 offset:41504
	ds_read_b128 v[206:209], v194 offset:4640
	ds_read_b128 v[214:217], v195 offset:36896
	s_waitcnt lgkmcnt(6)
	v_mfma_f32_32x32x16_bf16 v[52:67], v[174:177], v[210:213], v[52:67]
	global_load_dwordx4 v[68:71], v[164:165], off offset:384
	s_waitcnt lgkmcnt(5)
	v_mfma_f32_32x32x16_bf16 v[36:51], v[174:177], v[218:221], v[36:51]
	global_load_dwordx4 v[72:75], v[162:163], off offset:384
	s_waitcnt lgkmcnt(4)
	v_mfma_f32_32x32x16_bf16 v[4:19], v[202:205], v[218:221], v[4:19]
	global_load_dwordx4 v[76:79], v[160:161], off offset:384
	s_waitcnt lgkmcnt(2)
	v_mfma_f32_32x32x16_bf16 v[36:51], v[178:181], v[222:225], v[36:51]
	global_load_dwordx4 v[80:83], v[158:159], off offset:384
	s_waitcnt lgkmcnt(1)
	v_mfma_f32_32x32x16_bf16 v[4:19], v[206:209], v[222:225], v[4:19]
	global_load_dwordx4 v[84:87], v[156:157], off offset:384
	ds_read_b128 v[222:225], v195 offset:41568
	ds_read_b128 v[174:177], v194 offset:4672
	v_mfma_f32_32x32x16_bf16 v[20:35], v[202:205], v[210:213], v[20:35]
	global_load_dwordx4 v[92:95], v[154:155], off offset:384
	ds_read_b128 v[210:213], v194 offset:4704
	ds_read_b128 v[202:205], v194 offset:64
	s_waitcnt lgkmcnt(4)
	v_mfma_f32_32x32x16_bf16 v[52:67], v[178:181], v[214:217], v[52:67]
	global_load_dwordx4 v[104:107], v[152:153], off offset:384
	ds_read_b128 v[218:221], v195 offset:36960
	ds_read_b128 v[178:181], v195 offset:41536
	v_mfma_f32_32x32x16_bf16 v[20:35], v[206:209], v[214:217], v[20:35]
	global_load_dwordx4 v[112:115], v[146:147], off offset:384
	ds_read_b128 v[214:217], v195 offset:36928
	ds_read_b128 v[206:209], v194 offset:96
	s_waitcnt lgkmcnt(1)
	v_mfma_f32_32x32x16_bf16 v[52:67], v[202:205], v[214:217], v[52:67]
	s_waitcnt vmcnt(23)
	ds_write_b128 v190, v[88:91] offset:18432
	v_mfma_f32_32x32x16_bf16 v[36:51], v[202:205], v[178:181], v[36:51]
	s_waitcnt vmcnt(22)
	ds_write_b128 v190, v[96:99] offset:55296
	v_mfma_f32_32x32x16_bf16 v[20:35], v[174:177], v[214:217], v[20:35]
	s_waitcnt vmcnt(21)
	ds_write_b128 v191, v[100:103] offset:18432
	v_mfma_f32_32x32x16_bf16 v[4:19], v[174:177], v[178:181], v[4:19]
	s_waitcnt vmcnt(20)
	ds_write_b128 v191, v[108:111] offset:55296
	s_waitcnt lgkmcnt(4)
	v_mfma_f32_32x32x16_bf16 v[52:67], v[206:209], v[218:221], v[52:67]
	s_waitcnt vmcnt(19)
	ds_write_b128 v192, v[116:119] offset:18432
	v_mfma_f32_32x32x16_bf16 v[36:51], v[206:209], v[222:225], v[36:51]
	s_waitcnt vmcnt(18)
	ds_write_b128 v192, v[120:123] offset:55296
	v_mfma_f32_32x32x16_bf16 v[20:35], v[210:213], v[218:221], v[20:35]
	s_waitcnt vmcnt(17)
	ds_write_b128 v193, v[124:127] offset:18432
	v_mfma_f32_32x32x16_bf16 v[4:19], v[210:213], v[222:225], v[4:19]
	s_waitcnt vmcnt(16)
	ds_write_b128 v193, v[128:131] offset:55296
	s_waitcnt lgkmcnt(0)
	s_barrier
	ds_read_b128 v[174:177], v196
	ds_read_b128 v[210:213], v197 offset:36864
	ds_read_b128 v[218:221], v197 offset:41472
	ds_read_b128 v[202:205], v196 offset:4608
	ds_read_b128 v[178:181], v196 offset:32
	ds_read_b128 v[222:225], v197 offset:41504
	ds_read_b128 v[206:209], v196 offset:4640
	ds_read_b128 v[214:217], v197 offset:36896
	s_waitcnt lgkmcnt(6)
	v_mfma_f32_32x32x16_bf16 v[52:67], v[174:177], v[210:213], v[52:67]
	global_load_dwordx4 v[88:91], v[164:165], off offset:512
	s_waitcnt lgkmcnt(5)
	v_mfma_f32_32x32x16_bf16 v[36:51], v[174:177], v[218:221], v[36:51]
	global_load_dwordx4 v[96:99], v[162:163], off offset:512
	s_waitcnt lgkmcnt(4)
	v_mfma_f32_32x32x16_bf16 v[4:19], v[202:205], v[218:221], v[4:19]
	global_load_dwordx4 v[100:103], v[160:161], off offset:512
	s_waitcnt lgkmcnt(2)
	v_mfma_f32_32x32x16_bf16 v[36:51], v[178:181], v[222:225], v[36:51]
	global_load_dwordx4 v[108:111], v[158:159], off offset:512
	s_waitcnt lgkmcnt(1)
	v_mfma_f32_32x32x16_bf16 v[4:19], v[206:209], v[222:225], v[4:19]
	global_load_dwordx4 v[116:119], v[156:157], off offset:512
	ds_read_b128 v[222:225], v197 offset:41568
	ds_read_b128 v[174:177], v196 offset:4672
	v_mfma_f32_32x32x16_bf16 v[20:35], v[202:205], v[210:213], v[20:35]
	global_load_dwordx4 v[120:123], v[154:155], off offset:512
	ds_read_b128 v[210:213], v196 offset:4704
	ds_read_b128 v[202:205], v196 offset:64
	s_waitcnt lgkmcnt(4)
	v_mfma_f32_32x32x16_bf16 v[52:67], v[178:181], v[214:217], v[52:67]
	global_load_dwordx4 v[124:127], v[152:153], off offset:512
	ds_read_b128 v[218:221], v197 offset:36960
	ds_read_b128 v[178:181], v197 offset:41536
	v_mfma_f32_32x32x16_bf16 v[20:35], v[206:209], v[214:217], v[20:35]
	global_load_dwordx4 v[128:131], v[146:147], off offset:512
	ds_read_b128 v[214:217], v197 offset:36928
	ds_read_b128 v[206:209], v196 offset:96
	s_waitcnt lgkmcnt(1)
	v_mfma_f32_32x32x16_bf16 v[52:67], v[202:205], v[214:217], v[52:67]
	s_waitcnt vmcnt(23)
	ds_write_b128 v190, v[132:135]
	v_mfma_f32_32x32x16_bf16 v[36:51], v[202:205], v[178:181], v[36:51]
	s_waitcnt vmcnt(22)
	ds_write_b128 v190, v[136:139] offset:36864
	v_mfma_f32_32x32x16_bf16 v[20:35], v[174:177], v[214:217], v[20:35]
	s_waitcnt vmcnt(21)
	ds_write_b128 v191, v[140:143]
	v_mfma_f32_32x32x16_bf16 v[4:19], v[174:177], v[178:181], v[4:19]
	s_waitcnt vmcnt(20)
	ds_write_b128 v191, v[198:201] offset:36864
	s_waitcnt lgkmcnt(4)
	v_mfma_f32_32x32x16_bf16 v[52:67], v[206:209], v[218:221], v[52:67]
	s_waitcnt vmcnt(19)
	ds_write_b128 v192, v[226:229]
	v_mfma_f32_32x32x16_bf16 v[36:51], v[206:209], v[222:225], v[36:51]
	s_waitcnt vmcnt(18)
	ds_write_b128 v192, v[230:233] offset:36864
	v_mfma_f32_32x32x16_bf16 v[20:35], v[210:213], v[218:221], v[20:35]
	s_waitcnt vmcnt(17)
	ds_write_b128 v193, v[242:245]
	v_mfma_f32_32x32x16_bf16 v[4:19], v[210:213], v[222:225], v[4:19]
	s_waitcnt vmcnt(16)
	ds_write_b128 v193, v[246:249] offset:36864
	s_waitcnt lgkmcnt(0)
	s_barrier
; #define MFMA(a, b, c) __builtin_amdgcn_mfma_f32_32x32x16_bf16((a), (b), (c), 0, 0, 0)
; template <class Epi, class ColV>
; DI void gemm_tile(const bf16_t* __restrict__ A, int lda, const bf16_t* __restrict__ Bt, int ldb, int K, int m0, int n0, unsigned char* smem, Epi epi, ColV colv, const bf16_t* __restrict__ HYT = nullptr) {
;     ...
;     auto step = [&](int kt, u32x4 (&ldset)[8], const u32x4 (&stset)[8]) {
;         const int buf = kt & 1;
;         if (kt + 2 < nk) gload(ldset, kt + 2);
;         const bf16_t* Ab = As + (buf * 128 + 64 * wr + li) * LS + 8 * lh;
;         const bf16_t* Bb = Bs + (buf * 128 + 64 * wc + li) * LS + 8 * lh;
;         bf16x8 fa[2][2], fb[2][2], ga[2][2], gb[2][2];
; #pragma unroll
;         for (int k2 = 0; k2 < 2; ++k2) { fa[k2][0] = ld8(Ab + 16 * k2); fa[k2][1] = ld8(Ab + 32 * LS + 16 * k2); fb[k2][0] = ld8(Bb + 16 * k2); fb[k2][1] = ld8(Bb + 32 * LS + 16 * k2); }
;         __builtin_amdgcn_sched_barrier(0);
; #pragma unroll
;         for (int k2 = 0; k2 < 2; ++k2) {
;             acc[0][0] = MFMA(fa[k2][0], fb[k2][0], acc[0][0]); acc[0][1] = MFMA(fa[k2][0], fb[k2][1], acc[0][1]);
;             acc[1][0] = MFMA(fa[k2][1], fb[k2][0], acc[1][0]); acc[1][1] = MFMA(fa[k2][1], fb[k2][1], acc[1][1]);
;         }
; #pragma unroll
;         for (int k2 = 0; k2 < 2; ++k2) { const int ks = 2 + k2; ga[k2][0] = ld8(Ab + 16 * ks); ga[k2][1] = ld8(Ab + 32 * LS + 16 * ks); gb[k2][0] = ld8(Bb + 16 * ks); gb[k2][1] = ld8(Bb + 32 * LS + 16 * ks); }
; #pragma unroll
;         for (int k2 = 0; k2 < 2; ++k2) {
;             acc[0][0] = MFMA(ga[k2][0], gb[k2][0], acc[0][0]); acc[0][1] = MFMA(ga[k2][0], gb[k2][1], acc[0][1]);
;             acc[1][0] = MFMA(ga[k2][1], gb[k2][0], acc[1][0]); acc[1][1] = MFMA(ga[k2][1], gb[k2][1], acc[1][1]);
;         }
;         if (kt + 1 < nk) sstore(stset, buf ^ 1, kt + 1);
; #pragma unroll
;         for (int i = 0; i < 8; ++i) { __builtin_amdgcn_sched_group_barrier(0x008, 1, 0); __builtin_amdgcn_sched_group_barrier(0x100, 1, 0); }
; #pragma unroll
;         for (int i = 0; i < 8; ++i) { __builtin_amdgcn_sched_group_barrier(0x008, 1, 0); __builtin_amdgcn_sched_group_barrier(0x200, 1, 0); }
;         __builtin_amdgcn_sched_barrier(0);
;         __syncthreads();
;     };
	ds_read_b128 v[174:177], v194
	ds_read_b128 v[210:213], v195 offset:36864
	ds_read_b128 v[218:221], v195 offset:41472
	ds_read_b128 v[202:205], v194 offset:4608
	ds_read_b128 v[178:181], v194 offset:32
	ds_read_b128 v[222:225], v195 offset:41504
	ds_read_b128 v[206:209], v194 offset:4640
	ds_read_b128 v[214:217], v195 offset:36896
	s_waitcnt lgkmcnt(6)
	v_mfma_f32_32x32x16_bf16 v[52:67], v[174:177], v[210:213], v[52:67]
	global_load_dwordx4 v[132:135], v[164:165], off offset:640
	s_waitcnt lgkmcnt(5)
	v_mfma_f32_32x32x16_bf16 v[36:51], v[174:177], v[218:221], v[36:51]
	global_load_dwordx4 v[136:139], v[162:163], off offset:640
	s_waitcnt lgkmcnt(4)
	v_mfma_f32_32x32x16_bf16 v[4:19], v[202:205], v[218:221], v[4:19]
	global_load_dwordx4 v[140:143], v[160:161], off offset:640
	s_waitcnt lgkmcnt(2)
	v_mfma_f32_32x32x16_bf16 v[36:51], v[178:181], v[222:225], v[36:51]
	global_load_dwordx4 v[198:201], v[158:159], off offset:640
	s_waitcnt lgkmcnt(1)
	v_mfma_f32_32x32x16_bf16 v[4:19], v[206:209], v[222:225], v[4:19]
	global_load_dwordx4 v[226:229], v[156:157], off offset:640
	ds_read_b128 v[222:225], v195 offset:41568
	ds_read_b128 v[174:177], v194 offset:4672
	v_mfma_f32_32x32x16_bf16 v[20:35], v[202:205], v[210:213], v[20:35]
	global_load_dwordx4 v[230:233], v[154:155], off offset:640
	ds_read_b128 v[210:213], v194 offset:4704
	ds_read_b128 v[202:205], v194 offset:64
	s_waitcnt lgkmcnt(4)
	v_mfma_f32_32x32x16_bf16 v[52:67], v[178:181], v[214:217], v[52:67]
	global_load_dwordx4 v[242:245], v[152:153], off offset:640
	ds_read_b128 v[218:221], v195 offset:36960
	ds_read_b128 v[178:181], v195 offset:41536
	v_mfma_f32_32x32x16_bf16 v[20:35], v[206:209], v[214:217], v[20:35]
	global_load_dwordx4 v[246:249], v[146:147], off offset:640
	ds_read_b128 v[214:217], v195 offset:36928
	ds_read_b128 v[206:209], v194 offset:96
	s_waitcnt lgkmcnt(1)
	v_mfma_f32_32x32x16_bf16 v[52:67], v[202:205], v[214:217], v[52:67]
	s_waitcnt vmcnt(23)
	ds_write_b128 v190, v[68:71] offset:18432
	v_mfma_f32_32x32x16_bf16 v[36:51], v[202:205], v[178:181], v[36:51]
	s_waitcnt vmcnt(22)
	ds_write_b128 v190, v[72:75] offset:55296
	v_mfma_f32_32x32x16_bf16 v[20:35], v[174:177], v[214:217], v[20:35]
	s_waitcnt vmcnt(21)
	ds_write_b128 v191, v[76:79] offset:18432
	v_mfma_f32_32x32x16_bf16 v[4:19], v[174:177], v[178:181], v[4:19]
	s_waitcnt vmcnt(20)
	ds_write_b128 v191, v[80:83] offset:55296
	s_waitcnt lgkmcnt(4)
	v_mfma_f32_32x32x16_bf16 v[52:67], v[206:209], v[218:221], v[52:67]
	s_waitcnt vmcnt(19)
	ds_write_b128 v192, v[84:87] offset:18432
	v_mfma_f32_32x32x16_bf16 v[36:51], v[206:209], v[222:225], v[36:51]
	s_waitcnt vmcnt(18)
	ds_write_b128 v192, v[92:95] offset:55296
	v_mfma_f32_32x32x16_bf16 v[20:35], v[210:213], v[218:221], v[20:35]
	s_waitcnt vmcnt(17)
	ds_write_b128 v193, v[104:107] offset:18432
	v_mfma_f32_32x32x16_bf16 v[4:19], v[210:213], v[222:225], v[4:19]
	s_waitcnt vmcnt(16)
	ds_write_b128 v193, v[112:115] offset:55296
	s_waitcnt lgkmcnt(0)
	s_barrier
	ds_read_b128 v[174:177], v196
	ds_read_b128 v[210:213], v197 offset:36864
	ds_read_b128 v[218:221], v197 offset:41472
	ds_read_b128 v[202:205], v196 offset:4608
	ds_read_b128 v[178:181], v196 offset:32
	ds_read_b128 v[222:225], v197 offset:41504
	ds_read_b128 v[206:209], v196 offset:4640
	ds_read_b128 v[214:217], v197 offset:36896
	s_waitcnt lgkmcnt(6)
	v_mfma_f32_32x32x16_bf16 v[52:67], v[174:177], v[210:213], v[52:67]
	global_load_dwordx4 v[68:71], v[164:165], off offset:768
	s_waitcnt lgkmcnt(5)
	v_mfma_f32_32x32x16_bf16 v[36:51], v[174:177], v[218:221], v[36:51]
	global_load_dwordx4 v[72:75], v[162:163], off offset:768
	s_waitcnt lgkmcnt(4)
	v_mfma_f32_32x32x16_bf16 v[4:19], v[202:205], v[218:221], v[4:19]
	global_load_dwordx4 v[76:79], v[160:161], off offset:768
	s_waitcnt lgkmcnt(2)
	v_mfma_f32_32x32x16_bf16 v[36:51], v[178:181], v[222:225], v[36:51]
	global_load_dwordx4 v[80:83], v[158:159], off offset:768
	s_waitcnt lgkmcnt(1)
	v_mfma_f32_32x32x16_bf16 v[4:19], v[206:209], v[222:225], v[4:19]
	global_load_dwordx4 v[84:87], v[156:157], off offset:768
	ds_read_b128 v[222:225], v197 offset:41568
	ds_read_b128 v[174:177], v196 offset:4672
	v_mfma_f32_32x32x16_bf16 v[20:35], v[202:205], v[210:213], v[20:35]
	global_load_dwordx4 v[92:95], v[154:155], off offset:768
	ds_read_b128 v[210:213], v196 offset:4704
	ds_read_b128 v[202:205], v196 offset:64
	s_waitcnt lgkmcnt(4)
	v_mfma_f32_32x32x16_bf16 v[52:67], v[178:181], v[214:217], v[52:67]
	global_load_dwordx4 v[104:107], v[152:153], off offset:768
	ds_read_b128 v[218:221], v197 offset:36960
	ds_read_b128 v[178:181], v197 offset:41536
	v_mfma_f32_32x32x16_bf16 v[20:35], v[206:209], v[214:217], v[20:35]
	global_load_dwordx4 v[112:115], v[146:147], off offset:768
	ds_read_b128 v[214:217], v197 offset:36928
	ds_read_b128 v[206:209], v196 offset:96
	s_waitcnt lgkmcnt(1)
	v_mfma_f32_32x32x16_bf16 v[52:67], v[202:205], v[214:217], v[52:67]
	s_waitcnt vmcnt(23)
	ds_write_b128 v190, v[88:91]
	v_mfma_f32_32x32x16_bf16 v[36:51], v[202:205], v[178:181], v[36:51]
	s_waitcnt vmcnt(22)
	ds_write_b128 v190, v[96:99] offset:36864
	v_mfma_f32_32x32x16_bf16 v[20:35], v[174:177], v[214:217], v[20:35]
	s_waitcnt vmcnt(21)
	ds_write_b128 v191, v[100:103]
	v_mfma_f32_32x32x16_bf16 v[4:19], v[174:177], v[178:181], v[4:19]
	s_waitcnt vmcnt(20)
	ds_write_b128 v191, v[108:111] offset:36864
	s_waitcnt lgkmcnt(4)
	v_mfma_f32_32x32x16_bf16 v[52:67], v[206:209], v[218:221], v[52:67]
	s_waitcnt vmcnt(19)
	ds_write_b128 v192, v[116:119]
	v_mfma_f32_32x32x16_bf16 v[36:51], v[206:209], v[222:225], v[36:51]
	s_waitcnt vmcnt(18)
	ds_write_b128 v192, v[120:123] offset:36864
	v_mfma_f32_32x32x16_bf16 v[20:35], v[210:213], v[218:221], v[20:35]
	s_waitcnt vmcnt(17)
	ds_write_b128 v193, v[124:127]
	v_mfma_f32_32x32x16_bf16 v[4:19], v[210:213], v[222:225], v[4:19]
	s_waitcnt vmcnt(16)
	ds_write_b128 v193, v[128:131] offset:36864
	s_waitcnt lgkmcnt(0)
	s_barrier
; #define MFMA(a, b, c) __builtin_amdgcn_mfma_f32_32x32x16_bf16((a), (b), (c), 0, 0, 0)
; template <class Epi, class ColV>
; DI void gemm_tile(const bf16_t* __restrict__ A, int lda, const bf16_t* __restrict__ Bt, int ldb, int K, int m0, int n0, unsigned char* smem, Epi epi, ColV colv, const bf16_t* __restrict__ HYT = nullptr) {
;     ...
;     auto step = [&](int kt, u32x4 (&ldset)[8], const u32x4 (&stset)[8]) {
;         const int buf = kt & 1;
;         if (kt + 2 < nk) gload(ldset, kt + 2);
;         const bf16_t* Ab = As + (buf * 128 + 64 * wr + li) * LS + 8 * lh;
;         const bf16_t* Bb = Bs + (buf * 128 + 64 * wc + li) * LS + 8 * lh;
;         bf16x8 fa[2][2], fb[2][2], ga[2][2], gb[2][2];
; #pragma unroll
;         for (int k2 = 0; k2 < 2; ++k2) { fa[k2][0] = ld8(Ab + 16 * k2); fa[k2][1] = ld8(Ab + 32 * LS + 16 * k2); fb[k2][0] = ld8(Bb + 16 * k2); fb[k2][1] = ld8(Bb + 32 * LS + 16 * k2); }
;         __builtin_amdgcn_sched_barrier(0);
; #pragma unroll
;         for (int k2 = 0; k2 < 2; ++k2) {
;             acc[0][0] = MFMA(fa[k2][0], fb[k2][0], acc[0][0]); acc[0][1] = MFMA(fa[k2][0], fb[k2][1], acc[0][1]);
;             acc[1][0] = MFMA(fa[k2][1], fb[k2][0], acc[1][0]); acc[1][1] = MFMA(fa[k2][1], fb[k2][1], acc[1][1]);
;         }
; #pragma unroll
;         for (int k2 = 0; k2 < 2; ++k2) { const int ks = 2 + k2; ga[k2][0] = ld8(Ab + 16 * ks); ga[k2][1] = ld8(Ab + 32 * LS + 16 * ks); gb[k2][0] = ld8(Bb + 16 * ks); gb[k2][1] = ld8(Bb + 32 * LS + 16 * ks); }
; #pragma unroll
;         for (int k2 = 0; k2 < 2; ++k2) {
;             acc[0][0] = MFMA(ga[k2][0], gb[k2][0], acc[0][0]); acc[0][1] = MFMA(ga[k2][0], gb[k2][1], acc[0][1]);
;             acc[1][0] = MFMA(ga[k2][1], gb[k2][0], acc[1][0]); acc[1][1] = MFMA(ga[k2][1], gb[k2][1], acc[1][1]);
;         }
;         if (kt + 1 < nk) sstore(stset, buf ^ 1, kt + 1);
; #pragma unroll
;         for (int i = 0; i < 8; ++i) { __builtin_amdgcn_sched_group_barrier(0x008, 1, 0); __builtin_amdgcn_sched_group_barrier(0x100, 1, 0); }
; #pragma unroll
;         for (int i = 0; i < 8; ++i) { __builtin_amdgcn_sched_group_barrier(0x008, 1, 0); __builtin_amdgcn_sched_group_barrier(0x200, 1, 0); }
;         __builtin_amdgcn_sched_barrier(0);
;         __syncthreads();
;     };
	ds_read_b128 v[174:177], v194
	ds_read_b128 v[210:213], v195 offset:36864
	ds_read_b128 v[218:221], v195 offset:41472
	ds_read_b128 v[202:205], v194 offset:4608
	ds_read_b128 v[178:181], v194 offset:32
	ds_read_b128 v[222:225], v195 offset:41504
	ds_read_b128 v[206:209], v194 offset:4640
	ds_read_b128 v[214:217], v195 offset:36896
	s_waitcnt lgkmcnt(6)
	v_mfma_f32_32x32x16_bf16 v[52:67], v[174:177], v[210:213], v[52:67]
	global_load_dwordx4 v[88:91], v[164:165], off offset:896
	s_waitcnt lgkmcnt(5)
	v_mfma_f32_32x32x16_bf16 v[36:51], v[174:177], v[218:221], v[36:51]
	global_load_dwordx4 v[96:99], v[162:163], off offset:896
	s_waitcnt lgkmcnt(4)
	v_mfma_f32_32x32x16_bf16 v[4:19], v[202:205], v[218:221], v[4:19]
	global_load_dwordx4 v[100:103], v[160:161], off offset:896
	s_waitcnt lgkmcnt(2)
	v_mfma_f32_32x32x16_bf16 v[36:51], v[178:181], v[222:225], v[36:51]
	global_load_dwordx4 v[108:111], v[158:159], off offset:896
	s_waitcnt lgkmcnt(1)
	v_mfma_f32_32x32x16_bf16 v[4:19], v[206:209], v[222:225], v[4:19]
	global_load_dwordx4 v[116:119], v[156:157], off offset:896
	ds_read_b128 v[222:225], v195 offset:41568
	ds_read_b128 v[174:177], v194 offset:4672
	v_mfma_f32_32x32x16_bf16 v[20:35], v[202:205], v[210:213], v[20:35]
	global_load_dwordx4 v[120:123], v[154:155], off offset:896
	ds_read_b128 v[210:213], v194 offset:4704
	ds_read_b128 v[202:205], v194 offset:64
	s_waitcnt lgkmcnt(4)
	v_mfma_f32_32x32x16_bf16 v[52:67], v[178:181], v[214:217], v[52:67]
	global_load_dwordx4 v[124:127], v[152:153], off offset:896
	ds_read_b128 v[218:221], v195 offset:36960
	ds_read_b128 v[178:181], v195 offset:41536
	v_mfma_f32_32x32x16_bf16 v[20:35], v[206:209], v[214:217], v[20:35]
	global_load_dwordx4 v[128:131], v[146:147], off offset:896
	ds_read_b128 v[214:217], v195 offset:36928
	ds_read_b128 v[206:209], v194 offset:96
	s_waitcnt lgkmcnt(1)
	v_mfma_f32_32x32x16_bf16 v[52:67], v[202:205], v[214:217], v[52:67]
	s_waitcnt vmcnt(23)
	ds_write_b128 v190, v[132:135] offset:18432
	v_mfma_f32_32x32x16_bf16 v[36:51], v[202:205], v[178:181], v[36:51]
	s_waitcnt vmcnt(22)
	ds_write_b128 v190, v[136:139] offset:55296
	v_mfma_f32_32x32x16_bf16 v[20:35], v[174:177], v[214:217], v[20:35]
	s_waitcnt vmcnt(21)
	ds_write_b128 v191, v[140:143] offset:18432
	v_mfma_f32_32x32x16_bf16 v[4:19], v[174:177], v[178:181], v[4:19]
	s_waitcnt vmcnt(20)
	ds_write_b128 v191, v[198:201] offset:55296
	s_waitcnt lgkmcnt(4)
	v_mfma_f32_32x32x16_bf16 v[52:67], v[206:209], v[218:221], v[52:67]
	s_waitcnt vmcnt(19)
	ds_write_b128 v192, v[226:229] offset:18432
	v_mfma_f32_32x32x16_bf16 v[36:51], v[206:209], v[222:225], v[36:51]
	s_waitcnt vmcnt(18)
	ds_write_b128 v192, v[230:233] offset:55296
	v_mfma_f32_32x32x16_bf16 v[20:35], v[210:213], v[218:221], v[20:35]
	s_waitcnt vmcnt(17)
	ds_write_b128 v193, v[242:245] offset:18432
	v_mfma_f32_32x32x16_bf16 v[4:19], v[210:213], v[222:225], v[4:19]
	s_waitcnt vmcnt(16)
	ds_write_b128 v193, v[246:249] offset:55296
	s_waitcnt lgkmcnt(0)
	s_barrier
	ds_read_b128 v[174:177], v196
	ds_read_b128 v[210:213], v197 offset:36864
	ds_read_b128 v[218:221], v197 offset:41472
	ds_read_b128 v[202:205], v196 offset:4608
	ds_read_b128 v[178:181], v196 offset:32
	ds_read_b128 v[222:225], v197 offset:41504
	ds_read_b128 v[206:209], v196 offset:4640
	ds_read_b128 v[214:217], v197 offset:36896
	s_waitcnt lgkmcnt(6)
	v_mfma_f32_32x32x16_bf16 v[52:67], v[174:177], v[210:213], v[52:67]
	global_load_dwordx4 v[132:135], v[164:165], off offset:1024
	s_waitcnt lgkmcnt(5)
	v_mfma_f32_32x32x16_bf16 v[36:51], v[174:177], v[218:221], v[36:51]
	global_load_dwordx4 v[136:139], v[162:163], off offset:1024
	s_waitcnt lgkmcnt(4)
	v_mfma_f32_32x32x16_bf16 v[4:19], v[202:205], v[218:221], v[4:19]
	global_load_dwordx4 v[140:143], v[160:161], off offset:1024
	s_waitcnt lgkmcnt(2)
	v_mfma_f32_32x32x16_bf16 v[36:51], v[178:181], v[222:225], v[36:51]
	global_load_dwordx4 v[198:201], v[158:159], off offset:1024
	s_waitcnt lgkmcnt(1)
	v_mfma_f32_32x32x16_bf16 v[4:19], v[206:209], v[222:225], v[4:19]
	global_load_dwordx4 v[226:229], v[156:157], off offset:1024
	ds_read_b128 v[222:225], v197 offset:41568
	ds_read_b128 v[174:177], v196 offset:4672
	v_mfma_f32_32x32x16_bf16 v[20:35], v[202:205], v[210:213], v[20:35]
	global_load_dwordx4 v[230:233], v[154:155], off offset:1024
	ds_read_b128 v[210:213], v196 offset:4704
	ds_read_b128 v[202:205], v196 offset:64
	s_waitcnt lgkmcnt(4)
	v_mfma_f32_32x32x16_bf16 v[52:67], v[178:181], v[214:217], v[52:67]
	global_load_dwordx4 v[242:245], v[152:153], off offset:1024
	ds_read_b128 v[218:221], v197 offset:36960
	ds_read_b128 v[178:181], v197 offset:41536
	v_mfma_f32_32x32x16_bf16 v[20:35], v[206:209], v[214:217], v[20:35]
	global_load_dwordx4 v[246:249], v[146:147], off offset:1024
	ds_read_b128 v[214:217], v197 offset:36928
	ds_read_b128 v[206:209], v196 offset:96
	s_waitcnt lgkmcnt(1)
	v_mfma_f32_32x32x16_bf16 v[52:67], v[202:205], v[214:217], v[52:67]
	s_waitcnt vmcnt(23)
	ds_write_b128 v190, v[68:71]
	v_mfma_f32_32x32x16_bf16 v[36:51], v[202:205], v[178:181], v[36:51]
	s_waitcnt vmcnt(22)
	ds_write_b128 v190, v[72:75] offset:36864
	v_mfma_f32_32x32x16_bf16 v[20:35], v[174:177], v[214:217], v[20:35]
	s_waitcnt vmcnt(21)
	ds_write_b128 v191, v[76:79]
	v_mfma_f32_32x32x16_bf16 v[4:19], v[174:177], v[178:181], v[4:19]
	s_waitcnt vmcnt(20)
	ds_write_b128 v191, v[80:83] offset:36864
	s_waitcnt lgkmcnt(4)
	v_mfma_f32_32x32x16_bf16 v[52:67], v[206:209], v[218:221], v[52:67]
	s_waitcnt vmcnt(19)
	ds_write_b128 v192, v[84:87]
	v_mfma_f32_32x32x16_bf16 v[36:51], v[206:209], v[222:225], v[36:51]
	s_waitcnt vmcnt(18)
	ds_write_b128 v192, v[92:95] offset:36864
	v_mfma_f32_32x32x16_bf16 v[20:35], v[210:213], v[218:221], v[20:35]
	s_waitcnt vmcnt(17)
	ds_write_b128 v193, v[104:107]
	v_mfma_f32_32x32x16_bf16 v[4:19], v[210:213], v[222:225], v[4:19]
	s_waitcnt vmcnt(16)
	ds_write_b128 v193, v[112:115] offset:36864
	s_waitcnt lgkmcnt(0)
	s_barrier
; template <class Epi, class ColV>
; DI void gemm_tile(const bf16_t* __restrict__ A, int lda, const bf16_t* __restrict__ Bt, int ldb, int K, int m0, int n0, unsigned char* smem, Epi epi, ColV colv, const bf16_t* __restrict__ HYT = nullptr) {
;     ...
;     auto step = [&](int kt, u32x4 (&ldset)[8], const u32x4 (&stset)[8]) {
;         const int buf = kt & 1;
;         if (kt + 2 < nk) gload(ldset, kt + 2);
;         const bf16_t* Ab = As + (buf * 128 + 64 * wr + li) * LS + 8 * lh;
;         const bf16_t* Bb = Bs + (buf * 128 + 64 * wc + li) * LS + 8 * lh;
;         bf16x8 fa[2][2], fb[2][2], ga[2][2], gb[2][2];
; #pragma unroll
;         for (int k2 = 0; k2 < 2; ++k2) { fa[k2][0] = ld8(Ab + 16 * k2); fa[k2][1] = ld8(Ab + 32 * LS + 16 * k2); fb[k2][0] = ld8(Bb + 16 * k2); fb[k2][1] = ld8(Bb + 32 * LS + 16 * k2); }
;         __builtin_amdgcn_sched_barrier(0);
; #pragma unroll
;         for (int k2 = 0; k2 < 2; ++k2) {
;             acc[0][0] = MFMA(fa[k2][0], fb[k2][0], acc[0][0]); acc[0][1] = MFMA(fa[k2][0], fb[k2][1], acc[0][1]);
;             acc[1][0] = MFMA(fa[k2][1], fb[k2][0], acc[1][0]); acc[1][1] = MFMA(fa[k2][1], fb[k2][1], acc[1][1]);
;         }
; #pragma unroll
;         for (int k2 = 0; k2 < 2; ++k2) { const int ks = 2 + k2; ga[k2][0] = ld8(Ab + 16 * ks); ga[k2][1] = ld8(Ab + 32 * LS + 16 * ks); gb[k2][0] = ld8(Bb + 16 * ks); gb[k2][1] = ld8(Bb + 32 * LS + 16 * ks); }
; #pragma unroll
;         for (int k2 = 0; k2 < 2; ++k2) {
;             acc[0][0] = MFMA(ga[k2][0], gb[k2][0], acc[0][0]); acc[0][1] = MFMA(ga[k2][0], gb[k2][1], acc[0][1]);
;             acc[1][0] = MFMA(ga[k2][1], gb[k2][0], acc[1][0]); acc[1][1] = MFMA(ga[k2][1], gb[k2][1], acc[1][1]);
;         }
;         if (kt + 1 < nk) sstore(stset, buf ^ 1, kt + 1);
; #pragma unroll
;         for (int i = 0; i < 8; ++i) { __builtin_amdgcn_sched_group_barrier(0x008, 1, 0); __builtin_amdgcn_sched_group_barrier(0x100, 1, 0); }
; #pragma unroll
;         for (int i = 0; i < 8; ++i) { __builtin_amdgcn_sched_group_barrier(0x008, 1, 0); __builtin_amdgcn_sched_group_barrier(0x200, 1, 0); }
;         __builtin_amdgcn_sched_barrier(0);
;         __syncthreads();
;     };
;     gload(R0, 0); gload(R1, 1);
;     sstore(R0, 0, 0); __syncthreads();
;     for (int kt = 0; kt < nk; kt += 2) {
;         step(kt, R0, R1);
;         if (kt + 1 < nk) step(kt + 1, R1, R0);
;     }
	v_lshl_add_u64 v[164:165], v[164:165], 0, s[100:101]
	v_lshl_add_u64 v[162:163], v[162:163], 0, s[100:101]
	v_lshl_add_u64 v[160:161], v[160:161], 0, s[100:101]
	v_lshl_add_u64 v[158:159], v[158:159], 0, s[100:101]
	v_lshl_add_u64 v[156:157], v[156:157], 0, s[100:101]
	v_lshl_add_u64 v[154:155], v[154:155], 0, s[100:101]
	v_lshl_add_u64 v[152:153], v[152:153], 0, s[100:101]
	v_lshl_add_u64 v[146:147], v[146:147], 0, s[100:101]
	s_sub_u32 s41, s41, 1
	s_cmp_lg_u32 s41, 0
	s_cbranch_scc1 .Lg3_phase11
	ds_read_b128 v[174:177], v194
	ds_read_b128 v[210:213], v195 offset:36864
	ds_read_b128 v[218:221], v195 offset:41472
	ds_read_b128 v[202:205], v194 offset:4608
	ds_read_b128 v[178:181], v194 offset:32
	ds_read_b128 v[222:225], v195 offset:41504
	ds_read_b128 v[206:209], v194 offset:4640
	ds_read_b128 v[214:217], v195 offset:36896
	s_waitcnt lgkmcnt(6)
	v_mfma_f32_32x32x16_bf16 v[52:67], v[174:177], v[210:213], v[52:67]
	global_load_dwordx4 v[68:71], v[164:165], off offset:384
	s_waitcnt lgkmcnt(5)
	v_mfma_f32_32x32x16_bf16 v[36:51], v[174:177], v[218:221], v[36:51]
	global_load_dwordx4 v[72:75], v[162:163], off offset:384
	s_waitcnt lgkmcnt(4)
	v_mfma_f32_32x32x16_bf16 v[4:19], v[202:205], v[218:221], v[4:19]
	global_load_dwordx4 v[76:79], v[160:161], off offset:384
	s_waitcnt lgkmcnt(2)
	v_mfma_f32_32x32x16_bf16 v[36:51], v[178:181], v[222:225], v[36:51]
	global_load_dwordx4 v[80:83], v[158:159], off offset:384
	s_waitcnt lgkmcnt(1)
	v_mfma_f32_32x32x16_bf16 v[4:19], v[206:209], v[222:225], v[4:19]
	global_load_dwordx4 v[84:87], v[156:157], off offset:384
	ds_read_b128 v[222:225], v195 offset:41568
	ds_read_b128 v[174:177], v194 offset:4672
	v_mfma_f32_32x32x16_bf16 v[20:35], v[202:205], v[210:213], v[20:35]
	global_load_dwordx4 v[92:95], v[154:155], off offset:384
	ds_read_b128 v[210:213], v194 offset:4704
	ds_read_b128 v[202:205], v194 offset:64
	s_waitcnt lgkmcnt(4)
	v_mfma_f32_32x32x16_bf16 v[52:67], v[178:181], v[214:217], v[52:67]
	global_load_dwordx4 v[104:107], v[152:153], off offset:384
	ds_read_b128 v[218:221], v195 offset:36960
	ds_read_b128 v[178:181], v195 offset:41536
	v_mfma_f32_32x32x16_bf16 v[20:35], v[206:209], v[214:217], v[20:35]
	global_load_dwordx4 v[112:115], v[146:147], off offset:384
	ds_read_b128 v[214:217], v195 offset:36928
	ds_read_b128 v[206:209], v194 offset:96
	s_waitcnt lgkmcnt(1)
	v_mfma_f32_32x32x16_bf16 v[52:67], v[202:205], v[214:217], v[52:67]
	s_waitcnt vmcnt(23)
	ds_write_b128 v190, v[88:91] offset:18432
	v_mfma_f32_32x32x16_bf16 v[36:51], v[202:205], v[178:181], v[36:51]
	s_waitcnt vmcnt(22)
	ds_write_b128 v190, v[96:99] offset:55296
	v_mfma_f32_32x32x16_bf16 v[20:35], v[174:177], v[214:217], v[20:35]
	s_waitcnt vmcnt(21)
	ds_write_b128 v191, v[100:103] offset:18432
	v_mfma_f32_32x32x16_bf16 v[4:19], v[174:177], v[178:181], v[4:19]
	s_waitcnt vmcnt(20)
	ds_write_b128 v191, v[108:111] offset:55296
	s_waitcnt lgkmcnt(4)
	v_mfma_f32_32x32x16_bf16 v[52:67], v[206:209], v[218:221], v[52:67]
	s_waitcnt vmcnt(19)
	ds_write_b128 v192, v[116:119] offset:18432
	v_mfma_f32_32x32x16_bf16 v[36:51], v[206:209], v[222:225], v[36:51]
	s_waitcnt vmcnt(18)
	ds_write_b128 v192, v[120:123] offset:55296
	v_mfma_f32_32x32x16_bf16 v[20:35], v[210:213], v[218:221], v[20:35]
	s_waitcnt vmcnt(17)
	ds_write_b128 v193, v[124:127] offset:18432
	v_mfma_f32_32x32x16_bf16 v[4:19], v[210:213], v[222:225], v[4:19]
	s_waitcnt vmcnt(16)
	ds_write_b128 v193, v[128:131] offset:55296
	s_waitcnt lgkmcnt(0)
	s_barrier
	ds_read_b128 v[174:177], v196
	ds_read_b128 v[178:181], v196 offset:32
	ds_read_b128 v[202:205], v196 offset:4608
	ds_read_b128 v[206:209], v196 offset:4640
	ds_read_b128 v[210:213], v197 offset:36864
	ds_read_b128 v[214:217], v197 offset:36896
	ds_read_b128 v[218:221], v197 offset:41472
	ds_read_b128 v[222:225], v197 offset:41504
	s_waitcnt lgkmcnt(3)
	v_mfma_f32_32x32x16_bf16 v[52:67], v[174:177], v[210:213], v[52:67]
	s_waitcnt lgkmcnt(1)
	v_mfma_f32_32x32x16_bf16 v[36:51], v[174:177], v[218:221], v[36:51]
	v_mfma_f32_32x32x16_bf16 v[4:19], v[202:205], v[218:221], v[4:19]
	s_waitcnt lgkmcnt(0)
	v_mfma_f32_32x32x16_bf16 v[36:51], v[178:181], v[222:225], v[36:51]
	v_mfma_f32_32x32x16_bf16 v[4:19], v[206:209], v[222:225], v[4:19]
	ds_read_b128 v[222:225], v197 offset:41568
	ds_read_b128 v[174:177], v196 offset:4672
	v_mfma_f32_32x32x16_bf16 v[20:35], v[202:205], v[210:213], v[20:35]
	ds_read_b128 v[210:213], v196 offset:4704
	ds_read_b128 v[202:205], v196 offset:64
	v_mfma_f32_32x32x16_bf16 v[52:67], v[178:181], v[214:217], v[52:67]
	ds_read_b128 v[218:221], v197 offset:36960
	ds_read_b128 v[178:181], v197 offset:41536
	v_mfma_f32_32x32x16_bf16 v[20:35], v[206:209], v[214:217], v[20:35]
	ds_read_b128 v[214:217], v197 offset:36928
	ds_read_b128 v[206:209], v196 offset:96
	s_waitcnt lgkmcnt(1)
	v_mfma_f32_32x32x16_bf16 v[52:67], v[202:205], v[214:217], v[52:67]
	s_waitcnt vmcnt(15)
	ds_write_b128 v190, v[132:135]
	v_mfma_f32_32x32x16_bf16 v[36:51], v[202:205], v[178:181], v[36:51]
	s_waitcnt vmcnt(14)
	ds_write_b128 v190, v[136:139] offset:36864
	v_mfma_f32_32x32x16_bf16 v[20:35], v[174:177], v[214:217], v[20:35]
	s_waitcnt vmcnt(13)
	ds_write_b128 v191, v[140:143]
	v_mfma_f32_32x32x16_bf16 v[4:19], v[174:177], v[178:181], v[4:19]
	s_waitcnt vmcnt(12)
	ds_write_b128 v191, v[198:201] offset:36864
	s_waitcnt lgkmcnt(4)
	v_mfma_f32_32x32x16_bf16 v[52:67], v[206:209], v[218:221], v[52:67]
	s_waitcnt vmcnt(11)
	ds_write_b128 v192, v[226:229]
	v_mfma_f32_32x32x16_bf16 v[36:51], v[206:209], v[222:225], v[36:51]
	s_waitcnt vmcnt(10)
	ds_write_b128 v192, v[230:233] offset:36864
	v_mfma_f32_32x32x16_bf16 v[20:35], v[210:213], v[218:221], v[20:35]
	s_waitcnt vmcnt(9)
	ds_write_b128 v193, v[242:245]
	v_mfma_f32_32x32x16_bf16 v[4:19], v[210:213], v[222:225], v[4:19]
	s_waitcnt vmcnt(8)
	ds_write_b128 v193, v[246:249] offset:36864
	s_waitcnt lgkmcnt(0)
	s_barrier
; template <class Epi, class ColV>
; DI void gemm_tile(const bf16_t* __restrict__ A, int lda, const bf16_t* __restrict__ Bt, int ldb, int K, int m0, int n0, unsigned char* smem, Epi epi, ColV colv, const bf16_t* __restrict__ HYT = nullptr) {
;     ...
;         if (kt + 1 < nk) sstore(stset, buf ^ 1, kt + 1);
; #pragma unroll
;         for (int i = 0; i < 8; ++i) { __builtin_amdgcn_sched_group_barrier(0x008, 1, 0); __builtin_amdgcn_sched_group_barrier(0x100, 1, 0); }
; #pragma unroll
;         for (int i = 0; i < 8; ++i) { __builtin_amdgcn_sched_group_barrier(0x008, 1, 0); __builtin_amdgcn_sched_group_barrier(0x200, 1, 0); }
;         __builtin_amdgcn_sched_barrier(0);
;         __syncthreads();
;     };
;     gload(R0, 0); gload(R1, 1);
;     sstore(R0, 0, 0); __syncthreads();
;     for (int kt = 0; kt < nk; kt += 2) {
;         step(kt, R0, R1);
;         if (kt + 1 < nk) step(kt + 1, R1, R0);
;     }
	ds_read_b128 v[174:177], v194
	ds_read_b128 v[178:181], v194 offset:32
	ds_read_b128 v[202:205], v194 offset:4608
	ds_read_b128 v[206:209], v194 offset:4640
	ds_read_b128 v[210:213], v195 offset:36864
	ds_read_b128 v[214:217], v195 offset:36896
	ds_read_b128 v[218:221], v195 offset:41472
	ds_read_b128 v[222:225], v195 offset:41504
	s_waitcnt lgkmcnt(3)
	v_mfma_f32_32x32x16_bf16 v[52:67], v[174:177], v[210:213], v[52:67]
	s_waitcnt lgkmcnt(1)
	v_mfma_f32_32x32x16_bf16 v[36:51], v[174:177], v[218:221], v[36:51]
	v_mfma_f32_32x32x16_bf16 v[4:19], v[202:205], v[218:221], v[4:19]
	s_waitcnt lgkmcnt(0)
	v_mfma_f32_32x32x16_bf16 v[36:51], v[178:181], v[222:225], v[36:51]
	v_mfma_f32_32x32x16_bf16 v[4:19], v[206:209], v[222:225], v[4:19]
	ds_read_b128 v[222:225], v195 offset:41568
	ds_read_b128 v[174:177], v194 offset:4672
	v_mfma_f32_32x32x16_bf16 v[20:35], v[202:205], v[210:213], v[20:35]
	ds_read_b128 v[210:213], v194 offset:4704
	ds_read_b128 v[202:205], v194 offset:64
	v_mfma_f32_32x32x16_bf16 v[52:67], v[178:181], v[214:217], v[52:67]
	ds_read_b128 v[218:221], v195 offset:36960
	ds_read_b128 v[178:181], v195 offset:41536
	v_mfma_f32_32x32x16_bf16 v[20:35], v[206:209], v[214:217], v[20:35]
	ds_read_b128 v[214:217], v195 offset:36928
	ds_read_b128 v[206:209], v194 offset:96
	s_waitcnt lgkmcnt(1)
	v_mfma_f32_32x32x16_bf16 v[52:67], v[202:205], v[214:217], v[52:67]
	s_waitcnt vmcnt(7)
	ds_write_b128 v190, v[68:71] offset:18432
	v_mfma_f32_32x32x16_bf16 v[36:51], v[202:205], v[178:181], v[36:51]
	s_waitcnt vmcnt(6)
	ds_write_b128 v190, v[72:75] offset:55296
	v_mfma_f32_32x32x16_bf16 v[20:35], v[174:177], v[214:217], v[20:35]
	s_waitcnt vmcnt(5)
	ds_write_b128 v191, v[76:79] offset:18432
	v_mfma_f32_32x32x16_bf16 v[4:19], v[174:177], v[178:181], v[4:19]
	s_waitcnt vmcnt(4)
	ds_write_b128 v191, v[80:83] offset:55296
	s_waitcnt lgkmcnt(4)
	v_mfma_f32_32x32x16_bf16 v[52:67], v[206:209], v[218:221], v[52:67]
	s_waitcnt vmcnt(3)
	ds_write_b128 v192, v[84:87] offset:18432
	v_mfma_f32_32x32x16_bf16 v[36:51], v[206:209], v[222:225], v[36:51]
	s_waitcnt vmcnt(2)
	ds_write_b128 v192, v[92:95] offset:55296
	v_mfma_f32_32x32x16_bf16 v[20:35], v[210:213], v[218:221], v[20:35]
	s_waitcnt vmcnt(1)
	ds_write_b128 v193, v[104:107] offset:18432
	v_mfma_f32_32x32x16_bf16 v[4:19], v[210:213], v[222:225], v[4:19]
	s_waitcnt vmcnt(0)
	ds_write_b128 v193, v[112:115] offset:55296
	s_waitcnt lgkmcnt(0)
	s_barrier
	ds_read_b128 v[174:177], v196
	ds_read_b128 v[178:181], v196 offset:32
	ds_read_b128 v[202:205], v196 offset:4608
	ds_read_b128 v[206:209], v196 offset:4640
	ds_read_b128 v[210:213], v197 offset:36864
	ds_read_b128 v[214:217], v197 offset:36896
	ds_read_b128 v[218:221], v197 offset:41472
	ds_read_b128 v[222:225], v197 offset:41504
	s_waitcnt lgkmcnt(3)
	v_mfma_f32_32x32x16_bf16 v[52:67], v[174:177], v[210:213], v[52:67]
	s_waitcnt lgkmcnt(1)
	v_mfma_f32_32x32x16_bf16 v[36:51], v[174:177], v[218:221], v[36:51]
	v_mfma_f32_32x32x16_bf16 v[4:19], v[202:205], v[218:221], v[4:19]
	s_waitcnt lgkmcnt(0)
	v_mfma_f32_32x32x16_bf16 v[36:51], v[178:181], v[222:225], v[36:51]
	v_mfma_f32_32x32x16_bf16 v[4:19], v[206:209], v[222:225], v[4:19]
	ds_read_b128 v[222:225], v197 offset:41568
	ds_read_b128 v[174:177], v196 offset:4672
	v_mfma_f32_32x32x16_bf16 v[20:35], v[202:205], v[210:213], v[20:35]
	ds_read_b128 v[210:213], v196 offset:4704
	ds_read_b128 v[202:205], v196 offset:64
	v_mfma_f32_32x32x16_bf16 v[52:67], v[178:181], v[214:217], v[52:67]
	ds_read_b128 v[218:221], v197 offset:36960
	ds_read_b128 v[178:181], v197 offset:41536
	v_mfma_f32_32x32x16_bf16 v[20:35], v[206:209], v[214:217], v[20:35]
	ds_read_b128 v[214:217], v197 offset:36928
	ds_read_b128 v[206:209], v196 offset:96
	s_waitcnt lgkmcnt(1)
	v_mfma_f32_32x32x16_bf16 v[52:67], v[202:205], v[214:217], v[52:67]
	v_mfma_f32_32x32x16_bf16 v[36:51], v[202:205], v[178:181], v[36:51]
	v_mfma_f32_32x32x16_bf16 v[20:35], v[174:177], v[214:217], v[20:35]
	v_mfma_f32_32x32x16_bf16 v[4:19], v[174:177], v[178:181], v[4:19]
	s_waitcnt lgkmcnt(0)
	v_mfma_f32_32x32x16_bf16 v[52:67], v[206:209], v[218:221], v[52:67]
	v_mfma_f32_32x32x16_bf16 v[36:51], v[206:209], v[222:225], v[36:51]
	v_mfma_f32_32x32x16_bf16 v[20:35], v[210:213], v[218:221], v[20:35]
	v_mfma_f32_32x32x16_bf16 v[4:19], v[210:213], v[222:225], v[4:19]
	s_waitcnt lgkmcnt(0)
	s_barrier
	s_nop 7
	s_nop 3
	s_branch .LBB0_37

; #define MFMA(a, b, c) __builtin_amdgcn_mfma_f32_32x32x16_bf16((a), (b), (c), 0, 0, 0)
; template <class Epi, class ColV>
; DI void gemm_tile(const bf16_t* __restrict__ A, int lda, const bf16_t* __restrict__ Bt, int ldb, int K, int m0, int n0, unsigned char* smem, Epi epi, ColV colv, const bf16_t* __restrict__ HYT = nullptr) {
;     ...
;     auto gload = [&](u32x4 (&r)[8], int kt) {
; #pragma unroll
;         for (int i = 0; i < 4; ++i) { int id = tid + 256 * i, row = id >> 3, kc = id & 7;
;             if (HYT && kt >= 12) r[i] = *(const u32x4*)(HYT + (size_t)((kt - 12) * 64 + (id >> 4)) * NT + m0 + (id & 15) * 8);
;             else r[i] = *(const u32x4*)(A + (size_t)(m0 + row) * lda + kt * 64 + kc * 8);
;             r[4 + i] = *(const u32x4*)(Bt + (size_t)(n0 + row) * ldb + kt * 64 + kc * 8); }
;     };
;     auto sstore = [&](const u32x4 (&r)[8], int buf, int kt) {
; #pragma unroll
;         for (int i = 0; i < 4; ++i) { int id = tid + 256 * i, row = id >> 3, kc = id & 7;
;             if (HYT && kt >= 12) { const int kk = id >> 4, rr = (id & 15) * 8; bf16_t* d = As + (buf * 128 + rr) * LS + kk; const bf16x8 v = __builtin_bit_cast(bf16x8, r[i]);
; #pragma unroll
;                 for (int e = 0; e < 8; ++e) d[e * LS] = (bf16_t)v[e]; }
;             else *(u32x4*)(As + (buf * 128 + row) * LS + kc * 8) = r[i];
;             *(u32x4*)(Bs + (buf * 128 + row) * LS + kc * 8) = r[4 + i]; }
;     };
;     auto step = [&](int kt, u32x4 (&ldset)[8], const u32x4 (&stset)[8]) {
;         const int buf = kt & 1;
;         if (kt + 2 < nk) gload(ldset, kt + 2);
;         const bf16_t* Ab = As + (buf * 128 + 64 * wr + li) * LS + 8 * lh;
;         const bf16_t* Bb = Bs + (buf * 128 + 64 * wc + li) * LS + 8 * lh;
;         bf16x8 fa[2][2], fb[2][2], ga[2][2], gb[2][2];
; #pragma unroll
;         for (int k2 = 0; k2 < 2; ++k2) { fa[k2][0] = ld8(Ab + 16 * k2); fa[k2][1] = ld8(Ab + 32 * LS + 16 * k2); fb[k2][0] = ld8(Bb + 16 * k2); fb[k2][1] = ld8(Bb + 32 * LS + 16 * k2); }
;         __builtin_amdgcn_sched_barrier(0);
; #pragma unroll
;         for (int k2 = 0; k2 < 2; ++k2) {
;             acc[0][0] = MFMA(fa[k2][0], fb[k2][0], acc[0][0]); acc[0][1] = MFMA(fa[k2][0], fb[k2][1], acc[0][1]);
;             acc[1][0] = MFMA(fa[k2][1], fb[k2][0], acc[1][0]); acc[1][1] = MFMA(fa[k2][1], fb[k2][1], acc[1][1]);
;         }
; #pragma unroll
.LBB0_56:
	s_cmp_lt_u32 s40, 14
	s_cselect_b64 s[18:19], -1, 0
	s_cmp_gt_u32 s40, 13
	s_cselect_b64 s[12:13], -1, 0
	s_and_b64 vcc, exec, s[12:13]
	v_lshl_add_u64 v[164:165], v[144:145], 0, v[2:3]
	v_lshl_add_u64 v[162:163], v[142:143], 0, v[2:3]
	v_lshl_add_u64 v[160:161], v[140:141], 0, v[2:3]
	v_lshl_add_u64 v[158:159], v[138:139], 0, v[2:3]
	v_lshl_add_u64 v[156:157], v[136:137], 0, v[2:3]
	v_lshl_add_u64 v[154:155], v[134:135], 0, v[2:3]
	v_lshl_add_u64 v[152:153], v[132:133], 0, v[2:3]
	v_lshl_add_u64 v[146:147], v[0:1], 0, v[2:3]
	s_mov_b32 s100, 0x26ca000
	s_mov_b32 s101, 0
	v_lshl_add_u64 v[164:165], v[164:165], 0, s[100:101]
	v_lshl_add_u64 v[160:161], v[160:161], 0, s[100:101]
	v_lshl_add_u64 v[156:157], v[156:157], 0, s[100:101]
	v_lshl_add_u64 v[152:153], v[152:153], 0, s[100:101]
	s_mov_b32 s100, 0x680000
	s_mov_b32 s101, 0
	v_lshl_add_u64 v[162:163], v[162:163], 0, s[100:101]
	v_lshl_add_u64 v[158:159], v[158:159], 0, s[100:101]
	v_lshl_add_u64 v[154:155], v[154:155], 0, s[100:101]
	v_lshl_add_u64 v[146:147], v[146:147], 0, s[100:101]
	ds_read_b128 v[174:177], v194
	ds_read_b128 v[210:213], v195 offset:36864
	ds_read_b128 v[218:221], v195 offset:41472
	ds_read_b128 v[202:205], v194 offset:4608
	ds_read_b128 v[178:181], v194 offset:32
	ds_read_b128 v[222:225], v195 offset:41504
	ds_read_b128 v[206:209], v194 offset:4640
	ds_read_b128 v[214:217], v195 offset:36896
	s_waitcnt lgkmcnt(6)
	v_mfma_f32_32x32x16_bf16 v[52:67], v[174:177], v[210:213], v[52:67]
	global_load_dwordx4 v[132:135], v[164:165], off offset:256
	global_load_dwordx4 v[136:139], v[162:163], off offset:256
	s_waitcnt lgkmcnt(5)
	v_mfma_f32_32x32x16_bf16 v[36:51], v[174:177], v[218:221], v[36:51]
	global_load_dwordx4 v[140:143], v[160:161], off offset:256
	global_load_dwordx4 v[198:201], v[158:159], off offset:256
	s_waitcnt lgkmcnt(4)
	v_mfma_f32_32x32x16_bf16 v[4:19], v[202:205], v[218:221], v[4:19]
	global_load_dwordx4 v[226:229], v[156:157], off offset:256
	global_load_dwordx4 v[230:233], v[154:155], off offset:256
	s_waitcnt lgkmcnt(2)
	v_mfma_f32_32x32x16_bf16 v[36:51], v[178:181], v[222:225], v[36:51]
	global_load_dwordx4 v[242:245], v[152:153], off offset:256
	global_load_dwordx4 v[246:249], v[146:147], off offset:256
	s_waitcnt lgkmcnt(1)
	v_mfma_f32_32x32x16_bf16 v[4:19], v[206:209], v[222:225], v[4:19]
	global_load_dwordx4 v[68:71], v[164:165], off offset:384
	global_load_dwordx4 v[72:75], v[162:163], off offset:384
	ds_read_b128 v[222:225], v195 offset:41568
	ds_read_b128 v[174:177], v194 offset:4672
	v_mfma_f32_32x32x16_bf16 v[20:35], v[202:205], v[210:213], v[20:35]
	global_load_dwordx4 v[76:79], v[160:161], off offset:384
	global_load_dwordx4 v[80:83], v[158:159], off offset:384
	ds_read_b128 v[210:213], v194 offset:4704
	ds_read_b128 v[202:205], v194 offset:64
	s_waitcnt lgkmcnt(4)
	v_mfma_f32_32x32x16_bf16 v[52:67], v[178:181], v[214:217], v[52:67]
	global_load_dwordx4 v[84:87], v[156:157], off offset:384
	global_load_dwordx4 v[92:95], v[154:155], off offset:384
	ds_read_b128 v[218:221], v195 offset:36960
	ds_read_b128 v[178:181], v195 offset:41536
	v_mfma_f32_32x32x16_bf16 v[20:35], v[206:209], v[214:217], v[20:35]
	global_load_dwordx4 v[104:107], v[152:153], off offset:384
	global_load_dwordx4 v[112:115], v[146:147], off offset:384
	ds_read_b128 v[214:217], v195 offset:36928
	ds_read_b128 v[206:209], v194 offset:96
	s_waitcnt lgkmcnt(1)
	v_mfma_f32_32x32x16_bf16 v[52:67], v[202:205], v[214:217], v[52:67]
	s_waitcnt vmcnt(16)
	ds_write_b128 v167, v[88:91] offset:18432
	v_mfma_f32_32x32x16_bf16 v[36:51], v[202:205], v[178:181], v[36:51]
	ds_write_b128 v167, v[96:99] offset:55296
	v_mfma_f32_32x32x16_bf16 v[20:35], v[174:177], v[214:217], v[20:35]
	ds_write_b128 v190, v[100:103] offset:18432
	v_mfma_f32_32x32x16_bf16 v[4:19], v[174:177], v[178:181], v[4:19]
	ds_write_b128 v190, v[108:111] offset:55296
	s_waitcnt lgkmcnt(4)
	v_mfma_f32_32x32x16_bf16 v[52:67], v[206:209], v[218:221], v[52:67]
	ds_write_b128 v191, v[116:119] offset:18432
	v_mfma_f32_32x32x16_bf16 v[36:51], v[206:209], v[222:225], v[36:51]
	ds_write_b128 v191, v[120:123] offset:55296
	v_mfma_f32_32x32x16_bf16 v[20:35], v[210:213], v[218:221], v[20:35]
	ds_write_b128 v192, v[124:127] offset:18432
	v_mfma_f32_32x32x16_bf16 v[4:19], v[210:213], v[222:225], v[4:19]
	ds_write_b128 v192, v[128:131] offset:55296
	s_waitcnt lgkmcnt(0)
	s_barrier
; #define MFMA(a, b, c) __builtin_amdgcn_mfma_f32_32x32x16_bf16((a), (b), (c), 0, 0, 0)
; template <class Epi, class ColV>
; DI void gemm_tile(const bf16_t* __restrict__ A, int lda, const bf16_t* __restrict__ Bt, int ldb, int K, int m0, int n0, unsigned char* smem, Epi epi, ColV colv, const bf16_t* __restrict__ HYT = nullptr) {
;     ...
;     auto step = [&](int kt, u32x4 (&ldset)[8], const u32x4 (&stset)[8]) {
;         const int buf = kt & 1;
;         if (kt + 2 < nk) gload(ldset, kt + 2);
;         const bf16_t* Ab = As + (buf * 128 + 64 * wr + li) * LS + 8 * lh;
;         const bf16_t* Bb = Bs + (buf * 128 + 64 * wc + li) * LS + 8 * lh;
;         bf16x8 fa[2][2], fb[2][2], ga[2][2], gb[2][2];
; #pragma unroll
;         for (int k2 = 0; k2 < 2; ++k2) { fa[k2][0] = ld8(Ab + 16 * k2); fa[k2][1] = ld8(Ab + 32 * LS + 16 * k2); fb[k2][0] = ld8(Bb + 16 * k2); fb[k2][1] = ld8(Bb + 32 * LS + 16 * k2); }
;         __builtin_amdgcn_sched_barrier(0);
; #pragma unroll
;         for (int k2 = 0; k2 < 2; ++k2) {
;             acc[0][0] = MFMA(fa[k2][0], fb[k2][0], acc[0][0]); acc[0][1] = MFMA(fa[k2][0], fb[k2][1], acc[0][1]);
;             acc[1][0] = MFMA(fa[k2][1], fb[k2][0], acc[1][0]); acc[1][1] = MFMA(fa[k2][1], fb[k2][1], acc[1][1]);
;         }
; #pragma unroll
;         for (int k2 = 0; k2 < 2; ++k2) { const int ks = 2 + k2; ga[k2][0] = ld8(Ab + 16 * ks); ga[k2][1] = ld8(Ab + 32 * LS + 16 * ks); gb[k2][0] = ld8(Bb + 16 * ks); gb[k2][1] = ld8(Bb + 32 * LS + 16 * ks); }
; #pragma unroll
;         for (int k2 = 0; k2 < 2; ++k2) {
;             acc[0][0] = MFMA(ga[k2][0], gb[k2][0], acc[0][0]); acc[0][1] = MFMA(ga[k2][0], gb[k2][1], acc[0][1]);
;             acc[1][0] = MFMA(ga[k2][1], gb[k2][0], acc[1][0]); acc[1][1] = MFMA(ga[k2][1], gb[k2][1], acc[1][1]);
;         }
;         if (kt + 1 < nk) sstore(stset, buf ^ 1, kt + 1);
; #pragma unroll
;         for (int i = 0; i < 8; ++i) { __builtin_amdgcn_sched_group_barrier(0x008, 1, 0); __builtin_amdgcn_sched_group_barrier(0x100, 1, 0); }
; #pragma unroll
;         for (int i = 0; i < 8; ++i) { __builtin_amdgcn_sched_group_barrier(0x008, 1, 0); __builtin_amdgcn_sched_group_barrier(0x200, 1, 0); }
;         __builtin_amdgcn_sched_barrier(0);
;         __syncthreads();
;     };
	ds_read_b128 v[174:177], v196
	ds_read_b128 v[210:213], v197 offset:36864
	ds_read_b128 v[218:221], v197 offset:41472
	ds_read_b128 v[202:205], v196 offset:4608
	ds_read_b128 v[178:181], v196 offset:32
	ds_read_b128 v[222:225], v197 offset:41504
	ds_read_b128 v[206:209], v196 offset:4640
	ds_read_b128 v[214:217], v197 offset:36896
	s_waitcnt lgkmcnt(6)
	v_mfma_f32_32x32x16_bf16 v[52:67], v[174:177], v[210:213], v[52:67]
	global_load_dwordx4 v[88:91], v[164:165], off offset:512
	s_waitcnt lgkmcnt(5)
	v_mfma_f32_32x32x16_bf16 v[36:51], v[174:177], v[218:221], v[36:51]
	global_load_dwordx4 v[96:99], v[162:163], off offset:512
	s_waitcnt lgkmcnt(4)
	v_mfma_f32_32x32x16_bf16 v[4:19], v[202:205], v[218:221], v[4:19]
	global_load_dwordx4 v[100:103], v[160:161], off offset:512
	s_waitcnt lgkmcnt(2)
	v_mfma_f32_32x32x16_bf16 v[36:51], v[178:181], v[222:225], v[36:51]
	global_load_dwordx4 v[108:111], v[158:159], off offset:512
	s_waitcnt lgkmcnt(1)
	v_mfma_f32_32x32x16_bf16 v[4:19], v[206:209], v[222:225], v[4:19]
	global_load_dwordx4 v[116:119], v[156:157], off offset:512
	ds_read_b128 v[222:225], v197 offset:41568
	ds_read_b128 v[174:177], v196 offset:4672
	v_mfma_f32_32x32x16_bf16 v[20:35], v[202:205], v[210:213], v[20:35]
	global_load_dwordx4 v[120:123], v[154:155], off offset:512
	ds_read_b128 v[210:213], v196 offset:4704
	ds_read_b128 v[202:205], v196 offset:64
	s_waitcnt lgkmcnt(4)
	v_mfma_f32_32x32x16_bf16 v[52:67], v[178:181], v[214:217], v[52:67]
	global_load_dwordx4 v[124:127], v[152:153], off offset:512
	ds_read_b128 v[218:221], v197 offset:36960
	ds_read_b128 v[178:181], v197 offset:41536
	v_mfma_f32_32x32x16_bf16 v[20:35], v[206:209], v[214:217], v[20:35]
	global_load_dwordx4 v[128:131], v[146:147], off offset:512
	ds_read_b128 v[214:217], v197 offset:36928
	ds_read_b128 v[206:209], v196 offset:96
	s_waitcnt lgkmcnt(1)
	v_mfma_f32_32x32x16_bf16 v[52:67], v[202:205], v[214:217], v[52:67]
	s_waitcnt vmcnt(23)
	ds_write_b128 v167, v[132:135]
	v_mfma_f32_32x32x16_bf16 v[36:51], v[202:205], v[178:181], v[36:51]
	s_waitcnt vmcnt(22)
	ds_write_b128 v167, v[136:139] offset:36864
	v_mfma_f32_32x32x16_bf16 v[20:35], v[174:177], v[214:217], v[20:35]
	s_waitcnt vmcnt(21)
	ds_write_b128 v190, v[140:143]
	v_mfma_f32_32x32x16_bf16 v[4:19], v[174:177], v[178:181], v[4:19]
	s_waitcnt vmcnt(20)
	ds_write_b128 v190, v[198:201] offset:36864
	s_waitcnt lgkmcnt(4)
	v_mfma_f32_32x32x16_bf16 v[52:67], v[206:209], v[218:221], v[52:67]
	s_waitcnt vmcnt(19)
	ds_write_b128 v191, v[226:229]
	v_mfma_f32_32x32x16_bf16 v[36:51], v[206:209], v[222:225], v[36:51]
	s_waitcnt vmcnt(18)
	ds_write_b128 v191, v[230:233] offset:36864
	v_mfma_f32_32x32x16_bf16 v[20:35], v[210:213], v[218:221], v[20:35]
	s_waitcnt vmcnt(17)
	ds_write_b128 v192, v[242:245]
	v_mfma_f32_32x32x16_bf16 v[4:19], v[210:213], v[222:225], v[4:19]
	s_waitcnt vmcnt(16)
	ds_write_b128 v192, v[246:249] offset:36864
	s_waitcnt lgkmcnt(0)
	s_barrier
	ds_read_b128 v[174:177], v194
	ds_read_b128 v[210:213], v195 offset:36864
	ds_read_b128 v[218:221], v195 offset:41472
	ds_read_b128 v[202:205], v194 offset:4608
	ds_read_b128 v[178:181], v194 offset:32
	ds_read_b128 v[222:225], v195 offset:41504
	ds_read_b128 v[206:209], v194 offset:4640
	ds_read_b128 v[214:217], v195 offset:36896
	s_waitcnt lgkmcnt(6)
	v_mfma_f32_32x32x16_bf16 v[52:67], v[174:177], v[210:213], v[52:67]
	global_load_dwordx4 v[132:135], v[164:165], off offset:640
	s_waitcnt lgkmcnt(5)
	v_mfma_f32_32x32x16_bf16 v[36:51], v[174:177], v[218:221], v[36:51]
	global_load_dwordx4 v[136:139], v[162:163], off offset:640
	s_waitcnt lgkmcnt(4)
	v_mfma_f32_32x32x16_bf16 v[4:19], v[202:205], v[218:221], v[4:19]
	global_load_dwordx4 v[140:143], v[160:161], off offset:640
	s_waitcnt lgkmcnt(2)
	v_mfma_f32_32x32x16_bf16 v[36:51], v[178:181], v[222:225], v[36:51]
	global_load_dwordx4 v[198:201], v[158:159], off offset:640
	s_waitcnt lgkmcnt(1)
	v_mfma_f32_32x32x16_bf16 v[4:19], v[206:209], v[222:225], v[4:19]
	global_load_dwordx4 v[226:229], v[156:157], off offset:640
	ds_read_b128 v[222:225], v195 offset:41568
	ds_read_b128 v[174:177], v194 offset:4672
	v_mfma_f32_32x32x16_bf16 v[20:35], v[202:205], v[210:213], v[20:35]
	global_load_dwordx4 v[230:233], v[154:155], off offset:640
	ds_read_b128 v[210:213], v194 offset:4704
	ds_read_b128 v[202:205], v194 offset:64
	s_waitcnt lgkmcnt(4)
	v_mfma_f32_32x32x16_bf16 v[52:67], v[178:181], v[214:217], v[52:67]
	global_load_dwordx4 v[242:245], v[152:153], off offset:640
	ds_read_b128 v[218:221], v195 offset:36960
	ds_read_b128 v[178:181], v195 offset:41536
	v_mfma_f32_32x32x16_bf16 v[20:35], v[206:209], v[214:217], v[20:35]
	global_load_dwordx4 v[246:249], v[146:147], off offset:640
	ds_read_b128 v[214:217], v195 offset:36928
	ds_read_b128 v[206:209], v194 offset:96
	s_waitcnt lgkmcnt(1)
	v_mfma_f32_32x32x16_bf16 v[52:67], v[202:205], v[214:217], v[52:67]
	s_waitcnt vmcnt(23)
	ds_write_b128 v167, v[68:71] offset:18432
	v_mfma_f32_32x32x16_bf16 v[36:51], v[202:205], v[178:181], v[36:51]
	s_waitcnt vmcnt(22)
	ds_write_b128 v167, v[72:75] offset:55296
	v_mfma_f32_32x32x16_bf16 v[20:35], v[174:177], v[214:217], v[20:35]
	s_waitcnt vmcnt(21)
	ds_write_b128 v190, v[76:79] offset:18432
	v_mfma_f32_32x32x16_bf16 v[4:19], v[174:177], v[178:181], v[4:19]
	s_waitcnt vmcnt(20)
	ds_write_b128 v190, v[80:83] offset:55296
	s_waitcnt lgkmcnt(4)
	v_mfma_f32_32x32x16_bf16 v[52:67], v[206:209], v[218:221], v[52:67]
	s_waitcnt vmcnt(19)
	ds_write_b128 v191, v[84:87] offset:18432
	v_mfma_f32_32x32x16_bf16 v[36:51], v[206:209], v[222:225], v[36:51]
	s_waitcnt vmcnt(18)
	ds_write_b128 v191, v[92:95] offset:55296
	v_mfma_f32_32x32x16_bf16 v[20:35], v[210:213], v[218:221], v[20:35]
	s_waitcnt vmcnt(17)
	ds_write_b128 v192, v[104:107] offset:18432
	v_mfma_f32_32x32x16_bf16 v[4:19], v[210:213], v[222:225], v[4:19]
	s_waitcnt vmcnt(16)
	ds_write_b128 v192, v[112:115] offset:55296
	s_waitcnt lgkmcnt(0)
	s_barrier
; #define MFMA(a, b, c) __builtin_amdgcn_mfma_f32_32x32x16_bf16((a), (b), (c), 0, 0, 0)
; template <class Epi, class ColV>
; DI void gemm_tile(const bf16_t* __restrict__ A, int lda, const bf16_t* __restrict__ Bt, int ldb, int K, int m0, int n0, unsigned char* smem, Epi epi, ColV colv, const bf16_t* __restrict__ HYT = nullptr) {
;     ...
;     auto step = [&](int kt, u32x4 (&ldset)[8], const u32x4 (&stset)[8]) {
;         const int buf = kt & 1;
;         if (kt + 2 < nk) gload(ldset, kt + 2);
;         const bf16_t* Ab = As + (buf * 128 + 64 * wr + li) * LS + 8 * lh;
;         const bf16_t* Bb = Bs + (buf * 128 + 64 * wc + li) * LS + 8 * lh;
;         bf16x8 fa[2][2], fb[2][2], ga[2][2], gb[2][2];
; #pragma unroll
;         for (int k2 = 0; k2 < 2; ++k2) { fa[k2][0] = ld8(Ab + 16 * k2); fa[k2][1] = ld8(Ab + 32 * LS + 16 * k2); fb[k2][0] = ld8(Bb + 16 * k2); fb[k2][1] = ld8(Bb + 32 * LS + 16 * k2); }
;         __builtin_amdgcn_sched_barrier(0);
; #pragma unroll
;         for (int k2 = 0; k2 < 2; ++k2) {
;             acc[0][0] = MFMA(fa[k2][0], fb[k2][0], acc[0][0]); acc[0][1] = MFMA(fa[k2][0], fb[k2][1], acc[0][1]);
;             acc[1][0] = MFMA(fa[k2][1], fb[k2][0], acc[1][0]); acc[1][1] = MFMA(fa[k2][1], fb[k2][1], acc[1][1]);
;         }
; #pragma unroll
;         for (int k2 = 0; k2 < 2; ++k2) { const int ks = 2 + k2; ga[k2][0] = ld8(Ab + 16 * ks); ga[k2][1] = ld8(Ab + 32 * LS + 16 * ks); gb[k2][0] = ld8(Bb + 16 * ks); gb[k2][1] = ld8(Bb + 32 * LS + 16 * ks); }
; #pragma unroll
;         for (int k2 = 0; k2 < 2; ++k2) {
;             acc[0][0] = MFMA(ga[k2][0], gb[k2][0], acc[0][0]); acc[0][1] = MFMA(ga[k2][0], gb[k2][1], acc[0][1]);
;             acc[1][0] = MFMA(ga[k2][1], gb[k2][0], acc[1][0]); acc[1][1] = MFMA(ga[k2][1], gb[k2][1], acc[1][1]);
;         }
;         if (kt + 1 < nk) sstore(stset, buf ^ 1, kt + 1);
; #pragma unroll
;         for (int i = 0; i < 8; ++i) { __builtin_amdgcn_sched_group_barrier(0x008, 1, 0); __builtin_amdgcn_sched_group_barrier(0x100, 1, 0); }
; #pragma unroll
;         for (int i = 0; i < 8; ++i) { __builtin_amdgcn_sched_group_barrier(0x008, 1, 0); __builtin_amdgcn_sched_group_barrier(0x200, 1, 0); }
;         __builtin_amdgcn_sched_barrier(0);
;         __syncthreads();
;     };
	ds_read_b128 v[174:177], v196
	ds_read_b128 v[210:213], v197 offset:36864
	ds_read_b128 v[218:221], v197 offset:41472
	ds_read_b128 v[202:205], v196 offset:4608
	ds_read_b128 v[178:181], v196 offset:32
	ds_read_b128 v[222:225], v197 offset:41504
	ds_read_b128 v[206:209], v196 offset:4640
	ds_read_b128 v[214:217], v197 offset:36896
	s_waitcnt lgkmcnt(6)
	v_mfma_f32_32x32x16_bf16 v[52:67], v[174:177], v[210:213], v[52:67]
	global_load_dwordx4 v[68:71], v[164:165], off offset:768
	s_waitcnt lgkmcnt(5)
	v_mfma_f32_32x32x16_bf16 v[36:51], v[174:177], v[218:221], v[36:51]
	global_load_dwordx4 v[72:75], v[162:163], off offset:768
	s_waitcnt lgkmcnt(4)
	v_mfma_f32_32x32x16_bf16 v[4:19], v[202:205], v[218:221], v[4:19]
	global_load_dwordx4 v[76:79], v[160:161], off offset:768
	s_waitcnt lgkmcnt(2)
	v_mfma_f32_32x32x16_bf16 v[36:51], v[178:181], v[222:225], v[36:51]
	global_load_dwordx4 v[80:83], v[158:159], off offset:768
	s_waitcnt lgkmcnt(1)
	v_mfma_f32_32x32x16_bf16 v[4:19], v[206:209], v[222:225], v[4:19]
	global_load_dwordx4 v[84:87], v[156:157], off offset:768
	ds_read_b128 v[222:225], v197 offset:41568
	ds_read_b128 v[174:177], v196 offset:4672
	v_mfma_f32_32x32x16_bf16 v[20:35], v[202:205], v[210:213], v[20:35]
	global_load_dwordx4 v[92:95], v[154:155], off offset:768
	ds_read_b128 v[210:213], v196 offset:4704
	ds_read_b128 v[202:205], v196 offset:64
	s_waitcnt lgkmcnt(4)
	v_mfma_f32_32x32x16_bf16 v[52:67], v[178:181], v[214:217], v[52:67]
	global_load_dwordx4 v[104:107], v[152:153], off offset:768
	ds_read_b128 v[218:221], v197 offset:36960
	ds_read_b128 v[178:181], v197 offset:41536
	v_mfma_f32_32x32x16_bf16 v[20:35], v[206:209], v[214:217], v[20:35]
	global_load_dwordx4 v[112:115], v[146:147], off offset:768
	ds_read_b128 v[214:217], v197 offset:36928
	ds_read_b128 v[206:209], v196 offset:96
	s_waitcnt lgkmcnt(1)
	v_mfma_f32_32x32x16_bf16 v[52:67], v[202:205], v[214:217], v[52:67]
	s_waitcnt vmcnt(23)
	ds_write_b128 v167, v[88:91]
	v_mfma_f32_32x32x16_bf16 v[36:51], v[202:205], v[178:181], v[36:51]
	s_waitcnt vmcnt(22)
	ds_write_b128 v167, v[96:99] offset:36864
	v_mfma_f32_32x32x16_bf16 v[20:35], v[174:177], v[214:217], v[20:35]
	s_waitcnt vmcnt(21)
	ds_write_b128 v190, v[100:103]
	v_mfma_f32_32x32x16_bf16 v[4:19], v[174:177], v[178:181], v[4:19]
	s_waitcnt vmcnt(20)
	ds_write_b128 v190, v[108:111] offset:36864
	s_waitcnt lgkmcnt(4)
	v_mfma_f32_32x32x16_bf16 v[52:67], v[206:209], v[218:221], v[52:67]
	s_waitcnt vmcnt(19)
	ds_write_b128 v191, v[116:119]
	v_mfma_f32_32x32x16_bf16 v[36:51], v[206:209], v[222:225], v[36:51]
	s_waitcnt vmcnt(18)
	ds_write_b128 v191, v[120:123] offset:36864
	v_mfma_f32_32x32x16_bf16 v[20:35], v[210:213], v[218:221], v[20:35]
	s_waitcnt vmcnt(17)
	ds_write_b128 v192, v[124:127]
	v_mfma_f32_32x32x16_bf16 v[4:19], v[210:213], v[222:225], v[4:19]
	s_waitcnt vmcnt(16)
	ds_write_b128 v192, v[128:131] offset:36864
	s_waitcnt lgkmcnt(0)
	s_barrier
	ds_read_b128 v[174:177], v194
	ds_read_b128 v[210:213], v195 offset:36864
	ds_read_b128 v[218:221], v195 offset:41472
	ds_read_b128 v[202:205], v194 offset:4608
	ds_read_b128 v[178:181], v194 offset:32
	ds_read_b128 v[222:225], v195 offset:41504
	ds_read_b128 v[206:209], v194 offset:4640
	ds_read_b128 v[214:217], v195 offset:36896
	s_waitcnt lgkmcnt(6)
	v_mfma_f32_32x32x16_bf16 v[52:67], v[174:177], v[210:213], v[52:67]
	global_load_dwordx4 v[88:91], v[164:165], off offset:896
	s_waitcnt lgkmcnt(5)
	v_mfma_f32_32x32x16_bf16 v[36:51], v[174:177], v[218:221], v[36:51]
	global_load_dwordx4 v[96:99], v[162:163], off offset:896
	s_waitcnt lgkmcnt(4)
	v_mfma_f32_32x32x16_bf16 v[4:19], v[202:205], v[218:221], v[4:19]
	global_load_dwordx4 v[100:103], v[160:161], off offset:896
	s_waitcnt lgkmcnt(2)
	v_mfma_f32_32x32x16_bf16 v[36:51], v[178:181], v[222:225], v[36:51]
	global_load_dwordx4 v[108:111], v[158:159], off offset:896
	s_waitcnt lgkmcnt(1)
	v_mfma_f32_32x32x16_bf16 v[4:19], v[206:209], v[222:225], v[4:19]
	global_load_dwordx4 v[116:119], v[156:157], off offset:896
	ds_read_b128 v[222:225], v195 offset:41568
	ds_read_b128 v[174:177], v194 offset:4672
	v_mfma_f32_32x32x16_bf16 v[20:35], v[202:205], v[210:213], v[20:35]
	global_load_dwordx4 v[120:123], v[154:155], off offset:896
	ds_read_b128 v[210:213], v194 offset:4704
	ds_read_b128 v[202:205], v194 offset:64
	s_waitcnt lgkmcnt(4)
	v_mfma_f32_32x32x16_bf16 v[52:67], v[178:181], v[214:217], v[52:67]
	global_load_dwordx4 v[124:127], v[152:153], off offset:896
	ds_read_b128 v[218:221], v195 offset:36960
	ds_read_b128 v[178:181], v195 offset:41536
	v_mfma_f32_32x32x16_bf16 v[20:35], v[206:209], v[214:217], v[20:35]
	global_load_dwordx4 v[128:131], v[146:147], off offset:896
	ds_read_b128 v[214:217], v195 offset:36928
	ds_read_b128 v[206:209], v194 offset:96
	s_waitcnt lgkmcnt(1)
	v_mfma_f32_32x32x16_bf16 v[52:67], v[202:205], v[214:217], v[52:67]
	s_waitcnt vmcnt(23)
	ds_write_b128 v167, v[132:135] offset:18432
	v_mfma_f32_32x32x16_bf16 v[36:51], v[202:205], v[178:181], v[36:51]
	s_waitcnt vmcnt(22)
	ds_write_b128 v167, v[136:139] offset:55296
	v_mfma_f32_32x32x16_bf16 v[20:35], v[174:177], v[214:217], v[20:35]
	s_waitcnt vmcnt(21)
	ds_write_b128 v190, v[140:143] offset:18432
	v_mfma_f32_32x32x16_bf16 v[4:19], v[174:177], v[178:181], v[4:19]
	s_waitcnt vmcnt(20)
	ds_write_b128 v190, v[198:201] offset:55296
	s_waitcnt lgkmcnt(4)
	v_mfma_f32_32x32x16_bf16 v[52:67], v[206:209], v[218:221], v[52:67]
	s_waitcnt vmcnt(19)
	ds_write_b128 v191, v[226:229] offset:18432
	v_mfma_f32_32x32x16_bf16 v[36:51], v[206:209], v[222:225], v[36:51]
	s_waitcnt vmcnt(18)
	ds_write_b128 v191, v[230:233] offset:55296
	v_mfma_f32_32x32x16_bf16 v[20:35], v[210:213], v[218:221], v[20:35]
	s_waitcnt vmcnt(17)
	ds_write_b128 v192, v[242:245] offset:18432
	v_mfma_f32_32x32x16_bf16 v[4:19], v[210:213], v[222:225], v[4:19]
	s_waitcnt vmcnt(16)
	ds_write_b128 v192, v[246:249] offset:55296
	s_waitcnt lgkmcnt(0)
	s_barrier
; #define MFMA(a, b, c) __builtin_amdgcn_mfma_f32_32x32x16_bf16((a), (b), (c), 0, 0, 0)
; template <class Epi, class ColV>
; DI void gemm_tile(const bf16_t* __restrict__ A, int lda, const bf16_t* __restrict__ Bt, int ldb, int K, int m0, int n0, unsigned char* smem, Epi epi, ColV colv, const bf16_t* __restrict__ HYT = nullptr) {
;     ...
;     auto step = [&](int kt, u32x4 (&ldset)[8], const u32x4 (&stset)[8]) {
;         const int buf = kt & 1;
;         if (kt + 2 < nk) gload(ldset, kt + 2);
;         const bf16_t* Ab = As + (buf * 128 + 64 * wr + li) * LS + 8 * lh;
;         const bf16_t* Bb = Bs + (buf * 128 + 64 * wc + li) * LS + 8 * lh;
;         bf16x8 fa[2][2], fb[2][2], ga[2][2], gb[2][2];
; #pragma unroll
;         for (int k2 = 0; k2 < 2; ++k2) { fa[k2][0] = ld8(Ab + 16 * k2); fa[k2][1] = ld8(Ab + 32 * LS + 16 * k2); fb[k2][0] = ld8(Bb + 16 * k2); fb[k2][1] = ld8(Bb + 32 * LS + 16 * k2); }
;         __builtin_amdgcn_sched_barrier(0);
; #pragma unroll
;         for (int k2 = 0; k2 < 2; ++k2) {
;             acc[0][0] = MFMA(fa[k2][0], fb[k2][0], acc[0][0]); acc[0][1] = MFMA(fa[k2][0], fb[k2][1], acc[0][1]);
;             acc[1][0] = MFMA(fa[k2][1], fb[k2][0], acc[1][0]); acc[1][1] = MFMA(fa[k2][1], fb[k2][1], acc[1][1]);
;         }
; #pragma unroll
;         for (int k2 = 0; k2 < 2; ++k2) { const int ks = 2 + k2; ga[k2][0] = ld8(Ab + 16 * ks); ga[k2][1] = ld8(Ab + 32 * LS + 16 * ks); gb[k2][0] = ld8(Bb + 16 * ks); gb[k2][1] = ld8(Bb + 32 * LS + 16 * ks); }
; #pragma unroll
;         for (int k2 = 0; k2 < 2; ++k2) {
;             acc[0][0] = MFMA(ga[k2][0], gb[k2][0], acc[0][0]); acc[0][1] = MFMA(ga[k2][0], gb[k2][1], acc[0][1]);
;             acc[1][0] = MFMA(ga[k2][1], gb[k2][0], acc[1][0]); acc[1][1] = MFMA(ga[k2][1], gb[k2][1], acc[1][1]);
;         }
;         if (kt + 1 < nk) sstore(stset, buf ^ 1, kt + 1);
; #pragma unroll
;         for (int i = 0; i < 8; ++i) { __builtin_amdgcn_sched_group_barrier(0x008, 1, 0); __builtin_amdgcn_sched_group_barrier(0x100, 1, 0); }
; #pragma unroll
;         for (int i = 0; i < 8; ++i) { __builtin_amdgcn_sched_group_barrier(0x008, 1, 0); __builtin_amdgcn_sched_group_barrier(0x200, 1, 0); }
;         __builtin_amdgcn_sched_barrier(0);
;         __syncthreads();
;     };
	ds_read_b128 v[174:177], v196
	ds_read_b128 v[210:213], v197 offset:36864
	ds_read_b128 v[218:221], v197 offset:41472
	ds_read_b128 v[202:205], v196 offset:4608
	ds_read_b128 v[178:181], v196 offset:32
	ds_read_b128 v[222:225], v197 offset:41504
	ds_read_b128 v[206:209], v196 offset:4640
	ds_read_b128 v[214:217], v197 offset:36896
	s_waitcnt lgkmcnt(6)
	v_mfma_f32_32x32x16_bf16 v[52:67], v[174:177], v[210:213], v[52:67]
	global_load_dwordx4 v[132:135], v[164:165], off offset:1024
	s_waitcnt lgkmcnt(5)
	v_mfma_f32_32x32x16_bf16 v[36:51], v[174:177], v[218:221], v[36:51]
	global_load_dwordx4 v[136:139], v[162:163], off offset:1024
	s_waitcnt lgkmcnt(4)
	v_mfma_f32_32x32x16_bf16 v[4:19], v[202:205], v[218:221], v[4:19]
	global_load_dwordx4 v[140:143], v[160:161], off offset:1024
	s_waitcnt lgkmcnt(2)
	v_mfma_f32_32x32x16_bf16 v[36:51], v[178:181], v[222:225], v[36:51]
	global_load_dwordx4 v[198:201], v[158:159], off offset:1024
	s_waitcnt lgkmcnt(1)
	v_mfma_f32_32x32x16_bf16 v[4:19], v[206:209], v[222:225], v[4:19]
	global_load_dwordx4 v[226:229], v[156:157], off offset:1024
	ds_read_b128 v[222:225], v197 offset:41568
	ds_read_b128 v[174:177], v196 offset:4672
	v_mfma_f32_32x32x16_bf16 v[20:35], v[202:205], v[210:213], v[20:35]
	global_load_dwordx4 v[230:233], v[154:155], off offset:1024
	ds_read_b128 v[210:213], v196 offset:4704
	ds_read_b128 v[202:205], v196 offset:64
	s_waitcnt lgkmcnt(4)
	v_mfma_f32_32x32x16_bf16 v[52:67], v[178:181], v[214:217], v[52:67]
	global_load_dwordx4 v[242:245], v[152:153], off offset:1024
	ds_read_b128 v[218:221], v197 offset:36960
	ds_read_b128 v[178:181], v197 offset:41536
	v_mfma_f32_32x32x16_bf16 v[20:35], v[206:209], v[214:217], v[20:35]
	global_load_dwordx4 v[246:249], v[146:147], off offset:1024
	ds_read_b128 v[214:217], v197 offset:36928
	ds_read_b128 v[206:209], v196 offset:96
	s_waitcnt lgkmcnt(1)
	v_mfma_f32_32x32x16_bf16 v[52:67], v[202:205], v[214:217], v[52:67]
	s_waitcnt vmcnt(23)
	ds_write_b128 v167, v[68:71]
	v_mfma_f32_32x32x16_bf16 v[36:51], v[202:205], v[178:181], v[36:51]
	s_waitcnt vmcnt(22)
	ds_write_b128 v167, v[72:75] offset:36864
	v_mfma_f32_32x32x16_bf16 v[20:35], v[174:177], v[214:217], v[20:35]
	s_waitcnt vmcnt(21)
	ds_write_b128 v190, v[76:79]
	v_mfma_f32_32x32x16_bf16 v[4:19], v[174:177], v[178:181], v[4:19]
	s_waitcnt vmcnt(20)
	ds_write_b128 v190, v[80:83] offset:36864
	s_waitcnt lgkmcnt(4)
	v_mfma_f32_32x32x16_bf16 v[52:67], v[206:209], v[218:221], v[52:67]
	s_waitcnt vmcnt(19)
	ds_write_b128 v191, v[84:87]
	v_mfma_f32_32x32x16_bf16 v[36:51], v[206:209], v[222:225], v[36:51]
	s_waitcnt vmcnt(18)
	ds_write_b128 v191, v[92:95] offset:36864
	v_mfma_f32_32x32x16_bf16 v[20:35], v[210:213], v[218:221], v[20:35]
	s_waitcnt vmcnt(17)
	ds_write_b128 v192, v[104:107]
	v_mfma_f32_32x32x16_bf16 v[4:19], v[210:213], v[222:225], v[4:19]
	s_waitcnt vmcnt(16)
	ds_write_b128 v192, v[112:115] offset:36864
	s_waitcnt lgkmcnt(0)
	s_barrier
	ds_read_b128 v[174:177], v194
	ds_read_b128 v[210:213], v195 offset:36864
	ds_read_b128 v[218:221], v195 offset:41472
	ds_read_b128 v[202:205], v194 offset:4608
	ds_read_b128 v[178:181], v194 offset:32
	ds_read_b128 v[222:225], v195 offset:41504
	ds_read_b128 v[206:209], v194 offset:4640
	ds_read_b128 v[214:217], v195 offset:36896
	s_waitcnt lgkmcnt(6)
	v_mfma_f32_32x32x16_bf16 v[52:67], v[174:177], v[210:213], v[52:67]
	global_load_dwordx4 v[68:71], v[164:165], off offset:1152
	s_waitcnt lgkmcnt(5)
	v_mfma_f32_32x32x16_bf16 v[36:51], v[174:177], v[218:221], v[36:51]
	global_load_dwordx4 v[72:75], v[162:163], off offset:1152
	s_waitcnt lgkmcnt(4)
	v_mfma_f32_32x32x16_bf16 v[4:19], v[202:205], v[218:221], v[4:19]
	global_load_dwordx4 v[76:79], v[160:161], off offset:1152
	s_waitcnt lgkmcnt(2)
	v_mfma_f32_32x32x16_bf16 v[36:51], v[178:181], v[222:225], v[36:51]
	global_load_dwordx4 v[80:83], v[158:159], off offset:1152
	s_waitcnt lgkmcnt(1)
	v_mfma_f32_32x32x16_bf16 v[4:19], v[206:209], v[222:225], v[4:19]
	global_load_dwordx4 v[84:87], v[156:157], off offset:1152
	ds_read_b128 v[222:225], v195 offset:41568
	ds_read_b128 v[174:177], v194 offset:4672
	v_mfma_f32_32x32x16_bf16 v[20:35], v[202:205], v[210:213], v[20:35]
	global_load_dwordx4 v[92:95], v[154:155], off offset:1152
	ds_read_b128 v[210:213], v194 offset:4704
	ds_read_b128 v[202:205], v194 offset:64
	s_waitcnt lgkmcnt(4)
	v_mfma_f32_32x32x16_bf16 v[52:67], v[178:181], v[214:217], v[52:67]
	global_load_dwordx4 v[104:107], v[152:153], off offset:1152
	ds_read_b128 v[218:221], v195 offset:36960
	ds_read_b128 v[178:181], v195 offset:41536
	v_mfma_f32_32x32x16_bf16 v[20:35], v[206:209], v[214:217], v[20:35]
	global_load_dwordx4 v[112:115], v[146:147], off offset:1152
	ds_read_b128 v[214:217], v195 offset:36928
	ds_read_b128 v[206:209], v194 offset:96
	s_waitcnt lgkmcnt(1)
	v_mfma_f32_32x32x16_bf16 v[52:67], v[202:205], v[214:217], v[52:67]
	s_waitcnt vmcnt(23)
	ds_write_b128 v167, v[88:91] offset:18432
	v_mfma_f32_32x32x16_bf16 v[36:51], v[202:205], v[178:181], v[36:51]
	s_waitcnt vmcnt(22)
	ds_write_b128 v167, v[96:99] offset:55296
	v_mfma_f32_32x32x16_bf16 v[20:35], v[174:177], v[214:217], v[20:35]
	s_waitcnt vmcnt(21)
	ds_write_b128 v190, v[100:103] offset:18432
	v_mfma_f32_32x32x16_bf16 v[4:19], v[174:177], v[178:181], v[4:19]
	s_waitcnt vmcnt(20)
	ds_write_b128 v190, v[108:111] offset:55296
	s_waitcnt lgkmcnt(4)
	v_mfma_f32_32x32x16_bf16 v[52:67], v[206:209], v[218:221], v[52:67]
	s_waitcnt vmcnt(19)
	ds_write_b128 v191, v[116:119] offset:18432
	v_mfma_f32_32x32x16_bf16 v[36:51], v[206:209], v[222:225], v[36:51]
	s_waitcnt vmcnt(18)
	ds_write_b128 v191, v[120:123] offset:55296
	v_mfma_f32_32x32x16_bf16 v[20:35], v[210:213], v[218:221], v[20:35]
	s_waitcnt vmcnt(17)
	ds_write_b128 v192, v[124:127] offset:18432
	v_mfma_f32_32x32x16_bf16 v[4:19], v[210:213], v[222:225], v[4:19]
	s_waitcnt vmcnt(16)
	ds_write_b128 v192, v[128:131] offset:55296
	s_waitcnt lgkmcnt(0)
	s_barrier
; #define MFMA(a, b, c) __builtin_amdgcn_mfma_f32_32x32x16_bf16((a), (b), (c), 0, 0, 0)
; template <class Epi, class ColV>
; DI void gemm_tile(const bf16_t* __restrict__ A, int lda, const bf16_t* __restrict__ Bt, int ldb, int K, int m0, int n0, unsigned char* smem, Epi epi, ColV colv, const bf16_t* __restrict__ HYT = nullptr) {
;     ...
;     auto step = [&](int kt, u32x4 (&ldset)[8], const u32x4 (&stset)[8]) {
;         const int buf = kt & 1;
;         if (kt + 2 < nk) gload(ldset, kt + 2);
;         const bf16_t* Ab = As + (buf * 128 + 64 * wr + li) * LS + 8 * lh;
;         const bf16_t* Bb = Bs + (buf * 128 + 64 * wc + li) * LS + 8 * lh;
;         bf16x8 fa[2][2], fb[2][2], ga[2][2], gb[2][2];
; #pragma unroll
;         for (int k2 = 0; k2 < 2; ++k2) { fa[k2][0] = ld8(Ab + 16 * k2); fa[k2][1] = ld8(Ab + 32 * LS + 16 * k2); fb[k2][0] = ld8(Bb + 16 * k2); fb[k2][1] = ld8(Bb + 32 * LS + 16 * k2); }
;         __builtin_amdgcn_sched_barrier(0);
; #pragma unroll
;         for (int k2 = 0; k2 < 2; ++k2) {
;             acc[0][0] = MFMA(fa[k2][0], fb[k2][0], acc[0][0]); acc[0][1] = MFMA(fa[k2][0], fb[k2][1], acc[0][1]);
;             acc[1][0] = MFMA(fa[k2][1], fb[k2][0], acc[1][0]); acc[1][1] = MFMA(fa[k2][1], fb[k2][1], acc[1][1]);
;         }
; #pragma unroll
;         for (int k2 = 0; k2 < 2; ++k2) { const int ks = 2 + k2; ga[k2][0] = ld8(Ab + 16 * ks); ga[k2][1] = ld8(Ab + 32 * LS + 16 * ks); gb[k2][0] = ld8(Bb + 16 * ks); gb[k2][1] = ld8(Bb + 32 * LS + 16 * ks); }
; #pragma unroll
;         for (int k2 = 0; k2 < 2; ++k2) {
;             acc[0][0] = MFMA(ga[k2][0], gb[k2][0], acc[0][0]); acc[0][1] = MFMA(ga[k2][0], gb[k2][1], acc[0][1]);
;             acc[1][0] = MFMA(ga[k2][1], gb[k2][0], acc[1][0]); acc[1][1] = MFMA(ga[k2][1], gb[k2][1], acc[1][1]);
;         }
;         if (kt + 1 < nk) sstore(stset, buf ^ 1, kt + 1);
; #pragma unroll
;         for (int i = 0; i < 8; ++i) { __builtin_amdgcn_sched_group_barrier(0x008, 1, 0); __builtin_amdgcn_sched_group_barrier(0x100, 1, 0); }
; #pragma unroll
;         for (int i = 0; i < 8; ++i) { __builtin_amdgcn_sched_group_barrier(0x008, 1, 0); __builtin_amdgcn_sched_group_barrier(0x200, 1, 0); }
;         __builtin_amdgcn_sched_barrier(0);
;         __syncthreads();
;     };
	ds_read_b128 v[174:177], v196
	ds_read_b128 v[210:213], v197 offset:36864
	ds_read_b128 v[218:221], v197 offset:41472
	ds_read_b128 v[202:205], v196 offset:4608
	ds_read_b128 v[178:181], v196 offset:32
	ds_read_b128 v[222:225], v197 offset:41504
	ds_read_b128 v[206:209], v196 offset:4640
	ds_read_b128 v[214:217], v197 offset:36896
	s_waitcnt lgkmcnt(6)
	v_mfma_f32_32x32x16_bf16 v[52:67], v[174:177], v[210:213], v[52:67]
	global_load_dwordx4 v[88:91], v[164:165], off offset:1280
	s_waitcnt lgkmcnt(5)
	v_mfma_f32_32x32x16_bf16 v[36:51], v[174:177], v[218:221], v[36:51]
	global_load_dwordx4 v[96:99], v[162:163], off offset:1280
	s_waitcnt lgkmcnt(4)
	v_mfma_f32_32x32x16_bf16 v[4:19], v[202:205], v[218:221], v[4:19]
	global_load_dwordx4 v[100:103], v[160:161], off offset:1280
	s_waitcnt lgkmcnt(2)
	v_mfma_f32_32x32x16_bf16 v[36:51], v[178:181], v[222:225], v[36:51]
	global_load_dwordx4 v[108:111], v[158:159], off offset:1280
	s_waitcnt lgkmcnt(1)
	v_mfma_f32_32x32x16_bf16 v[4:19], v[206:209], v[222:225], v[4:19]
	global_load_dwordx4 v[116:119], v[156:157], off offset:1280
	ds_read_b128 v[222:225], v197 offset:41568
	ds_read_b128 v[174:177], v196 offset:4672
	v_mfma_f32_32x32x16_bf16 v[20:35], v[202:205], v[210:213], v[20:35]
	global_load_dwordx4 v[120:123], v[154:155], off offset:1280
	ds_read_b128 v[210:213], v196 offset:4704
	ds_read_b128 v[202:205], v196 offset:64
	s_waitcnt lgkmcnt(4)
	v_mfma_f32_32x32x16_bf16 v[52:67], v[178:181], v[214:217], v[52:67]
	global_load_dwordx4 v[124:127], v[152:153], off offset:1280
	ds_read_b128 v[218:221], v197 offset:36960
	ds_read_b128 v[178:181], v197 offset:41536
	v_mfma_f32_32x32x16_bf16 v[20:35], v[206:209], v[214:217], v[20:35]
	global_load_dwordx4 v[128:131], v[146:147], off offset:1280
	ds_read_b128 v[214:217], v197 offset:36928
	ds_read_b128 v[206:209], v196 offset:96
	s_waitcnt lgkmcnt(1)
	v_mfma_f32_32x32x16_bf16 v[52:67], v[202:205], v[214:217], v[52:67]
	s_waitcnt vmcnt(23)
	ds_write_b128 v167, v[132:135]
	v_mfma_f32_32x32x16_bf16 v[36:51], v[202:205], v[178:181], v[36:51]
	s_waitcnt vmcnt(22)
	ds_write_b128 v167, v[136:139] offset:36864
	v_mfma_f32_32x32x16_bf16 v[20:35], v[174:177], v[214:217], v[20:35]
	s_waitcnt vmcnt(21)
	ds_write_b128 v190, v[140:143]
	v_mfma_f32_32x32x16_bf16 v[4:19], v[174:177], v[178:181], v[4:19]
	s_waitcnt vmcnt(20)
	ds_write_b128 v190, v[198:201] offset:36864
	s_waitcnt lgkmcnt(4)
	v_mfma_f32_32x32x16_bf16 v[52:67], v[206:209], v[218:221], v[52:67]
	s_waitcnt vmcnt(19)
	ds_write_b128 v191, v[226:229]
	v_mfma_f32_32x32x16_bf16 v[36:51], v[206:209], v[222:225], v[36:51]
	s_waitcnt vmcnt(18)
	ds_write_b128 v191, v[230:233] offset:36864
	v_mfma_f32_32x32x16_bf16 v[20:35], v[210:213], v[218:221], v[20:35]
	s_waitcnt vmcnt(17)
	ds_write_b128 v192, v[242:245]
	v_mfma_f32_32x32x16_bf16 v[4:19], v[210:213], v[222:225], v[4:19]
	s_waitcnt vmcnt(16)
	ds_write_b128 v192, v[246:249] offset:36864
	s_waitcnt lgkmcnt(0)
	s_barrier
	ds_read_b128 v[174:177], v194
	ds_read_b128 v[210:213], v195 offset:36864
	ds_read_b128 v[218:221], v195 offset:41472
	ds_read_b128 v[202:205], v194 offset:4608
	ds_read_b128 v[178:181], v194 offset:32
	ds_read_b128 v[222:225], v195 offset:41504
	ds_read_b128 v[206:209], v194 offset:4640
	ds_read_b128 v[214:217], v195 offset:36896
	s_waitcnt lgkmcnt(6)
	v_mfma_f32_32x32x16_bf16 v[52:67], v[174:177], v[210:213], v[52:67]
	global_load_dwordx4 v[132:135], v[164:165], off offset:1408
	s_waitcnt lgkmcnt(5)
	v_mfma_f32_32x32x16_bf16 v[36:51], v[174:177], v[218:221], v[36:51]
	global_load_dwordx4 v[136:139], v[162:163], off offset:1408
	s_waitcnt lgkmcnt(4)
	v_mfma_f32_32x32x16_bf16 v[4:19], v[202:205], v[218:221], v[4:19]
	global_load_dwordx4 v[140:143], v[160:161], off offset:1408
	s_waitcnt lgkmcnt(2)
	v_mfma_f32_32x32x16_bf16 v[36:51], v[178:181], v[222:225], v[36:51]
	global_load_dwordx4 v[198:201], v[158:159], off offset:1408
	s_waitcnt lgkmcnt(1)
	v_mfma_f32_32x32x16_bf16 v[4:19], v[206:209], v[222:225], v[4:19]
	global_load_dwordx4 v[226:229], v[156:157], off offset:1408
	ds_read_b128 v[222:225], v195 offset:41568
	ds_read_b128 v[174:177], v194 offset:4672
	v_mfma_f32_32x32x16_bf16 v[20:35], v[202:205], v[210:213], v[20:35]
	global_load_dwordx4 v[230:233], v[154:155], off offset:1408
	ds_read_b128 v[210:213], v194 offset:4704
	ds_read_b128 v[202:205], v194 offset:64
	s_waitcnt lgkmcnt(4)
	v_mfma_f32_32x32x16_bf16 v[52:67], v[178:181], v[214:217], v[52:67]
	global_load_dwordx4 v[242:245], v[152:153], off offset:1408
	ds_read_b128 v[218:221], v195 offset:36960
	ds_read_b128 v[178:181], v195 offset:41536
	v_mfma_f32_32x32x16_bf16 v[20:35], v[206:209], v[214:217], v[20:35]
	global_load_dwordx4 v[246:249], v[146:147], off offset:1408
	ds_read_b128 v[214:217], v195 offset:36928
	ds_read_b128 v[206:209], v194 offset:96
	s_waitcnt lgkmcnt(1)
	v_mfma_f32_32x32x16_bf16 v[52:67], v[202:205], v[214:217], v[52:67]
	s_waitcnt vmcnt(23)
	ds_write_b128 v167, v[68:71] offset:18432
	v_mfma_f32_32x32x16_bf16 v[36:51], v[202:205], v[178:181], v[36:51]
	s_waitcnt vmcnt(22)
	ds_write_b128 v167, v[72:75] offset:55296
	v_mfma_f32_32x32x16_bf16 v[20:35], v[174:177], v[214:217], v[20:35]
	s_waitcnt vmcnt(21)
	ds_write_b128 v190, v[76:79] offset:18432
	v_mfma_f32_32x32x16_bf16 v[4:19], v[174:177], v[178:181], v[4:19]
	s_waitcnt vmcnt(20)
	ds_write_b128 v190, v[80:83] offset:55296
	s_waitcnt lgkmcnt(4)
	v_mfma_f32_32x32x16_bf16 v[52:67], v[206:209], v[218:221], v[52:67]
	s_waitcnt vmcnt(19)
	ds_write_b128 v191, v[84:87] offset:18432
	v_mfma_f32_32x32x16_bf16 v[36:51], v[206:209], v[222:225], v[36:51]
	s_waitcnt vmcnt(18)
	ds_write_b128 v191, v[92:95] offset:55296
	v_mfma_f32_32x32x16_bf16 v[20:35], v[210:213], v[218:221], v[20:35]
	s_waitcnt vmcnt(17)
	ds_write_b128 v192, v[104:107] offset:18432
	v_mfma_f32_32x32x16_bf16 v[4:19], v[210:213], v[222:225], v[4:19]
	s_waitcnt vmcnt(16)
	ds_write_b128 v192, v[112:115] offset:55296
	s_waitcnt lgkmcnt(0)
	s_barrier
; #define MFMA(a, b, c) __builtin_amdgcn_mfma_f32_32x32x16_bf16((a), (b), (c), 0, 0, 0)
; template <class Epi, class ColV>
; DI void gemm_tile(const bf16_t* __restrict__ A, int lda, const bf16_t* __restrict__ Bt, int ldb, int K, int m0, int n0, unsigned char* smem, Epi epi, ColV colv, const bf16_t* __restrict__ HYT = nullptr) {
;     ...
;     auto step = [&](int kt, u32x4 (&ldset)[8], const u32x4 (&stset)[8]) {
;         const int buf = kt & 1;
;         if (kt + 2 < nk) gload(ldset, kt + 2);
;         const bf16_t* Ab = As + (buf * 128 + 64 * wr + li) * LS + 8 * lh;
;         const bf16_t* Bb = Bs + (buf * 128 + 64 * wc + li) * LS + 8 * lh;
;         bf16x8 fa[2][2], fb[2][2], ga[2][2], gb[2][2];
; #pragma unroll
;         for (int k2 = 0; k2 < 2; ++k2) { fa[k2][0] = ld8(Ab + 16 * k2); fa[k2][1] = ld8(Ab + 32 * LS + 16 * k2); fb[k2][0] = ld8(Bb + 16 * k2); fb[k2][1] = ld8(Bb + 32 * LS + 16 * k2); }
;         __builtin_amdgcn_sched_barrier(0);
; #pragma unroll
;         for (int k2 = 0; k2 < 2; ++k2) {
;             acc[0][0] = MFMA(fa[k2][0], fb[k2][0], acc[0][0]); acc[0][1] = MFMA(fa[k2][0], fb[k2][1], acc[0][1]);
;             acc[1][0] = MFMA(fa[k2][1], fb[k2][0], acc[1][0]); acc[1][1] = MFMA(fa[k2][1], fb[k2][1], acc[1][1]);
;         }
; #pragma unroll
;         for (int k2 = 0; k2 < 2; ++k2) { const int ks = 2 + k2; ga[k2][0] = ld8(Ab + 16 * ks); ga[k2][1] = ld8(Ab + 32 * LS + 16 * ks); gb[k2][0] = ld8(Bb + 16 * ks); gb[k2][1] = ld8(Bb + 32 * LS + 16 * ks); }
; #pragma unroll
;         for (int k2 = 0; k2 < 2; ++k2) {
;             acc[0][0] = MFMA(ga[k2][0], gb[k2][0], acc[0][0]); acc[0][1] = MFMA(ga[k2][0], gb[k2][1], acc[0][1]);
;             acc[1][0] = MFMA(ga[k2][1], gb[k2][0], acc[1][0]); acc[1][1] = MFMA(ga[k2][1], gb[k2][1], acc[1][1]);
;         }
;         if (kt + 1 < nk) sstore(stset, buf ^ 1, kt + 1);
; #pragma unroll
;         for (int i = 0; i < 8; ++i) { __builtin_amdgcn_sched_group_barrier(0x008, 1, 0); __builtin_amdgcn_sched_group_barrier(0x100, 1, 0); }
; #pragma unroll
;         for (int i = 0; i < 8; ++i) { __builtin_amdgcn_sched_group_barrier(0x008, 1, 0); __builtin_amdgcn_sched_group_barrier(0x200, 1, 0); }
;         __builtin_amdgcn_sched_barrier(0);
;         __syncthreads();
;     };
	ds_read_b128 v[174:177], v196
	ds_read_b128 v[210:213], v197 offset:36864
	ds_read_b128 v[218:221], v197 offset:41472
	ds_read_b128 v[202:205], v196 offset:4608
	ds_read_b128 v[178:181], v196 offset:32
	ds_read_b128 v[222:225], v197 offset:41504
	ds_read_b128 v[206:209], v196 offset:4640
	ds_read_b128 v[214:217], v197 offset:36896
	s_waitcnt lgkmcnt(6)
	v_mfma_f32_32x32x16_bf16 v[52:67], v[174:177], v[210:213], v[52:67]
	global_load_dwordx4 v[68:71], v[164:165], off offset:1536
	s_waitcnt lgkmcnt(5)
	v_mfma_f32_32x32x16_bf16 v[36:51], v[174:177], v[218:221], v[36:51]
	global_load_dwordx4 v[72:75], v[162:163], off offset:1536
	s_waitcnt lgkmcnt(4)
	v_mfma_f32_32x32x16_bf16 v[4:19], v[202:205], v[218:221], v[4:19]
	global_load_dwordx4 v[76:79], v[160:161], off offset:1536
	s_waitcnt lgkmcnt(2)
	v_mfma_f32_32x32x16_bf16 v[36:51], v[178:181], v[222:225], v[36:51]
	global_load_dwordx4 v[80:83], v[158:159], off offset:1536
	s_waitcnt lgkmcnt(1)
	v_mfma_f32_32x32x16_bf16 v[4:19], v[206:209], v[222:225], v[4:19]
	global_load_dwordx4 v[84:87], v[156:157], off offset:1536
	ds_read_b128 v[222:225], v197 offset:41568
	ds_read_b128 v[174:177], v196 offset:4672
	v_mfma_f32_32x32x16_bf16 v[20:35], v[202:205], v[210:213], v[20:35]
	global_load_dwordx4 v[92:95], v[154:155], off offset:1536
	ds_read_b128 v[210:213], v196 offset:4704
	ds_read_b128 v[202:205], v196 offset:64
	s_waitcnt lgkmcnt(4)
	v_mfma_f32_32x32x16_bf16 v[52:67], v[178:181], v[214:217], v[52:67]
	global_load_dwordx4 v[104:107], v[152:153], off offset:1536
	ds_read_b128 v[218:221], v197 offset:36960
	ds_read_b128 v[178:181], v197 offset:41536
	v_mfma_f32_32x32x16_bf16 v[20:35], v[206:209], v[214:217], v[20:35]
	global_load_dwordx4 v[112:115], v[146:147], off offset:1536
	ds_read_b128 v[214:217], v197 offset:36928
	ds_read_b128 v[206:209], v196 offset:96
	s_waitcnt lgkmcnt(1)
	v_mfma_f32_32x32x16_bf16 v[52:67], v[202:205], v[214:217], v[52:67]
	s_waitcnt vmcnt(23)
	ds_write_b128 v167, v[88:91]
	v_mfma_f32_32x32x16_bf16 v[36:51], v[202:205], v[178:181], v[36:51]
	s_waitcnt vmcnt(22)
	ds_write_b128 v167, v[96:99] offset:36864
	v_mfma_f32_32x32x16_bf16 v[20:35], v[174:177], v[214:217], v[20:35]
	s_waitcnt vmcnt(21)
	ds_write_b128 v190, v[100:103]
	v_mfma_f32_32x32x16_bf16 v[4:19], v[174:177], v[178:181], v[4:19]
	s_waitcnt vmcnt(20)
	ds_write_b128 v190, v[108:111] offset:36864
	s_waitcnt lgkmcnt(4)
	v_mfma_f32_32x32x16_bf16 v[52:67], v[206:209], v[218:221], v[52:67]
	s_waitcnt vmcnt(19)
	ds_write_b128 v191, v[116:119]
	v_mfma_f32_32x32x16_bf16 v[36:51], v[206:209], v[222:225], v[36:51]
	s_waitcnt vmcnt(18)
	ds_write_b128 v191, v[120:123] offset:36864
	v_mfma_f32_32x32x16_bf16 v[20:35], v[210:213], v[218:221], v[20:35]
	s_waitcnt vmcnt(17)
	ds_write_b128 v192, v[124:127]
	v_mfma_f32_32x32x16_bf16 v[4:19], v[210:213], v[222:225], v[4:19]
	s_waitcnt vmcnt(16)
	ds_write_b128 v192, v[128:131] offset:36864
	s_waitcnt lgkmcnt(0)
	s_barrier
	ds_read_b128 v[174:177], v194
	ds_read_b128 v[210:213], v195 offset:36864
	ds_read_b128 v[218:221], v195 offset:41472
	ds_read_b128 v[202:205], v194 offset:4608
	ds_read_b128 v[178:181], v194 offset:32
	ds_read_b128 v[222:225], v195 offset:41504
	ds_read_b128 v[206:209], v194 offset:4640
	ds_read_b128 v[214:217], v195 offset:36896
	s_waitcnt lgkmcnt(6)
	v_mfma_f32_32x32x16_bf16 v[52:67], v[174:177], v[210:213], v[52:67]
	global_load_dwordx4 v[88:91], v[164:165], off offset:1664
	s_waitcnt lgkmcnt(5)
	v_mfma_f32_32x32x16_bf16 v[36:51], v[174:177], v[218:221], v[36:51]
	global_load_dwordx4 v[96:99], v[162:163], off offset:1664
	s_waitcnt lgkmcnt(4)
	v_mfma_f32_32x32x16_bf16 v[4:19], v[202:205], v[218:221], v[4:19]
	global_load_dwordx4 v[100:103], v[160:161], off offset:1664
	s_waitcnt lgkmcnt(2)
	v_mfma_f32_32x32x16_bf16 v[36:51], v[178:181], v[222:225], v[36:51]
	global_load_dwordx4 v[108:111], v[158:159], off offset:1664
	s_waitcnt lgkmcnt(1)
	v_mfma_f32_32x32x16_bf16 v[4:19], v[206:209], v[222:225], v[4:19]
	global_load_dwordx4 v[116:119], v[156:157], off offset:1664
	ds_read_b128 v[222:225], v195 offset:41568
	ds_read_b128 v[174:177], v194 offset:4672
	v_mfma_f32_32x32x16_bf16 v[20:35], v[202:205], v[210:213], v[20:35]
	global_load_dwordx4 v[120:123], v[154:155], off offset:1664
	ds_read_b128 v[210:213], v194 offset:4704
	ds_read_b128 v[202:205], v194 offset:64
	s_waitcnt lgkmcnt(4)
	v_mfma_f32_32x32x16_bf16 v[52:67], v[178:181], v[214:217], v[52:67]
	global_load_dwordx4 v[124:127], v[152:153], off offset:1664
	ds_read_b128 v[218:221], v195 offset:36960
	ds_read_b128 v[178:181], v195 offset:41536
	v_mfma_f32_32x32x16_bf16 v[20:35], v[206:209], v[214:217], v[20:35]
	global_load_dwordx4 v[128:131], v[146:147], off offset:1664
	ds_read_b128 v[214:217], v195 offset:36928
	ds_read_b128 v[206:209], v194 offset:96
	s_waitcnt lgkmcnt(1)
	v_mfma_f32_32x32x16_bf16 v[52:67], v[202:205], v[214:217], v[52:67]
	s_waitcnt vmcnt(23)
	ds_write_b128 v167, v[132:135] offset:18432
	v_mfma_f32_32x32x16_bf16 v[36:51], v[202:205], v[178:181], v[36:51]
	s_waitcnt vmcnt(22)
	ds_write_b128 v167, v[136:139] offset:55296
	v_mfma_f32_32x32x16_bf16 v[20:35], v[174:177], v[214:217], v[20:35]
	s_waitcnt vmcnt(21)
	ds_write_b128 v190, v[140:143] offset:18432
	v_mfma_f32_32x32x16_bf16 v[4:19], v[174:177], v[178:181], v[4:19]
	s_waitcnt vmcnt(20)
	ds_write_b128 v190, v[198:201] offset:55296
	s_waitcnt lgkmcnt(4)
	v_mfma_f32_32x32x16_bf16 v[52:67], v[206:209], v[218:221], v[52:67]
	s_waitcnt vmcnt(19)
	ds_write_b128 v191, v[226:229] offset:18432
	v_mfma_f32_32x32x16_bf16 v[36:51], v[206:209], v[222:225], v[36:51]
	s_waitcnt vmcnt(18)
	ds_write_b128 v191, v[230:233] offset:55296
	v_mfma_f32_32x32x16_bf16 v[20:35], v[210:213], v[218:221], v[20:35]
	s_waitcnt vmcnt(17)
	ds_write_b128 v192, v[242:245] offset:18432
	v_mfma_f32_32x32x16_bf16 v[4:19], v[210:213], v[222:225], v[4:19]
	s_waitcnt vmcnt(16)
	ds_write_b128 v192, v[246:249] offset:55296
	s_waitcnt lgkmcnt(0)
	s_barrier
; #define MFMA(a, b, c) __builtin_amdgcn_mfma_f32_32x32x16_bf16((a), (b), (c), 0, 0, 0)
; template <class Epi, class ColV>
; DI void gemm_tile(const bf16_t* __restrict__ A, int lda, const bf16_t* __restrict__ Bt, int ldb, int K, int m0, int n0, unsigned char* smem, Epi epi, ColV colv, const bf16_t* __restrict__ HYT = nullptr) {
;     ...
;     auto step = [&](int kt, u32x4 (&ldset)[8], const u32x4 (&stset)[8]) {
;         const int buf = kt & 1;
;         if (kt + 2 < nk) gload(ldset, kt + 2);
;         const bf16_t* Ab = As + (buf * 128 + 64 * wr + li) * LS + 8 * lh;
;         const bf16_t* Bb = Bs + (buf * 128 + 64 * wc + li) * LS + 8 * lh;
;         bf16x8 fa[2][2], fb[2][2], ga[2][2], gb[2][2];
; #pragma unroll
;         for (int k2 = 0; k2 < 2; ++k2) { fa[k2][0] = ld8(Ab + 16 * k2); fa[k2][1] = ld8(Ab + 32 * LS + 16 * k2); fb[k2][0] = ld8(Bb + 16 * k2); fb[k2][1] = ld8(Bb + 32 * LS + 16 * k2); }
;         __builtin_amdgcn_sched_barrier(0);
; #pragma unroll
;         for (int k2 = 0; k2 < 2; ++k2) {
;             acc[0][0] = MFMA(fa[k2][0], fb[k2][0], acc[0][0]); acc[0][1] = MFMA(fa[k2][0], fb[k2][1], acc[0][1]);
;             acc[1][0] = MFMA(fa[k2][1], fb[k2][0], acc[1][0]); acc[1][1] = MFMA(fa[k2][1], fb[k2][1], acc[1][1]);
;         }
; #pragma unroll
;         for (int k2 = 0; k2 < 2; ++k2) { const int ks = 2 + k2; ga[k2][0] = ld8(Ab + 16 * ks); ga[k2][1] = ld8(Ab + 32 * LS + 16 * ks); gb[k2][0] = ld8(Bb + 16 * ks); gb[k2][1] = ld8(Bb + 32 * LS + 16 * ks); }
; #pragma unroll
;         for (int k2 = 0; k2 < 2; ++k2) {
;             acc[0][0] = MFMA(ga[k2][0], gb[k2][0], acc[0][0]); acc[0][1] = MFMA(ga[k2][0], gb[k2][1], acc[0][1]);
;             acc[1][0] = MFMA(ga[k2][1], gb[k2][0], acc[1][0]); acc[1][1] = MFMA(ga[k2][1], gb[k2][1], acc[1][1]);
;         }
;         if (kt + 1 < nk) sstore(stset, buf ^ 1, kt + 1);
; #pragma unroll
;         for (int i = 0; i < 8; ++i) { __builtin_amdgcn_sched_group_barrier(0x008, 1, 0); __builtin_amdgcn_sched_group_barrier(0x100, 1, 0); }
; #pragma unroll
;         for (int i = 0; i < 8; ++i) { __builtin_amdgcn_sched_group_barrier(0x008, 1, 0); __builtin_amdgcn_sched_group_barrier(0x200, 1, 0); }
;         __builtin_amdgcn_sched_barrier(0);
;         __syncthreads();
;     };
	ds_read_b128 v[174:177], v196
	ds_read_b128 v[210:213], v197 offset:36864
	ds_read_b128 v[218:221], v197 offset:41472
	ds_read_b128 v[202:205], v196 offset:4608
	ds_read_b128 v[178:181], v196 offset:32
	ds_read_b128 v[222:225], v197 offset:41504
	ds_read_b128 v[206:209], v196 offset:4640
	ds_read_b128 v[214:217], v197 offset:36896
	s_waitcnt lgkmcnt(6)
	v_mfma_f32_32x32x16_bf16 v[52:67], v[174:177], v[210:213], v[52:67]
	global_load_dwordx4 v[132:135], v[164:165], off offset:1792
	s_waitcnt lgkmcnt(5)
	v_mfma_f32_32x32x16_bf16 v[36:51], v[174:177], v[218:221], v[36:51]
	global_load_dwordx4 v[136:139], v[162:163], off offset:1792
	s_waitcnt lgkmcnt(4)
	v_mfma_f32_32x32x16_bf16 v[4:19], v[202:205], v[218:221], v[4:19]
	global_load_dwordx4 v[140:143], v[160:161], off offset:1792
	s_waitcnt lgkmcnt(2)
	v_mfma_f32_32x32x16_bf16 v[36:51], v[178:181], v[222:225], v[36:51]
	global_load_dwordx4 v[198:201], v[158:159], off offset:1792
	s_waitcnt lgkmcnt(1)
	v_mfma_f32_32x32x16_bf16 v[4:19], v[206:209], v[222:225], v[4:19]
	global_load_dwordx4 v[226:229], v[156:157], off offset:1792
	ds_read_b128 v[222:225], v197 offset:41568
	ds_read_b128 v[174:177], v196 offset:4672
	v_mfma_f32_32x32x16_bf16 v[20:35], v[202:205], v[210:213], v[20:35]
	global_load_dwordx4 v[230:233], v[154:155], off offset:1792
	ds_read_b128 v[210:213], v196 offset:4704
	ds_read_b128 v[202:205], v196 offset:64
	s_waitcnt lgkmcnt(4)
	v_mfma_f32_32x32x16_bf16 v[52:67], v[178:181], v[214:217], v[52:67]
	global_load_dwordx4 v[242:245], v[152:153], off offset:1792
	ds_read_b128 v[218:221], v197 offset:36960
	ds_read_b128 v[178:181], v197 offset:41536
	v_mfma_f32_32x32x16_bf16 v[20:35], v[206:209], v[214:217], v[20:35]
	global_load_dwordx4 v[246:249], v[146:147], off offset:1792
	ds_read_b128 v[214:217], v197 offset:36928
	ds_read_b128 v[206:209], v196 offset:96
	s_waitcnt lgkmcnt(1)
	v_mfma_f32_32x32x16_bf16 v[52:67], v[202:205], v[214:217], v[52:67]
	s_waitcnt vmcnt(23)
	ds_write_b128 v167, v[68:71]
	v_mfma_f32_32x32x16_bf16 v[36:51], v[202:205], v[178:181], v[36:51]
	s_waitcnt vmcnt(22)
	ds_write_b128 v167, v[72:75] offset:36864
	v_mfma_f32_32x32x16_bf16 v[20:35], v[174:177], v[214:217], v[20:35]
	s_waitcnt vmcnt(21)
	ds_write_b128 v190, v[76:79]
	v_mfma_f32_32x32x16_bf16 v[4:19], v[174:177], v[178:181], v[4:19]
	s_waitcnt vmcnt(20)
	ds_write_b128 v190, v[80:83] offset:36864
	s_waitcnt lgkmcnt(4)
	v_mfma_f32_32x32x16_bf16 v[52:67], v[206:209], v[218:221], v[52:67]
	s_waitcnt vmcnt(19)
	ds_write_b128 v191, v[84:87]
	v_mfma_f32_32x32x16_bf16 v[36:51], v[206:209], v[222:225], v[36:51]
	s_waitcnt vmcnt(18)
	ds_write_b128 v191, v[92:95] offset:36864
	v_mfma_f32_32x32x16_bf16 v[20:35], v[210:213], v[218:221], v[20:35]
	s_waitcnt vmcnt(17)
	ds_write_b128 v192, v[104:107]
	v_mfma_f32_32x32x16_bf16 v[4:19], v[210:213], v[222:225], v[4:19]
	s_waitcnt vmcnt(16)
	ds_write_b128 v192, v[112:115] offset:36864
	s_waitcnt lgkmcnt(0)
	s_barrier
	ds_read_b128 v[174:177], v194
	ds_read_b128 v[210:213], v195 offset:36864
	ds_read_b128 v[218:221], v195 offset:41472
	ds_read_b128 v[202:205], v194 offset:4608
	ds_read_b128 v[178:181], v194 offset:32
	ds_read_b128 v[222:225], v195 offset:41504
	ds_read_b128 v[206:209], v194 offset:4640
	ds_read_b128 v[214:217], v195 offset:36896
	s_waitcnt lgkmcnt(6)
	v_mfma_f32_32x32x16_bf16 v[52:67], v[174:177], v[210:213], v[52:67]
	global_load_dwordx4 v[68:71], v[164:165], off offset:1920
	s_waitcnt lgkmcnt(5)
	v_mfma_f32_32x32x16_bf16 v[36:51], v[174:177], v[218:221], v[36:51]
	global_load_dwordx4 v[72:75], v[162:163], off offset:1920
	s_waitcnt lgkmcnt(4)
	v_mfma_f32_32x32x16_bf16 v[4:19], v[202:205], v[218:221], v[4:19]
	global_load_dwordx4 v[76:79], v[160:161], off offset:1920
	s_waitcnt lgkmcnt(2)
	v_mfma_f32_32x32x16_bf16 v[36:51], v[178:181], v[222:225], v[36:51]
	global_load_dwordx4 v[80:83], v[158:159], off offset:1920
	s_waitcnt lgkmcnt(1)
	v_mfma_f32_32x32x16_bf16 v[4:19], v[206:209], v[222:225], v[4:19]
	global_load_dwordx4 v[84:87], v[156:157], off offset:1920
	ds_read_b128 v[222:225], v195 offset:41568
	ds_read_b128 v[174:177], v194 offset:4672
	v_mfma_f32_32x32x16_bf16 v[20:35], v[202:205], v[210:213], v[20:35]
	global_load_dwordx4 v[92:95], v[154:155], off offset:1920
	ds_read_b128 v[210:213], v194 offset:4704
	ds_read_b128 v[202:205], v194 offset:64
	s_waitcnt lgkmcnt(4)
	v_mfma_f32_32x32x16_bf16 v[52:67], v[178:181], v[214:217], v[52:67]
	global_load_dwordx4 v[104:107], v[152:153], off offset:1920
	ds_read_b128 v[218:221], v195 offset:36960
	ds_read_b128 v[178:181], v195 offset:41536
	v_mfma_f32_32x32x16_bf16 v[20:35], v[206:209], v[214:217], v[20:35]
	global_load_dwordx4 v[112:115], v[146:147], off offset:1920
	ds_read_b128 v[214:217], v195 offset:36928
	ds_read_b128 v[206:209], v194 offset:96
	s_waitcnt lgkmcnt(1)
	v_mfma_f32_32x32x16_bf16 v[52:67], v[202:205], v[214:217], v[52:67]
	s_waitcnt vmcnt(23)
	ds_write_b128 v167, v[88:91] offset:18432
	v_mfma_f32_32x32x16_bf16 v[36:51], v[202:205], v[178:181], v[36:51]
	s_waitcnt vmcnt(22)
	ds_write_b128 v167, v[96:99] offset:55296
	v_mfma_f32_32x32x16_bf16 v[20:35], v[174:177], v[214:217], v[20:35]
	s_waitcnt vmcnt(21)
	ds_write_b128 v190, v[100:103] offset:18432
	v_mfma_f32_32x32x16_bf16 v[4:19], v[174:177], v[178:181], v[4:19]
	s_waitcnt vmcnt(20)
	ds_write_b128 v190, v[108:111] offset:55296
	s_waitcnt lgkmcnt(4)
	v_mfma_f32_32x32x16_bf16 v[52:67], v[206:209], v[218:221], v[52:67]
	s_waitcnt vmcnt(19)
	ds_write_b128 v191, v[116:119] offset:18432
	v_mfma_f32_32x32x16_bf16 v[36:51], v[206:209], v[222:225], v[36:51]
	s_waitcnt vmcnt(18)
	ds_write_b128 v191, v[120:123] offset:55296
	v_mfma_f32_32x32x16_bf16 v[20:35], v[210:213], v[218:221], v[20:35]
	s_waitcnt vmcnt(17)
	ds_write_b128 v192, v[124:127] offset:18432
	v_mfma_f32_32x32x16_bf16 v[4:19], v[210:213], v[222:225], v[4:19]
	s_waitcnt vmcnt(16)
	ds_write_b128 v192, v[128:131] offset:55296
	s_waitcnt lgkmcnt(0)
	s_barrier
; template <class Epi, class ColV>
; DI void gemm_tile(const bf16_t* __restrict__ A, int lda, const bf16_t* __restrict__ Bt, int ldb, int K, int m0, int n0, unsigned char* smem, Epi epi, ColV colv, const bf16_t* __restrict__ HYT = nullptr) {
;     ...
;         if (kt + 1 < nk) sstore(stset, buf ^ 1, kt + 1);
; #pragma unroll
;         for (int i = 0; i < 8; ++i) { __builtin_amdgcn_sched_group_barrier(0x008, 1, 0); __builtin_amdgcn_sched_group_barrier(0x100, 1, 0); }
; #pragma unroll
;         for (int i = 0; i < 8; ++i) { __builtin_amdgcn_sched_group_barrier(0x008, 1, 0); __builtin_amdgcn_sched_group_barrier(0x200, 1, 0); }
;         __builtin_amdgcn_sched_barrier(0);
;         __syncthreads();
;     };
;     gload(R0, 0); gload(R1, 1);
;     sstore(R0, 0, 0); __syncthreads();
;     for (int kt = 0; kt < nk; kt += 2) {
;         step(kt, R0, R1);
;         if (kt + 1 < nk) step(kt + 1, R1, R0);
;     }
	ds_read_b128 v[174:177], v196
	ds_read_b128 v[210:213], v197 offset:36864
	ds_read_b128 v[218:221], v197 offset:41472
	ds_read_b128 v[202:205], v196 offset:4608
	ds_read_b128 v[178:181], v196 offset:32
	ds_read_b128 v[222:225], v197 offset:41504
	ds_read_b128 v[206:209], v196 offset:4640
	ds_read_b128 v[214:217], v197 offset:36896
	s_waitcnt lgkmcnt(6)
	v_mfma_f32_32x32x16_bf16 v[52:67], v[174:177], v[210:213], v[52:67]
	s_waitcnt lgkmcnt(5)
	v_mfma_f32_32x32x16_bf16 v[36:51], v[174:177], v[218:221], v[36:51]
	s_waitcnt lgkmcnt(4)
	v_mfma_f32_32x32x16_bf16 v[4:19], v[202:205], v[218:221], v[4:19]
	s_waitcnt lgkmcnt(2)
	v_mfma_f32_32x32x16_bf16 v[36:51], v[178:181], v[222:225], v[36:51]
	s_waitcnt lgkmcnt(1)
	v_mfma_f32_32x32x16_bf16 v[4:19], v[206:209], v[222:225], v[4:19]
	ds_read_b128 v[222:225], v197 offset:41568
	ds_read_b128 v[174:177], v196 offset:4672
	v_mfma_f32_32x32x16_bf16 v[20:35], v[202:205], v[210:213], v[20:35]
	ds_read_b128 v[210:213], v196 offset:4704
	ds_read_b128 v[202:205], v196 offset:64
	s_waitcnt lgkmcnt(4)
	v_mfma_f32_32x32x16_bf16 v[52:67], v[178:181], v[214:217], v[52:67]
	ds_read_b128 v[218:221], v197 offset:36960
	ds_read_b128 v[178:181], v197 offset:41536
	v_mfma_f32_32x32x16_bf16 v[20:35], v[206:209], v[214:217], v[20:35]
	ds_read_b128 v[214:217], v197 offset:36928
	ds_read_b128 v[206:209], v196 offset:96
	s_waitcnt lgkmcnt(1)
	v_mfma_f32_32x32x16_bf16 v[52:67], v[202:205], v[214:217], v[52:67]
	s_waitcnt vmcnt(15)
	ds_write_b128 v167, v[132:135]
	v_mfma_f32_32x32x16_bf16 v[36:51], v[202:205], v[178:181], v[36:51]
	s_waitcnt vmcnt(14)
	ds_write_b128 v167, v[136:139] offset:36864
	v_mfma_f32_32x32x16_bf16 v[20:35], v[174:177], v[214:217], v[20:35]
	s_waitcnt vmcnt(13)
	ds_write_b128 v190, v[140:143]
	v_mfma_f32_32x32x16_bf16 v[4:19], v[174:177], v[178:181], v[4:19]
	s_waitcnt vmcnt(12)
	ds_write_b128 v190, v[198:201] offset:36864
	s_waitcnt lgkmcnt(4)
	v_mfma_f32_32x32x16_bf16 v[52:67], v[206:209], v[218:221], v[52:67]
	s_waitcnt vmcnt(11)
	ds_write_b128 v191, v[226:229]
	v_mfma_f32_32x32x16_bf16 v[36:51], v[206:209], v[222:225], v[36:51]
	s_waitcnt vmcnt(10)
	ds_write_b128 v191, v[230:233] offset:36864
	v_mfma_f32_32x32x16_bf16 v[20:35], v[210:213], v[218:221], v[20:35]
	s_waitcnt vmcnt(9)
	ds_write_b128 v192, v[242:245]
	v_mfma_f32_32x32x16_bf16 v[4:19], v[210:213], v[222:225], v[4:19]
	s_waitcnt vmcnt(8)
	ds_write_b128 v192, v[246:249] offset:36864
	s_waitcnt lgkmcnt(0)
	s_barrier
	ds_read_b128 v[174:177], v194
	ds_read_b128 v[210:213], v195 offset:36864
	ds_read_b128 v[218:221], v195 offset:41472
	ds_read_b128 v[202:205], v194 offset:4608
	ds_read_b128 v[178:181], v194 offset:32
	ds_read_b128 v[222:225], v195 offset:41504
	ds_read_b128 v[206:209], v194 offset:4640
	ds_read_b128 v[214:217], v195 offset:36896
	s_waitcnt lgkmcnt(6)
	v_mfma_f32_32x32x16_bf16 v[52:67], v[174:177], v[210:213], v[52:67]
	s_waitcnt lgkmcnt(5)
	v_mfma_f32_32x32x16_bf16 v[36:51], v[174:177], v[218:221], v[36:51]
	s_waitcnt lgkmcnt(4)
	v_mfma_f32_32x32x16_bf16 v[4:19], v[202:205], v[218:221], v[4:19]
	s_waitcnt lgkmcnt(2)
	v_mfma_f32_32x32x16_bf16 v[36:51], v[178:181], v[222:225], v[36:51]
	s_waitcnt lgkmcnt(1)
	v_mfma_f32_32x32x16_bf16 v[4:19], v[206:209], v[222:225], v[4:19]
	ds_read_b128 v[222:225], v195 offset:41568
	ds_read_b128 v[174:177], v194 offset:4672
	v_mfma_f32_32x32x16_bf16 v[20:35], v[202:205], v[210:213], v[20:35]
	ds_read_b128 v[210:213], v194 offset:4704
	ds_read_b128 v[202:205], v194 offset:64
	s_waitcnt lgkmcnt(4)
	v_mfma_f32_32x32x16_bf16 v[52:67], v[178:181], v[214:217], v[52:67]
	ds_read_b128 v[218:221], v195 offset:36960
	ds_read_b128 v[178:181], v195 offset:41536
	v_mfma_f32_32x32x16_bf16 v[20:35], v[206:209], v[214:217], v[20:35]
	ds_read_b128 v[214:217], v195 offset:36928
	ds_read_b128 v[206:209], v194 offset:96
	s_waitcnt lgkmcnt(1)
	v_mfma_f32_32x32x16_bf16 v[52:67], v[202:205], v[214:217], v[52:67]
	s_waitcnt vmcnt(7)
	ds_write_b128 v167, v[68:71] offset:18432
	v_mfma_f32_32x32x16_bf16 v[36:51], v[202:205], v[178:181], v[36:51]
	s_waitcnt vmcnt(6)
	ds_write_b128 v167, v[72:75] offset:55296
	v_mfma_f32_32x32x16_bf16 v[20:35], v[174:177], v[214:217], v[20:35]
	s_waitcnt vmcnt(5)
	ds_write_b128 v190, v[76:79] offset:18432
	v_mfma_f32_32x32x16_bf16 v[4:19], v[174:177], v[178:181], v[4:19]
	s_waitcnt vmcnt(4)
	ds_write_b128 v190, v[80:83] offset:55296
	s_waitcnt lgkmcnt(4)
	v_mfma_f32_32x32x16_bf16 v[52:67], v[206:209], v[218:221], v[52:67]
	s_waitcnt vmcnt(3)
	ds_write_b128 v191, v[84:87] offset:18432
	v_mfma_f32_32x32x16_bf16 v[36:51], v[206:209], v[222:225], v[36:51]
	s_waitcnt vmcnt(2)
	ds_write_b128 v191, v[92:95] offset:55296
	v_mfma_f32_32x32x16_bf16 v[20:35], v[210:213], v[218:221], v[20:35]
	s_waitcnt vmcnt(1)
	ds_write_b128 v192, v[104:107] offset:18432
	v_mfma_f32_32x32x16_bf16 v[4:19], v[210:213], v[222:225], v[4:19]
	s_waitcnt vmcnt(0)
	ds_write_b128 v192, v[112:115] offset:55296
	s_waitcnt lgkmcnt(0)
	s_barrier
	ds_read_b128 v[174:177], v196
	ds_read_b128 v[210:213], v197 offset:36864
	ds_read_b128 v[218:221], v197 offset:41472
	ds_read_b128 v[202:205], v196 offset:4608
	ds_read_b128 v[178:181], v196 offset:32
	ds_read_b128 v[222:225], v197 offset:41504
	ds_read_b128 v[206:209], v196 offset:4640
	ds_read_b128 v[214:217], v197 offset:36896
	s_waitcnt lgkmcnt(6)
	v_mfma_f32_32x32x16_bf16 v[52:67], v[174:177], v[210:213], v[52:67]
	s_waitcnt lgkmcnt(5)
	v_mfma_f32_32x32x16_bf16 v[36:51], v[174:177], v[218:221], v[36:51]
	s_waitcnt lgkmcnt(4)
	v_mfma_f32_32x32x16_bf16 v[4:19], v[202:205], v[218:221], v[4:19]
	s_waitcnt lgkmcnt(2)
	v_mfma_f32_32x32x16_bf16 v[36:51], v[178:181], v[222:225], v[36:51]
	s_waitcnt lgkmcnt(1)
	v_mfma_f32_32x32x16_bf16 v[4:19], v[206:209], v[222:225], v[4:19]
	ds_read_b128 v[222:225], v197 offset:41568
	ds_read_b128 v[174:177], v196 offset:4672
	v_mfma_f32_32x32x16_bf16 v[20:35], v[202:205], v[210:213], v[20:35]
	ds_read_b128 v[210:213], v196 offset:4704
	ds_read_b128 v[202:205], v196 offset:64
	s_waitcnt lgkmcnt(4)
	v_mfma_f32_32x32x16_bf16 v[52:67], v[178:181], v[214:217], v[52:67]
	ds_read_b128 v[218:221], v197 offset:36960
	ds_read_b128 v[178:181], v197 offset:41536
	v_mfma_f32_32x32x16_bf16 v[20:35], v[206:209], v[214:217], v[20:35]
	ds_read_b128 v[214:217], v197 offset:36928
	ds_read_b128 v[206:209], v196 offset:96
	s_waitcnt lgkmcnt(1)
	v_mfma_f32_32x32x16_bf16 v[52:67], v[202:205], v[214:217], v[52:67]
	v_mfma_f32_32x32x16_bf16 v[36:51], v[202:205], v[178:181], v[36:51]
	v_mfma_f32_32x32x16_bf16 v[20:35], v[174:177], v[214:217], v[20:35]
	v_mfma_f32_32x32x16_bf16 v[4:19], v[174:177], v[178:181], v[4:19]
	s_waitcnt lgkmcnt(0)
	v_mfma_f32_32x32x16_bf16 v[52:67], v[206:209], v[218:221], v[52:67]
	v_mfma_f32_32x32x16_bf16 v[36:51], v[206:209], v[222:225], v[36:51]
	v_mfma_f32_32x32x16_bf16 v[20:35], v[210:213], v[218:221], v[20:35]
	v_mfma_f32_32x32x16_bf16 v[4:19], v[210:213], v[222:225], v[4:19]
	s_waitcnt lgkmcnt(0)
	s_barrier
	s_nop 7
	s_nop 3
	s_branch .LBB0_53

; #define MFMA(a, b, c) __builtin_amdgcn_mfma_f32_32x32x16_bf16((a), (b), (c), 0, 0, 0)
; template <class Epi, class ColV>
; DI void gemm_tile(const bf16_t* __restrict__ A, int lda, const bf16_t* __restrict__ Bt, int ldb, int K, int m0, int n0, unsigned char* smem, Epi epi, ColV colv, const bf16_t* __restrict__ HYT = nullptr) {
;     ...
;     auto gload = [&](u32x4 (&r)[8], int kt) {
; #pragma unroll
;         for (int i = 0; i < 4; ++i) { int id = tid + 256 * i, row = id >> 3, kc = id & 7;
;             if (HYT && kt >= 12) r[i] = *(const u32x4*)(HYT + (size_t)((kt - 12) * 64 + (id >> 4)) * NT + m0 + (id & 15) * 8);
;             else r[i] = *(const u32x4*)(A + (size_t)(m0 + row) * lda + kt * 64 + kc * 8);
;             r[4 + i] = *(const u32x4*)(Bt + (size_t)(n0 + row) * ldb + kt * 64 + kc * 8); }
;     };
;     auto sstore = [&](const u32x4 (&r)[8], int buf, int kt) {
; #pragma unroll
;         for (int i = 0; i < 4; ++i) { int id = tid + 256 * i, row = id >> 3, kc = id & 7;
;             if (HYT && kt >= 12) { const int kk = id >> 4, rr = (id & 15) * 8; bf16_t* d = As + (buf * 128 + rr) * LS + kk; const bf16x8 v = __builtin_bit_cast(bf16x8, r[i]);
; #pragma unroll
;                 for (int e = 0; e < 8; ++e) d[e * LS] = (bf16_t)v[e]; }
;             else *(u32x4*)(As + (buf * 128 + row) * LS + kc * 8) = r[i];
;             *(u32x4*)(Bs + (buf * 128 + row) * LS + kc * 8) = r[4 + i]; }
;     };
;     auto step = [&](int kt, u32x4 (&ldset)[8], const u32x4 (&stset)[8]) {
;         const int buf = kt & 1;
;         if (kt + 2 < nk) gload(ldset, kt + 2);
;         const bf16_t* Ab = As + (buf * 128 + 64 * wr + li) * LS + 8 * lh;
;         const bf16_t* Bb = Bs + (buf * 128 + 64 * wc + li) * LS + 8 * lh;
;         bf16x8 fa[2][2], fb[2][2], ga[2][2], gb[2][2];
; #pragma unroll
;         for (int k2 = 0; k2 < 2; ++k2) { fa[k2][0] = ld8(Ab + 16 * k2); fa[k2][1] = ld8(Ab + 32 * LS + 16 * k2); fb[k2][0] = ld8(Bb + 16 * k2); fb[k2][1] = ld8(Bb + 32 * LS + 16 * k2); }
;         __builtin_amdgcn_sched_barrier(0);
; #pragma unroll
;         for (int k2 = 0; k2 < 2; ++k2) {
;             acc[0][0] = MFMA(fa[k2][0], fb[k2][0], acc[0][0]); acc[0][1] = MFMA(fa[k2][0], fb[k2][1], acc[0][1]);
;             acc[1][0] = MFMA(fa[k2][1], fb[k2][0], acc[1][0]); acc[1][1] = MFMA(fa[k2][1], fb[k2][1], acc[1][1]);
;         }
; #pragma unroll
.LBB0_1558:
	s_cmp_lt_u32 s19, 14
	s_cselect_b64 s[12:13], -1, 0
	s_cmp_gt_u32 s19, 13
	s_cselect_b64 s[10:11], -1, 0
	s_and_b64 vcc, exec, s[10:11]
	v_lshl_add_u64 v[164:165], v[144:145], 0, v[2:3]
	v_lshl_add_u64 v[162:163], v[0:1], 0, v[2:3]
	v_lshl_add_u64 v[160:161], v[142:143], 0, v[2:3]
	v_lshl_add_u64 v[158:159], v[132:133], 0, v[2:3]
	v_lshl_add_u64 v[156:157], v[140:141], 0, v[2:3]
	v_lshl_add_u64 v[154:155], v[134:135], 0, v[2:3]
	v_lshl_add_u64 v[152:153], v[138:139], 0, v[2:3]
	v_lshl_add_u64 v[146:147], v[136:137], 0, v[2:3]
	s_mov_b32 s100, 0x26ca000
	s_mov_b32 s101, 0
	v_lshl_add_u64 v[164:165], v[164:165], 0, s[100:101]
	v_lshl_add_u64 v[160:161], v[160:161], 0, s[100:101]
	v_lshl_add_u64 v[156:157], v[156:157], 0, s[100:101]
	v_lshl_add_u64 v[152:153], v[152:153], 0, s[100:101]
	ds_read_b128 v[202:205], v194
	ds_read_b128 v[218:221], v195 offset:36864
	ds_read_b128 v[226:229], v195 offset:41472
	ds_read_b128 v[210:213], v194 offset:4608
	ds_read_b128 v[206:209], v194 offset:32
	ds_read_b128 v[230:233], v195 offset:41504
	ds_read_b128 v[214:217], v194 offset:4640
	ds_read_b128 v[222:225], v195 offset:36896
	s_waitcnt lgkmcnt(6)
	v_mfma_f32_32x32x16_bf16 v[52:67], v[202:205], v[218:221], v[52:67]
	global_load_dwordx4 v[132:135], v[164:165], off offset:256
	global_load_dwordx4 v[136:139], v[162:163], off offset:256
	s_waitcnt lgkmcnt(5)
	v_mfma_f32_32x32x16_bf16 v[36:51], v[202:205], v[226:229], v[36:51]
	global_load_dwordx4 v[140:143], v[160:161], off offset:256
	global_load_dwordx4 v[198:201], v[158:159], off offset:256
	s_waitcnt lgkmcnt(4)
	v_mfma_f32_32x32x16_bf16 v[4:19], v[210:213], v[226:229], v[4:19]
	global_load_dwordx4 v[174:177], v[156:157], off offset:256
	global_load_dwordx4 v[178:181], v[154:155], off offset:256
	s_waitcnt lgkmcnt(2)
	v_mfma_f32_32x32x16_bf16 v[36:51], v[206:209], v[230:233], v[36:51]
	global_load_dwordx4 v[242:245], v[152:153], off offset:256
	global_load_dwordx4 v[246:249], v[146:147], off offset:256
	s_waitcnt lgkmcnt(1)
	v_mfma_f32_32x32x16_bf16 v[4:19], v[214:217], v[230:233], v[4:19]
	global_load_dwordx4 v[68:71], v[164:165], off offset:384
	global_load_dwordx4 v[72:75], v[162:163], off offset:384
	ds_read_b128 v[230:233], v195 offset:41568
	ds_read_b128 v[202:205], v194 offset:4672
	v_mfma_f32_32x32x16_bf16 v[20:35], v[210:213], v[218:221], v[20:35]
	global_load_dwordx4 v[76:79], v[160:161], off offset:384
	global_load_dwordx4 v[80:83], v[158:159], off offset:384
	ds_read_b128 v[218:221], v194 offset:4704
	ds_read_b128 v[210:213], v194 offset:64
	s_waitcnt lgkmcnt(4)
	v_mfma_f32_32x32x16_bf16 v[52:67], v[206:209], v[222:225], v[52:67]
	global_load_dwordx4 v[84:87], v[156:157], off offset:384
	global_load_dwordx4 v[88:91], v[154:155], off offset:384
	ds_read_b128 v[226:229], v195 offset:36960
	ds_read_b128 v[206:209], v195 offset:41536
	v_mfma_f32_32x32x16_bf16 v[20:35], v[214:217], v[222:225], v[20:35]
	global_load_dwordx4 v[92:95], v[152:153], off offset:384
	global_load_dwordx4 v[104:107], v[146:147], off offset:384
	ds_read_b128 v[222:225], v195 offset:36928
	ds_read_b128 v[214:217], v194 offset:96
	s_waitcnt lgkmcnt(1)
	v_mfma_f32_32x32x16_bf16 v[52:67], v[210:213], v[222:225], v[52:67]
	s_waitcnt vmcnt(16)
	ds_write_b128 v167, v[96:99] offset:18432
	v_mfma_f32_32x32x16_bf16 v[36:51], v[210:213], v[206:209], v[36:51]
	ds_write_b128 v167, v[100:103] offset:55296
	v_mfma_f32_32x32x16_bf16 v[20:35], v[202:205], v[222:225], v[20:35]
	ds_write_b128 v190, v[108:111] offset:18432
	v_mfma_f32_32x32x16_bf16 v[4:19], v[202:205], v[206:209], v[4:19]
	ds_write_b128 v190, v[112:115] offset:55296
	s_waitcnt lgkmcnt(4)
	v_mfma_f32_32x32x16_bf16 v[52:67], v[214:217], v[226:229], v[52:67]
	ds_write_b128 v191, v[116:119] offset:18432
	v_mfma_f32_32x32x16_bf16 v[36:51], v[214:217], v[230:233], v[36:51]
	ds_write_b128 v191, v[120:123] offset:55296
	v_mfma_f32_32x32x16_bf16 v[20:35], v[218:221], v[226:229], v[20:35]
	ds_write_b128 v192, v[124:127] offset:18432
	v_mfma_f32_32x32x16_bf16 v[4:19], v[218:221], v[230:233], v[4:19]
	ds_write_b128 v192, v[128:131] offset:55296
	s_waitcnt lgkmcnt(0)
	s_barrier
	ds_read_b128 v[202:205], v196
	ds_read_b128 v[218:221], v197 offset:36864
	ds_read_b128 v[226:229], v197 offset:41472
	ds_read_b128 v[210:213], v196 offset:4608
	ds_read_b128 v[206:209], v196 offset:32
	ds_read_b128 v[230:233], v197 offset:41504
	ds_read_b128 v[214:217], v196 offset:4640
	ds_read_b128 v[222:225], v197 offset:36896
	s_waitcnt lgkmcnt(6)
	v_mfma_f32_32x32x16_bf16 v[52:67], v[202:205], v[218:221], v[52:67]
	global_load_dwordx4 v[96:99], v[164:165], off offset:512
	s_waitcnt lgkmcnt(5)
	v_mfma_f32_32x32x16_bf16 v[36:51], v[202:205], v[226:229], v[36:51]
	global_load_dwordx4 v[100:103], v[162:163], off offset:512
	s_waitcnt lgkmcnt(4)
	v_mfma_f32_32x32x16_bf16 v[4:19], v[210:213], v[226:229], v[4:19]
	global_load_dwordx4 v[108:111], v[160:161], off offset:512
	s_waitcnt lgkmcnt(2)
	v_mfma_f32_32x32x16_bf16 v[36:51], v[206:209], v[230:233], v[36:51]
	global_load_dwordx4 v[112:115], v[158:159], off offset:512
	s_waitcnt lgkmcnt(1)
	v_mfma_f32_32x32x16_bf16 v[4:19], v[214:217], v[230:233], v[4:19]
	global_load_dwordx4 v[116:119], v[156:157], off offset:512
	ds_read_b128 v[230:233], v197 offset:41568
	ds_read_b128 v[202:205], v196 offset:4672
	v_mfma_f32_32x32x16_bf16 v[20:35], v[210:213], v[218:221], v[20:35]
	global_load_dwordx4 v[120:123], v[154:155], off offset:512
	ds_read_b128 v[218:221], v196 offset:4704
	ds_read_b128 v[210:213], v196 offset:64
	s_waitcnt lgkmcnt(4)
; #define MFMA(a, b, c) __builtin_amdgcn_mfma_f32_32x32x16_bf16((a), (b), (c), 0, 0, 0)
; template <class Epi, class ColV>
; DI void gemm_tile(const bf16_t* __restrict__ A, int lda, const bf16_t* __restrict__ Bt, int ldb, int K, int m0, int n0, unsigned char* smem, Epi epi, ColV colv, const bf16_t* __restrict__ HYT = nullptr) {
;     ...
;     auto step = [&](int kt, u32x4 (&ldset)[8], const u32x4 (&stset)[8]) {
;         const int buf = kt & 1;
;         if (kt + 2 < nk) gload(ldset, kt + 2);
;         const bf16_t* Ab = As + (buf * 128 + 64 * wr + li) * LS + 8 * lh;
;         const bf16_t* Bb = Bs + (buf * 128 + 64 * wc + li) * LS + 8 * lh;
;         bf16x8 fa[2][2], fb[2][2], ga[2][2], gb[2][2];
; #pragma unroll
;         for (int k2 = 0; k2 < 2; ++k2) { fa[k2][0] = ld8(Ab + 16 * k2); fa[k2][1] = ld8(Ab + 32 * LS + 16 * k2); fb[k2][0] = ld8(Bb + 16 * k2); fb[k2][1] = ld8(Bb + 32 * LS + 16 * k2); }
;         __builtin_amdgcn_sched_barrier(0);
; #pragma unroll
;         for (int k2 = 0; k2 < 2; ++k2) {
;             acc[0][0] = MFMA(fa[k2][0], fb[k2][0], acc[0][0]); acc[0][1] = MFMA(fa[k2][0], fb[k2][1], acc[0][1]);
;             acc[1][0] = MFMA(fa[k2][1], fb[k2][0], acc[1][0]); acc[1][1] = MFMA(fa[k2][1], fb[k2][1], acc[1][1]);
;         }
; #pragma unroll
;         for (int k2 = 0; k2 < 2; ++k2) { const int ks = 2 + k2; ga[k2][0] = ld8(Ab + 16 * ks); ga[k2][1] = ld8(Ab + 32 * LS + 16 * ks); gb[k2][0] = ld8(Bb + 16 * ks); gb[k2][1] = ld8(Bb + 32 * LS + 16 * ks); }
; #pragma unroll
;         for (int k2 = 0; k2 < 2; ++k2) {
;             acc[0][0] = MFMA(ga[k2][0], gb[k2][0], acc[0][0]); acc[0][1] = MFMA(ga[k2][0], gb[k2][1], acc[0][1]);
;             acc[1][0] = MFMA(ga[k2][1], gb[k2][0], acc[1][0]); acc[1][1] = MFMA(ga[k2][1], gb[k2][1], acc[1][1]);
;         }
;         if (kt + 1 < nk) sstore(stset, buf ^ 1, kt + 1);
; #pragma unroll
;         for (int i = 0; i < 8; ++i) { __builtin_amdgcn_sched_group_barrier(0x008, 1, 0); __builtin_amdgcn_sched_group_barrier(0x100, 1, 0); }
; #pragma unroll
;         for (int i = 0; i < 8; ++i) { __builtin_amdgcn_sched_group_barrier(0x008, 1, 0); __builtin_amdgcn_sched_group_barrier(0x200, 1, 0); }
;         __builtin_amdgcn_sched_barrier(0);
;         __syncthreads();
;     };
	v_mfma_f32_32x32x16_bf16 v[52:67], v[206:209], v[222:225], v[52:67]
	global_load_dwordx4 v[124:127], v[152:153], off offset:512
	ds_read_b128 v[226:229], v197 offset:36960
	ds_read_b128 v[206:209], v197 offset:41536
	v_mfma_f32_32x32x16_bf16 v[20:35], v[214:217], v[222:225], v[20:35]
	global_load_dwordx4 v[128:131], v[146:147], off offset:512
	ds_read_b128 v[222:225], v197 offset:36928
	ds_read_b128 v[214:217], v196 offset:96
	s_waitcnt lgkmcnt(1)
	v_mfma_f32_32x32x16_bf16 v[52:67], v[210:213], v[222:225], v[52:67]
	s_waitcnt vmcnt(23)
	ds_write_b128 v167, v[132:135]
	v_mfma_f32_32x32x16_bf16 v[36:51], v[210:213], v[206:209], v[36:51]
	s_waitcnt vmcnt(22)
	ds_write_b128 v167, v[136:139] offset:36864
	v_mfma_f32_32x32x16_bf16 v[20:35], v[202:205], v[222:225], v[20:35]
	s_waitcnt vmcnt(21)
	ds_write_b128 v190, v[140:143]
	v_mfma_f32_32x32x16_bf16 v[4:19], v[202:205], v[206:209], v[4:19]
	s_waitcnt vmcnt(20)
	ds_write_b128 v190, v[198:201] offset:36864
	s_waitcnt lgkmcnt(4)
	v_mfma_f32_32x32x16_bf16 v[52:67], v[214:217], v[226:229], v[52:67]
	s_waitcnt vmcnt(19)
	ds_write_b128 v191, v[174:177]
	v_mfma_f32_32x32x16_bf16 v[36:51], v[214:217], v[230:233], v[36:51]
	s_waitcnt vmcnt(18)
	ds_write_b128 v191, v[178:181] offset:36864
	v_mfma_f32_32x32x16_bf16 v[20:35], v[218:221], v[226:229], v[20:35]
	s_waitcnt vmcnt(17)
	ds_write_b128 v192, v[242:245]
	v_mfma_f32_32x32x16_bf16 v[4:19], v[218:221], v[230:233], v[4:19]
	s_waitcnt vmcnt(16)
	ds_write_b128 v192, v[246:249] offset:36864
	s_waitcnt lgkmcnt(0)
	s_barrier
	ds_read_b128 v[202:205], v194
	ds_read_b128 v[218:221], v195 offset:36864
	ds_read_b128 v[226:229], v195 offset:41472
	ds_read_b128 v[210:213], v194 offset:4608
	ds_read_b128 v[206:209], v194 offset:32
	ds_read_b128 v[230:233], v195 offset:41504
	ds_read_b128 v[214:217], v194 offset:4640
	ds_read_b128 v[222:225], v195 offset:36896
	s_waitcnt lgkmcnt(6)
	v_mfma_f32_32x32x16_bf16 v[52:67], v[202:205], v[218:221], v[52:67]
	global_load_dwordx4 v[132:135], v[164:165], off offset:640
	s_waitcnt lgkmcnt(5)
	v_mfma_f32_32x32x16_bf16 v[36:51], v[202:205], v[226:229], v[36:51]
	global_load_dwordx4 v[136:139], v[162:163], off offset:640
	s_waitcnt lgkmcnt(4)
	v_mfma_f32_32x32x16_bf16 v[4:19], v[210:213], v[226:229], v[4:19]
	global_load_dwordx4 v[140:143], v[160:161], off offset:640
	s_waitcnt lgkmcnt(2)
	v_mfma_f32_32x32x16_bf16 v[36:51], v[206:209], v[230:233], v[36:51]
	global_load_dwordx4 v[198:201], v[158:159], off offset:640
	s_waitcnt lgkmcnt(1)
	v_mfma_f32_32x32x16_bf16 v[4:19], v[214:217], v[230:233], v[4:19]
	global_load_dwordx4 v[174:177], v[156:157], off offset:640
	ds_read_b128 v[230:233], v195 offset:41568
	ds_read_b128 v[202:205], v194 offset:4672
	v_mfma_f32_32x32x16_bf16 v[20:35], v[210:213], v[218:221], v[20:35]
	global_load_dwordx4 v[178:181], v[154:155], off offset:640
	ds_read_b128 v[218:221], v194 offset:4704
	ds_read_b128 v[210:213], v194 offset:64
	s_waitcnt lgkmcnt(4)
	v_mfma_f32_32x32x16_bf16 v[52:67], v[206:209], v[222:225], v[52:67]
	global_load_dwordx4 v[242:245], v[152:153], off offset:640
	ds_read_b128 v[226:229], v195 offset:36960
	ds_read_b128 v[206:209], v195 offset:41536
	v_mfma_f32_32x32x16_bf16 v[20:35], v[214:217], v[222:225], v[20:35]
	global_load_dwordx4 v[246:249], v[146:147], off offset:640
	ds_read_b128 v[222:225], v195 offset:36928
	ds_read_b128 v[214:217], v194 offset:96
	s_waitcnt lgkmcnt(1)
	v_mfma_f32_32x32x16_bf16 v[52:67], v[210:213], v[222:225], v[52:67]
	s_waitcnt vmcnt(23)
	ds_write_b128 v167, v[68:71] offset:18432
	v_mfma_f32_32x32x16_bf16 v[36:51], v[210:213], v[206:209], v[36:51]
	s_waitcnt vmcnt(22)
	ds_write_b128 v167, v[72:75] offset:55296
	v_mfma_f32_32x32x16_bf16 v[20:35], v[202:205], v[222:225], v[20:35]
	s_waitcnt vmcnt(21)
	ds_write_b128 v190, v[76:79] offset:18432
	v_mfma_f32_32x32x16_bf16 v[4:19], v[202:205], v[206:209], v[4:19]
	s_waitcnt vmcnt(20)
	ds_write_b128 v190, v[80:83] offset:55296
	s_waitcnt lgkmcnt(4)
	v_mfma_f32_32x32x16_bf16 v[52:67], v[214:217], v[226:229], v[52:67]
	s_waitcnt vmcnt(19)
	ds_write_b128 v191, v[84:87] offset:18432
	v_mfma_f32_32x32x16_bf16 v[36:51], v[214:217], v[230:233], v[36:51]
	s_waitcnt vmcnt(18)
	ds_write_b128 v191, v[88:91] offset:55296
	v_mfma_f32_32x32x16_bf16 v[20:35], v[218:221], v[226:229], v[20:35]
	s_waitcnt vmcnt(17)
	ds_write_b128 v192, v[92:95] offset:18432
	v_mfma_f32_32x32x16_bf16 v[4:19], v[218:221], v[230:233], v[4:19]
	s_waitcnt vmcnt(16)
	ds_write_b128 v192, v[104:107] offset:55296
	s_waitcnt lgkmcnt(0)
	s_barrier
; #define MFMA(a, b, c) __builtin_amdgcn_mfma_f32_32x32x16_bf16((a), (b), (c), 0, 0, 0)
; template <class Epi, class ColV>
; DI void gemm_tile(const bf16_t* __restrict__ A, int lda, const bf16_t* __restrict__ Bt, int ldb, int K, int m0, int n0, unsigned char* smem, Epi epi, ColV colv, const bf16_t* __restrict__ HYT = nullptr) {
;     ...
;     auto step = [&](int kt, u32x4 (&ldset)[8], const u32x4 (&stset)[8]) {
;         const int buf = kt & 1;
;         if (kt + 2 < nk) gload(ldset, kt + 2);
;         const bf16_t* Ab = As + (buf * 128 + 64 * wr + li) * LS + 8 * lh;
;         const bf16_t* Bb = Bs + (buf * 128 + 64 * wc + li) * LS + 8 * lh;
;         bf16x8 fa[2][2], fb[2][2], ga[2][2], gb[2][2];
; #pragma unroll
;         for (int k2 = 0; k2 < 2; ++k2) { fa[k2][0] = ld8(Ab + 16 * k2); fa[k2][1] = ld8(Ab + 32 * LS + 16 * k2); fb[k2][0] = ld8(Bb + 16 * k2); fb[k2][1] = ld8(Bb + 32 * LS + 16 * k2); }
;         __builtin_amdgcn_sched_barrier(0);
; #pragma unroll
;         for (int k2 = 0; k2 < 2; ++k2) {
;             acc[0][0] = MFMA(fa[k2][0], fb[k2][0], acc[0][0]); acc[0][1] = MFMA(fa[k2][0], fb[k2][1], acc[0][1]);
;             acc[1][0] = MFMA(fa[k2][1], fb[k2][0], acc[1][0]); acc[1][1] = MFMA(fa[k2][1], fb[k2][1], acc[1][1]);
;         }
; #pragma unroll
;         for (int k2 = 0; k2 < 2; ++k2) { const int ks = 2 + k2; ga[k2][0] = ld8(Ab + 16 * ks); ga[k2][1] = ld8(Ab + 32 * LS + 16 * ks); gb[k2][0] = ld8(Bb + 16 * ks); gb[k2][1] = ld8(Bb + 32 * LS + 16 * ks); }
; #pragma unroll
;         for (int k2 = 0; k2 < 2; ++k2) {
;             acc[0][0] = MFMA(ga[k2][0], gb[k2][0], acc[0][0]); acc[0][1] = MFMA(ga[k2][0], gb[k2][1], acc[0][1]);
;             acc[1][0] = MFMA(ga[k2][1], gb[k2][0], acc[1][0]); acc[1][1] = MFMA(ga[k2][1], gb[k2][1], acc[1][1]);
;         }
;         if (kt + 1 < nk) sstore(stset, buf ^ 1, kt + 1);
; #pragma unroll
;         for (int i = 0; i < 8; ++i) { __builtin_amdgcn_sched_group_barrier(0x008, 1, 0); __builtin_amdgcn_sched_group_barrier(0x100, 1, 0); }
; #pragma unroll
;         for (int i = 0; i < 8; ++i) { __builtin_amdgcn_sched_group_barrier(0x008, 1, 0); __builtin_amdgcn_sched_group_barrier(0x200, 1, 0); }
;         __builtin_amdgcn_sched_barrier(0);
;         __syncthreads();
;     };
	ds_read_b128 v[202:205], v196
	ds_read_b128 v[218:221], v197 offset:36864
	ds_read_b128 v[226:229], v197 offset:41472
	ds_read_b128 v[210:213], v196 offset:4608
	ds_read_b128 v[206:209], v196 offset:32
	ds_read_b128 v[230:233], v197 offset:41504
	ds_read_b128 v[214:217], v196 offset:4640
	ds_read_b128 v[222:225], v197 offset:36896
	s_waitcnt lgkmcnt(6)
	v_mfma_f32_32x32x16_bf16 v[52:67], v[202:205], v[218:221], v[52:67]
	global_load_dwordx4 v[68:71], v[164:165], off offset:768
	s_waitcnt lgkmcnt(5)
	v_mfma_f32_32x32x16_bf16 v[36:51], v[202:205], v[226:229], v[36:51]
	global_load_dwordx4 v[72:75], v[162:163], off offset:768
	s_waitcnt lgkmcnt(4)
	v_mfma_f32_32x32x16_bf16 v[4:19], v[210:213], v[226:229], v[4:19]
	global_load_dwordx4 v[76:79], v[160:161], off offset:768
	s_waitcnt lgkmcnt(2)
	v_mfma_f32_32x32x16_bf16 v[36:51], v[206:209], v[230:233], v[36:51]
	global_load_dwordx4 v[80:83], v[158:159], off offset:768
	s_waitcnt lgkmcnt(1)
	v_mfma_f32_32x32x16_bf16 v[4:19], v[214:217], v[230:233], v[4:19]
	global_load_dwordx4 v[84:87], v[156:157], off offset:768
	ds_read_b128 v[230:233], v197 offset:41568
	ds_read_b128 v[202:205], v196 offset:4672
	v_mfma_f32_32x32x16_bf16 v[20:35], v[210:213], v[218:221], v[20:35]
	global_load_dwordx4 v[88:91], v[154:155], off offset:768
	ds_read_b128 v[218:221], v196 offset:4704
	ds_read_b128 v[210:213], v196 offset:64
	s_waitcnt lgkmcnt(4)
	v_mfma_f32_32x32x16_bf16 v[52:67], v[206:209], v[222:225], v[52:67]
	global_load_dwordx4 v[92:95], v[152:153], off offset:768
	ds_read_b128 v[226:229], v197 offset:36960
	ds_read_b128 v[206:209], v197 offset:41536
	v_mfma_f32_32x32x16_bf16 v[20:35], v[214:217], v[222:225], v[20:35]
	global_load_dwordx4 v[104:107], v[146:147], off offset:768
	ds_read_b128 v[222:225], v197 offset:36928
	ds_read_b128 v[214:217], v196 offset:96
	s_waitcnt lgkmcnt(1)
	v_mfma_f32_32x32x16_bf16 v[52:67], v[210:213], v[222:225], v[52:67]
	s_waitcnt vmcnt(23)
	ds_write_b128 v167, v[96:99]
	v_mfma_f32_32x32x16_bf16 v[36:51], v[210:213], v[206:209], v[36:51]
	s_waitcnt vmcnt(22)
	ds_write_b128 v167, v[100:103] offset:36864
	v_mfma_f32_32x32x16_bf16 v[20:35], v[202:205], v[222:225], v[20:35]
	s_waitcnt vmcnt(21)
	ds_write_b128 v190, v[108:111]
	v_mfma_f32_32x32x16_bf16 v[4:19], v[202:205], v[206:209], v[4:19]
	s_waitcnt vmcnt(20)
	ds_write_b128 v190, v[112:115] offset:36864
	s_waitcnt lgkmcnt(4)
	v_mfma_f32_32x32x16_bf16 v[52:67], v[214:217], v[226:229], v[52:67]
	s_waitcnt vmcnt(19)
	ds_write_b128 v191, v[116:119]
	v_mfma_f32_32x32x16_bf16 v[36:51], v[214:217], v[230:233], v[36:51]
	s_waitcnt vmcnt(18)
	ds_write_b128 v191, v[120:123] offset:36864
	v_mfma_f32_32x32x16_bf16 v[20:35], v[218:221], v[226:229], v[20:35]
	s_waitcnt vmcnt(17)
	ds_write_b128 v192, v[124:127]
	v_mfma_f32_32x32x16_bf16 v[4:19], v[218:221], v[230:233], v[4:19]
	s_waitcnt vmcnt(16)
	ds_write_b128 v192, v[128:131] offset:36864
	s_waitcnt lgkmcnt(0)
	s_barrier
	ds_read_b128 v[202:205], v194
	ds_read_b128 v[218:221], v195 offset:36864
	ds_read_b128 v[226:229], v195 offset:41472
	ds_read_b128 v[210:213], v194 offset:4608
	ds_read_b128 v[206:209], v194 offset:32
	ds_read_b128 v[230:233], v195 offset:41504
	ds_read_b128 v[214:217], v194 offset:4640
	ds_read_b128 v[222:225], v195 offset:36896
	s_waitcnt lgkmcnt(6)
	v_mfma_f32_32x32x16_bf16 v[52:67], v[202:205], v[218:221], v[52:67]
	global_load_dwordx4 v[96:99], v[164:165], off offset:896
	s_waitcnt lgkmcnt(5)
	v_mfma_f32_32x32x16_bf16 v[36:51], v[202:205], v[226:229], v[36:51]
	global_load_dwordx4 v[100:103], v[162:163], off offset:896
	s_waitcnt lgkmcnt(4)
	v_mfma_f32_32x32x16_bf16 v[4:19], v[210:213], v[226:229], v[4:19]
	global_load_dwordx4 v[108:111], v[160:161], off offset:896
	s_waitcnt lgkmcnt(2)
	v_mfma_f32_32x32x16_bf16 v[36:51], v[206:209], v[230:233], v[36:51]
	global_load_dwordx4 v[112:115], v[158:159], off offset:896
	s_waitcnt lgkmcnt(1)
	v_mfma_f32_32x32x16_bf16 v[4:19], v[214:217], v[230:233], v[4:19]
	global_load_dwordx4 v[116:119], v[156:157], off offset:896
	ds_read_b128 v[230:233], v195 offset:41568
	ds_read_b128 v[202:205], v194 offset:4672
	v_mfma_f32_32x32x16_bf16 v[20:35], v[210:213], v[218:221], v[20:35]
	global_load_dwordx4 v[120:123], v[154:155], off offset:896
	ds_read_b128 v[218:221], v194 offset:4704
	ds_read_b128 v[210:213], v194 offset:64
	s_waitcnt lgkmcnt(4)
	v_mfma_f32_32x32x16_bf16 v[52:67], v[206:209], v[222:225], v[52:67]
	global_load_dwordx4 v[124:127], v[152:153], off offset:896
	ds_read_b128 v[226:229], v195 offset:36960
	ds_read_b128 v[206:209], v195 offset:41536
	v_mfma_f32_32x32x16_bf16 v[20:35], v[214:217], v[222:225], v[20:35]
	global_load_dwordx4 v[128:131], v[146:147], off offset:896
	ds_read_b128 v[222:225], v195 offset:36928
	ds_read_b128 v[214:217], v194 offset:96
	s_waitcnt lgkmcnt(1)
	v_mfma_f32_32x32x16_bf16 v[52:67], v[210:213], v[222:225], v[52:67]
	s_waitcnt vmcnt(23)
	ds_write_b128 v167, v[132:135] offset:18432
	v_mfma_f32_32x32x16_bf16 v[36:51], v[210:213], v[206:209], v[36:51]
	s_waitcnt vmcnt(22)
	ds_write_b128 v167, v[136:139] offset:55296
	v_mfma_f32_32x32x16_bf16 v[20:35], v[202:205], v[222:225], v[20:35]
	s_waitcnt vmcnt(21)
	ds_write_b128 v190, v[140:143] offset:18432
	v_mfma_f32_32x32x16_bf16 v[4:19], v[202:205], v[206:209], v[4:19]
	s_waitcnt vmcnt(20)
	ds_write_b128 v190, v[198:201] offset:55296
	s_waitcnt lgkmcnt(4)
	v_mfma_f32_32x32x16_bf16 v[52:67], v[214:217], v[226:229], v[52:67]
	s_waitcnt vmcnt(19)
	ds_write_b128 v191, v[174:177] offset:18432
	v_mfma_f32_32x32x16_bf16 v[36:51], v[214:217], v[230:233], v[36:51]
	s_waitcnt vmcnt(18)
	ds_write_b128 v191, v[178:181] offset:55296
	v_mfma_f32_32x32x16_bf16 v[20:35], v[218:221], v[226:229], v[20:35]
	s_waitcnt vmcnt(17)
	ds_write_b128 v192, v[242:245] offset:18432
	v_mfma_f32_32x32x16_bf16 v[4:19], v[218:221], v[230:233], v[4:19]
	s_waitcnt vmcnt(16)
	ds_write_b128 v192, v[246:249] offset:55296
	s_waitcnt lgkmcnt(0)
	s_barrier
; #define MFMA(a, b, c) __builtin_amdgcn_mfma_f32_32x32x16_bf16((a), (b), (c), 0, 0, 0)
; template <class Epi, class ColV>
; DI void gemm_tile(const bf16_t* __restrict__ A, int lda, const bf16_t* __restrict__ Bt, int ldb, int K, int m0, int n0, unsigned char* smem, Epi epi, ColV colv, const bf16_t* __restrict__ HYT = nullptr) {
;     ...
;     auto step = [&](int kt, u32x4 (&ldset)[8], const u32x4 (&stset)[8]) {
;         const int buf = kt & 1;
;         if (kt + 2 < nk) gload(ldset, kt + 2);
;         const bf16_t* Ab = As + (buf * 128 + 64 * wr + li) * LS + 8 * lh;
;         const bf16_t* Bb = Bs + (buf * 128 + 64 * wc + li) * LS + 8 * lh;
;         bf16x8 fa[2][2], fb[2][2], ga[2][2], gb[2][2];
; #pragma unroll
;         for (int k2 = 0; k2 < 2; ++k2) { fa[k2][0] = ld8(Ab + 16 * k2); fa[k2][1] = ld8(Ab + 32 * LS + 16 * k2); fb[k2][0] = ld8(Bb + 16 * k2); fb[k2][1] = ld8(Bb + 32 * LS + 16 * k2); }
;         __builtin_amdgcn_sched_barrier(0);
; #pragma unroll
;         for (int k2 = 0; k2 < 2; ++k2) {
;             acc[0][0] = MFMA(fa[k2][0], fb[k2][0], acc[0][0]); acc[0][1] = MFMA(fa[k2][0], fb[k2][1], acc[0][1]);
;             acc[1][0] = MFMA(fa[k2][1], fb[k2][0], acc[1][0]); acc[1][1] = MFMA(fa[k2][1], fb[k2][1], acc[1][1]);
;         }
; #pragma unroll
;         for (int k2 = 0; k2 < 2; ++k2) { const int ks = 2 + k2; ga[k2][0] = ld8(Ab + 16 * ks); ga[k2][1] = ld8(Ab + 32 * LS + 16 * ks); gb[k2][0] = ld8(Bb + 16 * ks); gb[k2][1] = ld8(Bb + 32 * LS + 16 * ks); }
; #pragma unroll
;         for (int k2 = 0; k2 < 2; ++k2) {
;             acc[0][0] = MFMA(ga[k2][0], gb[k2][0], acc[0][0]); acc[0][1] = MFMA(ga[k2][0], gb[k2][1], acc[0][1]);
;             acc[1][0] = MFMA(ga[k2][1], gb[k2][0], acc[1][0]); acc[1][1] = MFMA(ga[k2][1], gb[k2][1], acc[1][1]);
;         }
;         if (kt + 1 < nk) sstore(stset, buf ^ 1, kt + 1);
; #pragma unroll
;         for (int i = 0; i < 8; ++i) { __builtin_amdgcn_sched_group_barrier(0x008, 1, 0); __builtin_amdgcn_sched_group_barrier(0x100, 1, 0); }
; #pragma unroll
;         for (int i = 0; i < 8; ++i) { __builtin_amdgcn_sched_group_barrier(0x008, 1, 0); __builtin_amdgcn_sched_group_barrier(0x200, 1, 0); }
;         __builtin_amdgcn_sched_barrier(0);
;         __syncthreads();
;     };
	ds_read_b128 v[202:205], v196
	ds_read_b128 v[218:221], v197 offset:36864
	ds_read_b128 v[226:229], v197 offset:41472
	ds_read_b128 v[210:213], v196 offset:4608
	ds_read_b128 v[206:209], v196 offset:32
	ds_read_b128 v[230:233], v197 offset:41504
	ds_read_b128 v[214:217], v196 offset:4640
	ds_read_b128 v[222:225], v197 offset:36896
	s_waitcnt lgkmcnt(6)
	v_mfma_f32_32x32x16_bf16 v[52:67], v[202:205], v[218:221], v[52:67]
	global_load_dwordx4 v[132:135], v[164:165], off offset:1024
	s_waitcnt lgkmcnt(5)
	v_mfma_f32_32x32x16_bf16 v[36:51], v[202:205], v[226:229], v[36:51]
	global_load_dwordx4 v[136:139], v[162:163], off offset:1024
	s_waitcnt lgkmcnt(4)
	v_mfma_f32_32x32x16_bf16 v[4:19], v[210:213], v[226:229], v[4:19]
	global_load_dwordx4 v[140:143], v[160:161], off offset:1024
	s_waitcnt lgkmcnt(2)
	v_mfma_f32_32x32x16_bf16 v[36:51], v[206:209], v[230:233], v[36:51]
	global_load_dwordx4 v[198:201], v[158:159], off offset:1024
	s_waitcnt lgkmcnt(1)
	v_mfma_f32_32x32x16_bf16 v[4:19], v[214:217], v[230:233], v[4:19]
	global_load_dwordx4 v[174:177], v[156:157], off offset:1024
	ds_read_b128 v[230:233], v197 offset:41568
	ds_read_b128 v[202:205], v196 offset:4672
	v_mfma_f32_32x32x16_bf16 v[20:35], v[210:213], v[218:221], v[20:35]
	global_load_dwordx4 v[178:181], v[154:155], off offset:1024
	ds_read_b128 v[218:221], v196 offset:4704
	ds_read_b128 v[210:213], v196 offset:64
	s_waitcnt lgkmcnt(4)
	v_mfma_f32_32x32x16_bf16 v[52:67], v[206:209], v[222:225], v[52:67]
	global_load_dwordx4 v[242:245], v[152:153], off offset:1024
	ds_read_b128 v[226:229], v197 offset:36960
	ds_read_b128 v[206:209], v197 offset:41536
	v_mfma_f32_32x32x16_bf16 v[20:35], v[214:217], v[222:225], v[20:35]
	global_load_dwordx4 v[246:249], v[146:147], off offset:1024
	ds_read_b128 v[222:225], v197 offset:36928
	ds_read_b128 v[214:217], v196 offset:96
	s_waitcnt lgkmcnt(1)
	v_mfma_f32_32x32x16_bf16 v[52:67], v[210:213], v[222:225], v[52:67]
	s_waitcnt vmcnt(23)
	ds_write_b128 v167, v[68:71]
	v_mfma_f32_32x32x16_bf16 v[36:51], v[210:213], v[206:209], v[36:51]
	s_waitcnt vmcnt(22)
	ds_write_b128 v167, v[72:75] offset:36864
	v_mfma_f32_32x32x16_bf16 v[20:35], v[202:205], v[222:225], v[20:35]
	s_waitcnt vmcnt(21)
	ds_write_b128 v190, v[76:79]
	v_mfma_f32_32x32x16_bf16 v[4:19], v[202:205], v[206:209], v[4:19]
	s_waitcnt vmcnt(20)
	ds_write_b128 v190, v[80:83] offset:36864
	s_waitcnt lgkmcnt(4)
	v_mfma_f32_32x32x16_bf16 v[52:67], v[214:217], v[226:229], v[52:67]
	s_waitcnt vmcnt(19)
	ds_write_b128 v191, v[84:87]
	v_mfma_f32_32x32x16_bf16 v[36:51], v[214:217], v[230:233], v[36:51]
	s_waitcnt vmcnt(18)
	ds_write_b128 v191, v[88:91] offset:36864
	v_mfma_f32_32x32x16_bf16 v[20:35], v[218:221], v[226:229], v[20:35]
	s_waitcnt vmcnt(17)
	ds_write_b128 v192, v[92:95]
	v_mfma_f32_32x32x16_bf16 v[4:19], v[218:221], v[230:233], v[4:19]
	s_waitcnt vmcnt(16)
	ds_write_b128 v192, v[104:107] offset:36864
	s_waitcnt lgkmcnt(0)
	s_barrier
	ds_read_b128 v[202:205], v194
	ds_read_b128 v[218:221], v195 offset:36864
	ds_read_b128 v[226:229], v195 offset:41472
	ds_read_b128 v[210:213], v194 offset:4608
	ds_read_b128 v[206:209], v194 offset:32
	ds_read_b128 v[230:233], v195 offset:41504
	ds_read_b128 v[214:217], v194 offset:4640
	ds_read_b128 v[222:225], v195 offset:36896
	s_waitcnt lgkmcnt(6)
	v_mfma_f32_32x32x16_bf16 v[52:67], v[202:205], v[218:221], v[52:67]
	global_load_dwordx4 v[68:71], v[164:165], off offset:1152
	s_waitcnt lgkmcnt(5)
	v_mfma_f32_32x32x16_bf16 v[36:51], v[202:205], v[226:229], v[36:51]
	global_load_dwordx4 v[72:75], v[162:163], off offset:1152
	s_waitcnt lgkmcnt(4)
	v_mfma_f32_32x32x16_bf16 v[4:19], v[210:213], v[226:229], v[4:19]
	global_load_dwordx4 v[76:79], v[160:161], off offset:1152
	s_waitcnt lgkmcnt(2)
	v_mfma_f32_32x32x16_bf16 v[36:51], v[206:209], v[230:233], v[36:51]
	global_load_dwordx4 v[80:83], v[158:159], off offset:1152
	s_waitcnt lgkmcnt(1)
	v_mfma_f32_32x32x16_bf16 v[4:19], v[214:217], v[230:233], v[4:19]
	global_load_dwordx4 v[84:87], v[156:157], off offset:1152
	ds_read_b128 v[230:233], v195 offset:41568
	ds_read_b128 v[202:205], v194 offset:4672
	v_mfma_f32_32x32x16_bf16 v[20:35], v[210:213], v[218:221], v[20:35]
	global_load_dwordx4 v[88:91], v[154:155], off offset:1152
	ds_read_b128 v[218:221], v194 offset:4704
	ds_read_b128 v[210:213], v194 offset:64
	s_waitcnt lgkmcnt(4)
	v_mfma_f32_32x32x16_bf16 v[52:67], v[206:209], v[222:225], v[52:67]
	global_load_dwordx4 v[92:95], v[152:153], off offset:1152
	ds_read_b128 v[226:229], v195 offset:36960
	ds_read_b128 v[206:209], v195 offset:41536
	v_mfma_f32_32x32x16_bf16 v[20:35], v[214:217], v[222:225], v[20:35]
	global_load_dwordx4 v[104:107], v[146:147], off offset:1152
	ds_read_b128 v[222:225], v195 offset:36928
	ds_read_b128 v[214:217], v194 offset:96
	s_waitcnt lgkmcnt(1)
	v_mfma_f32_32x32x16_bf16 v[52:67], v[210:213], v[222:225], v[52:67]
	s_waitcnt vmcnt(23)
	ds_write_b128 v167, v[96:99] offset:18432
	v_mfma_f32_32x32x16_bf16 v[36:51], v[210:213], v[206:209], v[36:51]
	s_waitcnt vmcnt(22)
	ds_write_b128 v167, v[100:103] offset:55296
	v_mfma_f32_32x32x16_bf16 v[20:35], v[202:205], v[222:225], v[20:35]
	s_waitcnt vmcnt(21)
	ds_write_b128 v190, v[108:111] offset:18432
	v_mfma_f32_32x32x16_bf16 v[4:19], v[202:205], v[206:209], v[4:19]
	s_waitcnt vmcnt(20)
	ds_write_b128 v190, v[112:115] offset:55296
	s_waitcnt lgkmcnt(4)
	v_mfma_f32_32x32x16_bf16 v[52:67], v[214:217], v[226:229], v[52:67]
	s_waitcnt vmcnt(19)
	ds_write_b128 v191, v[116:119] offset:18432
	v_mfma_f32_32x32x16_bf16 v[36:51], v[214:217], v[230:233], v[36:51]
	s_waitcnt vmcnt(18)
	ds_write_b128 v191, v[120:123] offset:55296
	v_mfma_f32_32x32x16_bf16 v[20:35], v[218:221], v[226:229], v[20:35]
	s_waitcnt vmcnt(17)
	ds_write_b128 v192, v[124:127] offset:18432
	v_mfma_f32_32x32x16_bf16 v[4:19], v[218:221], v[230:233], v[4:19]
	s_waitcnt vmcnt(16)
	ds_write_b128 v192, v[128:131] offset:55296
	s_waitcnt lgkmcnt(0)
	s_barrier
; #define MFMA(a, b, c) __builtin_amdgcn_mfma_f32_32x32x16_bf16((a), (b), (c), 0, 0, 0)
; template <class Epi, class ColV>
; DI void gemm_tile(const bf16_t* __restrict__ A, int lda, const bf16_t* __restrict__ Bt, int ldb, int K, int m0, int n0, unsigned char* smem, Epi epi, ColV colv, const bf16_t* __restrict__ HYT = nullptr) {
;     ...
;     auto step = [&](int kt, u32x4 (&ldset)[8], const u32x4 (&stset)[8]) {
;         const int buf = kt & 1;
;         if (kt + 2 < nk) gload(ldset, kt + 2);
;         const bf16_t* Ab = As + (buf * 128 + 64 * wr + li) * LS + 8 * lh;
;         const bf16_t* Bb = Bs + (buf * 128 + 64 * wc + li) * LS + 8 * lh;
;         bf16x8 fa[2][2], fb[2][2], ga[2][2], gb[2][2];
; #pragma unroll
;         for (int k2 = 0; k2 < 2; ++k2) { fa[k2][0] = ld8(Ab + 16 * k2); fa[k2][1] = ld8(Ab + 32 * LS + 16 * k2); fb[k2][0] = ld8(Bb + 16 * k2); fb[k2][1] = ld8(Bb + 32 * LS + 16 * k2); }
;         __builtin_amdgcn_sched_barrier(0);
; #pragma unroll
;         for (int k2 = 0; k2 < 2; ++k2) {
;             acc[0][0] = MFMA(fa[k2][0], fb[k2][0], acc[0][0]); acc[0][1] = MFMA(fa[k2][0], fb[k2][1], acc[0][1]);
;             acc[1][0] = MFMA(fa[k2][1], fb[k2][0], acc[1][0]); acc[1][1] = MFMA(fa[k2][1], fb[k2][1], acc[1][1]);
;         }
; #pragma unroll
;         for (int k2 = 0; k2 < 2; ++k2) { const int ks = 2 + k2; ga[k2][0] = ld8(Ab + 16 * ks); ga[k2][1] = ld8(Ab + 32 * LS + 16 * ks); gb[k2][0] = ld8(Bb + 16 * ks); gb[k2][1] = ld8(Bb + 32 * LS + 16 * ks); }
; #pragma unroll
;         for (int k2 = 0; k2 < 2; ++k2) {
;             acc[0][0] = MFMA(ga[k2][0], gb[k2][0], acc[0][0]); acc[0][1] = MFMA(ga[k2][0], gb[k2][1], acc[0][1]);
;             acc[1][0] = MFMA(ga[k2][1], gb[k2][0], acc[1][0]); acc[1][1] = MFMA(ga[k2][1], gb[k2][1], acc[1][1]);
;         }
;         if (kt + 1 < nk) sstore(stset, buf ^ 1, kt + 1);
; #pragma unroll
;         for (int i = 0; i < 8; ++i) { __builtin_amdgcn_sched_group_barrier(0x008, 1, 0); __builtin_amdgcn_sched_group_barrier(0x100, 1, 0); }
; #pragma unroll
;         for (int i = 0; i < 8; ++i) { __builtin_amdgcn_sched_group_barrier(0x008, 1, 0); __builtin_amdgcn_sched_group_barrier(0x200, 1, 0); }
;         __builtin_amdgcn_sched_barrier(0);
;         __syncthreads();
;     };
	ds_read_b128 v[202:205], v196
	ds_read_b128 v[218:221], v197 offset:36864
	ds_read_b128 v[226:229], v197 offset:41472
	ds_read_b128 v[210:213], v196 offset:4608
	ds_read_b128 v[206:209], v196 offset:32
	ds_read_b128 v[230:233], v197 offset:41504
	ds_read_b128 v[214:217], v196 offset:4640
	ds_read_b128 v[222:225], v197 offset:36896
	s_waitcnt lgkmcnt(6)
	v_mfma_f32_32x32x16_bf16 v[52:67], v[202:205], v[218:221], v[52:67]
	global_load_dwordx4 v[96:99], v[164:165], off offset:1280
	s_waitcnt lgkmcnt(5)
	v_mfma_f32_32x32x16_bf16 v[36:51], v[202:205], v[226:229], v[36:51]
	global_load_dwordx4 v[100:103], v[162:163], off offset:1280
	s_waitcnt lgkmcnt(4)
	v_mfma_f32_32x32x16_bf16 v[4:19], v[210:213], v[226:229], v[4:19]
	global_load_dwordx4 v[108:111], v[160:161], off offset:1280
	s_waitcnt lgkmcnt(2)
	v_mfma_f32_32x32x16_bf16 v[36:51], v[206:209], v[230:233], v[36:51]
	global_load_dwordx4 v[112:115], v[158:159], off offset:1280
	s_waitcnt lgkmcnt(1)
	v_mfma_f32_32x32x16_bf16 v[4:19], v[214:217], v[230:233], v[4:19]
	global_load_dwordx4 v[116:119], v[156:157], off offset:1280
	ds_read_b128 v[230:233], v197 offset:41568
	ds_read_b128 v[202:205], v196 offset:4672
	v_mfma_f32_32x32x16_bf16 v[20:35], v[210:213], v[218:221], v[20:35]
	global_load_dwordx4 v[120:123], v[154:155], off offset:1280
	ds_read_b128 v[218:221], v196 offset:4704
	ds_read_b128 v[210:213], v196 offset:64
	s_waitcnt lgkmcnt(4)
	v_mfma_f32_32x32x16_bf16 v[52:67], v[206:209], v[222:225], v[52:67]
	global_load_dwordx4 v[124:127], v[152:153], off offset:1280
	ds_read_b128 v[226:229], v197 offset:36960
	ds_read_b128 v[206:209], v197 offset:41536
	v_mfma_f32_32x32x16_bf16 v[20:35], v[214:217], v[222:225], v[20:35]
	global_load_dwordx4 v[128:131], v[146:147], off offset:1280
	ds_read_b128 v[222:225], v197 offset:36928
	ds_read_b128 v[214:217], v196 offset:96
	s_waitcnt lgkmcnt(1)
	v_mfma_f32_32x32x16_bf16 v[52:67], v[210:213], v[222:225], v[52:67]
	s_waitcnt vmcnt(23)
	ds_write_b128 v167, v[132:135]
	v_mfma_f32_32x32x16_bf16 v[36:51], v[210:213], v[206:209], v[36:51]
	s_waitcnt vmcnt(22)
	ds_write_b128 v167, v[136:139] offset:36864
	v_mfma_f32_32x32x16_bf16 v[20:35], v[202:205], v[222:225], v[20:35]
	s_waitcnt vmcnt(21)
	ds_write_b128 v190, v[140:143]
	v_mfma_f32_32x32x16_bf16 v[4:19], v[202:205], v[206:209], v[4:19]
	s_waitcnt vmcnt(20)
	ds_write_b128 v190, v[198:201] offset:36864
	s_waitcnt lgkmcnt(4)
	v_mfma_f32_32x32x16_bf16 v[52:67], v[214:217], v[226:229], v[52:67]
	s_waitcnt vmcnt(19)
	ds_write_b128 v191, v[174:177]
	v_mfma_f32_32x32x16_bf16 v[36:51], v[214:217], v[230:233], v[36:51]
	s_waitcnt vmcnt(18)
	ds_write_b128 v191, v[178:181] offset:36864
	v_mfma_f32_32x32x16_bf16 v[20:35], v[218:221], v[226:229], v[20:35]
	s_waitcnt vmcnt(17)
	ds_write_b128 v192, v[242:245]
	v_mfma_f32_32x32x16_bf16 v[4:19], v[218:221], v[230:233], v[4:19]
	s_waitcnt vmcnt(16)
	ds_write_b128 v192, v[246:249] offset:36864
	s_waitcnt lgkmcnt(0)
	s_barrier
	ds_read_b128 v[202:205], v194
	ds_read_b128 v[218:221], v195 offset:36864
	ds_read_b128 v[226:229], v195 offset:41472
	ds_read_b128 v[210:213], v194 offset:4608
	ds_read_b128 v[206:209], v194 offset:32
	ds_read_b128 v[230:233], v195 offset:41504
	ds_read_b128 v[214:217], v194 offset:4640
	ds_read_b128 v[222:225], v195 offset:36896
	s_waitcnt lgkmcnt(6)
	v_mfma_f32_32x32x16_bf16 v[52:67], v[202:205], v[218:221], v[52:67]
	global_load_dwordx4 v[132:135], v[164:165], off offset:1408
	s_waitcnt lgkmcnt(5)
	v_mfma_f32_32x32x16_bf16 v[36:51], v[202:205], v[226:229], v[36:51]
	global_load_dwordx4 v[136:139], v[162:163], off offset:1408
	s_waitcnt lgkmcnt(4)
	v_mfma_f32_32x32x16_bf16 v[4:19], v[210:213], v[226:229], v[4:19]
	global_load_dwordx4 v[140:143], v[160:161], off offset:1408
	s_waitcnt lgkmcnt(2)
	v_mfma_f32_32x32x16_bf16 v[36:51], v[206:209], v[230:233], v[36:51]
	global_load_dwordx4 v[198:201], v[158:159], off offset:1408
	s_waitcnt lgkmcnt(1)
	v_mfma_f32_32x32x16_bf16 v[4:19], v[214:217], v[230:233], v[4:19]
	global_load_dwordx4 v[174:177], v[156:157], off offset:1408
	ds_read_b128 v[230:233], v195 offset:41568
	ds_read_b128 v[202:205], v194 offset:4672
	v_mfma_f32_32x32x16_bf16 v[20:35], v[210:213], v[218:221], v[20:35]
	global_load_dwordx4 v[178:181], v[154:155], off offset:1408
	ds_read_b128 v[218:221], v194 offset:4704
	ds_read_b128 v[210:213], v194 offset:64
	s_waitcnt lgkmcnt(4)
	v_mfma_f32_32x32x16_bf16 v[52:67], v[206:209], v[222:225], v[52:67]
	global_load_dwordx4 v[242:245], v[152:153], off offset:1408
	ds_read_b128 v[226:229], v195 offset:36960
	ds_read_b128 v[206:209], v195 offset:41536
	v_mfma_f32_32x32x16_bf16 v[20:35], v[214:217], v[222:225], v[20:35]
	global_load_dwordx4 v[246:249], v[146:147], off offset:1408
	ds_read_b128 v[222:225], v195 offset:36928
	ds_read_b128 v[214:217], v194 offset:96
	s_waitcnt lgkmcnt(1)
	v_mfma_f32_32x32x16_bf16 v[52:67], v[210:213], v[222:225], v[52:67]
	s_waitcnt vmcnt(23)
	ds_write_b128 v167, v[68:71] offset:18432
	v_mfma_f32_32x32x16_bf16 v[36:51], v[210:213], v[206:209], v[36:51]
	s_waitcnt vmcnt(22)
	ds_write_b128 v167, v[72:75] offset:55296
	v_mfma_f32_32x32x16_bf16 v[20:35], v[202:205], v[222:225], v[20:35]
	s_waitcnt vmcnt(21)
	ds_write_b128 v190, v[76:79] offset:18432
	v_mfma_f32_32x32x16_bf16 v[4:19], v[202:205], v[206:209], v[4:19]
	s_waitcnt vmcnt(20)
	ds_write_b128 v190, v[80:83] offset:55296
	s_waitcnt lgkmcnt(4)
	v_mfma_f32_32x32x16_bf16 v[52:67], v[214:217], v[226:229], v[52:67]
	s_waitcnt vmcnt(19)
	ds_write_b128 v191, v[84:87] offset:18432
	v_mfma_f32_32x32x16_bf16 v[36:51], v[214:217], v[230:233], v[36:51]
	s_waitcnt vmcnt(18)
	ds_write_b128 v191, v[88:91] offset:55296
	v_mfma_f32_32x32x16_bf16 v[20:35], v[218:221], v[226:229], v[20:35]
	s_waitcnt vmcnt(17)
	ds_write_b128 v192, v[92:95] offset:18432
	v_mfma_f32_32x32x16_bf16 v[4:19], v[218:221], v[230:233], v[4:19]
	s_waitcnt vmcnt(16)
	ds_write_b128 v192, v[104:107] offset:55296
	s_waitcnt lgkmcnt(0)
	s_barrier
; #define MFMA(a, b, c) __builtin_amdgcn_mfma_f32_32x32x16_bf16((a), (b), (c), 0, 0, 0)
; template <class Epi, class ColV>
; DI void gemm_tile(const bf16_t* __restrict__ A, int lda, const bf16_t* __restrict__ Bt, int ldb, int K, int m0, int n0, unsigned char* smem, Epi epi, ColV colv, const bf16_t* __restrict__ HYT = nullptr) {
;     ...
;     auto step = [&](int kt, u32x4 (&ldset)[8], const u32x4 (&stset)[8]) {
;         const int buf = kt & 1;
;         if (kt + 2 < nk) gload(ldset, kt + 2);
;         const bf16_t* Ab = As + (buf * 128 + 64 * wr + li) * LS + 8 * lh;
;         const bf16_t* Bb = Bs + (buf * 128 + 64 * wc + li) * LS + 8 * lh;
;         bf16x8 fa[2][2], fb[2][2], ga[2][2], gb[2][2];
; #pragma unroll
;         for (int k2 = 0; k2 < 2; ++k2) { fa[k2][0] = ld8(Ab + 16 * k2); fa[k2][1] = ld8(Ab + 32 * LS + 16 * k2); fb[k2][0] = ld8(Bb + 16 * k2); fb[k2][1] = ld8(Bb + 32 * LS + 16 * k2); }
;         __builtin_amdgcn_sched_barrier(0);
; #pragma unroll
;         for (int k2 = 0; k2 < 2; ++k2) {
;             acc[0][0] = MFMA(fa[k2][0], fb[k2][0], acc[0][0]); acc[0][1] = MFMA(fa[k2][0], fb[k2][1], acc[0][1]);
;             acc[1][0] = MFMA(fa[k2][1], fb[k2][0], acc[1][0]); acc[1][1] = MFMA(fa[k2][1], fb[k2][1], acc[1][1]);
;         }
; #pragma unroll
;         for (int k2 = 0; k2 < 2; ++k2) { const int ks = 2 + k2; ga[k2][0] = ld8(Ab + 16 * ks); ga[k2][1] = ld8(Ab + 32 * LS + 16 * ks); gb[k2][0] = ld8(Bb + 16 * ks); gb[k2][1] = ld8(Bb + 32 * LS + 16 * ks); }
; #pragma unroll
;         for (int k2 = 0; k2 < 2; ++k2) {
;             acc[0][0] = MFMA(ga[k2][0], gb[k2][0], acc[0][0]); acc[0][1] = MFMA(ga[k2][0], gb[k2][1], acc[0][1]);
;             acc[1][0] = MFMA(ga[k2][1], gb[k2][0], acc[1][0]); acc[1][1] = MFMA(ga[k2][1], gb[k2][1], acc[1][1]);
;         }
;         if (kt + 1 < nk) sstore(stset, buf ^ 1, kt + 1);
; #pragma unroll
;         for (int i = 0; i < 8; ++i) { __builtin_amdgcn_sched_group_barrier(0x008, 1, 0); __builtin_amdgcn_sched_group_barrier(0x100, 1, 0); }
; #pragma unroll
;         for (int i = 0; i < 8; ++i) { __builtin_amdgcn_sched_group_barrier(0x008, 1, 0); __builtin_amdgcn_sched_group_barrier(0x200, 1, 0); }
;         __builtin_amdgcn_sched_barrier(0);
;         __syncthreads();
	ds_read_b128 v[202:205], v196
	ds_read_b128 v[218:221], v197 offset:36864
	ds_read_b128 v[226:229], v197 offset:41472
	ds_read_b128 v[210:213], v196 offset:4608
	ds_read_b128 v[206:209], v196 offset:32
	ds_read_b128 v[230:233], v197 offset:41504
	ds_read_b128 v[214:217], v196 offset:4640
	ds_read_b128 v[222:225], v197 offset:36896
	s_waitcnt lgkmcnt(6)
	v_mfma_f32_32x32x16_bf16 v[52:67], v[202:205], v[218:221], v[52:67]
	global_load_dwordx4 v[68:71], v[164:165], off offset:1536
	s_waitcnt lgkmcnt(5)
	v_mfma_f32_32x32x16_bf16 v[36:51], v[202:205], v[226:229], v[36:51]
	global_load_dwordx4 v[72:75], v[162:163], off offset:1536
	s_waitcnt lgkmcnt(4)
	v_mfma_f32_32x32x16_bf16 v[4:19], v[210:213], v[226:229], v[4:19]
	global_load_dwordx4 v[76:79], v[160:161], off offset:1536
	s_waitcnt lgkmcnt(2)
	v_mfma_f32_32x32x16_bf16 v[36:51], v[206:209], v[230:233], v[36:51]
	global_load_dwordx4 v[80:83], v[158:159], off offset:1536
	s_waitcnt lgkmcnt(1)
	v_mfma_f32_32x32x16_bf16 v[4:19], v[214:217], v[230:233], v[4:19]
	global_load_dwordx4 v[84:87], v[156:157], off offset:1536
	ds_read_b128 v[230:233], v197 offset:41568
	ds_read_b128 v[202:205], v196 offset:4672
	v_mfma_f32_32x32x16_bf16 v[20:35], v[210:213], v[218:221], v[20:35]
	global_load_dwordx4 v[88:91], v[154:155], off offset:1536
	ds_read_b128 v[218:221], v196 offset:4704
	ds_read_b128 v[210:213], v196 offset:64
	s_waitcnt lgkmcnt(4)
	v_mfma_f32_32x32x16_bf16 v[52:67], v[206:209], v[222:225], v[52:67]
	global_load_dwordx4 v[92:95], v[152:153], off offset:1536
	ds_read_b128 v[226:229], v197 offset:36960
	ds_read_b128 v[206:209], v197 offset:41536
	v_mfma_f32_32x32x16_bf16 v[20:35], v[214:217], v[222:225], v[20:35]
	global_load_dwordx4 v[104:107], v[146:147], off offset:1536
	ds_read_b128 v[222:225], v197 offset:36928
	ds_read_b128 v[214:217], v196 offset:96
	s_waitcnt lgkmcnt(1)
	v_mfma_f32_32x32x16_bf16 v[52:67], v[210:213], v[222:225], v[52:67]
	s_waitcnt vmcnt(23)
	ds_write_b128 v167, v[96:99]
	v_mfma_f32_32x32x16_bf16 v[36:51], v[210:213], v[206:209], v[36:51]
	s_waitcnt vmcnt(22)
	ds_write_b128 v167, v[100:103] offset:36864
	v_mfma_f32_32x32x16_bf16 v[20:35], v[202:205], v[222:225], v[20:35]
	s_waitcnt vmcnt(21)
	ds_write_b128 v190, v[108:111]
	v_mfma_f32_32x32x16_bf16 v[4:19], v[202:205], v[206:209], v[4:19]
	s_waitcnt vmcnt(20)
	ds_write_b128 v190, v[112:115] offset:36864
	s_waitcnt lgkmcnt(4)
	v_mfma_f32_32x32x16_bf16 v[52:67], v[214:217], v[226:229], v[52:67]
	s_waitcnt vmcnt(19)
	ds_write_b128 v191, v[116:119]
	v_mfma_f32_32x32x16_bf16 v[36:51], v[214:217], v[230:233], v[36:51]
	s_waitcnt vmcnt(18)
	ds_write_b128 v191, v[120:123] offset:36864
	v_mfma_f32_32x32x16_bf16 v[20:35], v[218:221], v[226:229], v[20:35]
	s_waitcnt vmcnt(17)
	ds_write_b128 v192, v[124:127]
	v_mfma_f32_32x32x16_bf16 v[4:19], v[218:221], v[230:233], v[4:19]
	s_waitcnt vmcnt(16)
	ds_write_b128 v192, v[128:131] offset:36864
	s_waitcnt lgkmcnt(0)
	s_barrier
	ds_read_b128 v[202:205], v194
	ds_read_b128 v[218:221], v195 offset:36864
	ds_read_b128 v[226:229], v195 offset:41472
	ds_read_b128 v[210:213], v194 offset:4608
	ds_read_b128 v[206:209], v194 offset:32
	ds_read_b128 v[230:233], v195 offset:41504
	ds_read_b128 v[214:217], v194 offset:4640
	ds_read_b128 v[222:225], v195 offset:36896
	s_waitcnt lgkmcnt(6)
	v_mfma_f32_32x32x16_bf16 v[52:67], v[202:205], v[218:221], v[52:67]
	global_load_dwordx4 v[96:99], v[164:165], off offset:1664
	s_waitcnt lgkmcnt(5)
	v_mfma_f32_32x32x16_bf16 v[36:51], v[202:205], v[226:229], v[36:51]
	global_load_dwordx4 v[100:103], v[162:163], off offset:1664
	s_waitcnt lgkmcnt(4)
	v_mfma_f32_32x32x16_bf16 v[4:19], v[210:213], v[226:229], v[4:19]
	global_load_dwordx4 v[108:111], v[160:161], off offset:1664
	s_waitcnt lgkmcnt(2)
	v_mfma_f32_32x32x16_bf16 v[36:51], v[206:209], v[230:233], v[36:51]
	global_load_dwordx4 v[112:115], v[158:159], off offset:1664
	s_waitcnt lgkmcnt(1)
	v_mfma_f32_32x32x16_bf16 v[4:19], v[214:217], v[230:233], v[4:19]
	global_load_dwordx4 v[116:119], v[156:157], off offset:1664
	ds_read_b128 v[230:233], v195 offset:41568
	ds_read_b128 v[202:205], v194 offset:4672
	v_mfma_f32_32x32x16_bf16 v[20:35], v[210:213], v[218:221], v[20:35]
	global_load_dwordx4 v[120:123], v[154:155], off offset:1664
	ds_read_b128 v[218:221], v194 offset:4704
	ds_read_b128 v[210:213], v194 offset:64
	s_waitcnt lgkmcnt(4)
	v_mfma_f32_32x32x16_bf16 v[52:67], v[206:209], v[222:225], v[52:67]
	global_load_dwordx4 v[124:127], v[152:153], off offset:1664
	ds_read_b128 v[226:229], v195 offset:36960
	ds_read_b128 v[206:209], v195 offset:41536
	v_mfma_f32_32x32x16_bf16 v[20:35], v[214:217], v[222:225], v[20:35]
	global_load_dwordx4 v[128:131], v[146:147], off offset:1664
	ds_read_b128 v[222:225], v195 offset:36928
	ds_read_b128 v[214:217], v194 offset:96
	s_waitcnt lgkmcnt(1)
	v_mfma_f32_32x32x16_bf16 v[52:67], v[210:213], v[222:225], v[52:67]
	s_waitcnt vmcnt(23)
	ds_write_b128 v167, v[132:135] offset:18432
	v_mfma_f32_32x32x16_bf16 v[36:51], v[210:213], v[206:209], v[36:51]
	s_waitcnt vmcnt(22)
	ds_write_b128 v167, v[136:139] offset:55296
	v_mfma_f32_32x32x16_bf16 v[20:35], v[202:205], v[222:225], v[20:35]
	s_waitcnt vmcnt(21)
	ds_write_b128 v190, v[140:143] offset:18432
	v_mfma_f32_32x32x16_bf16 v[4:19], v[202:205], v[206:209], v[4:19]
	s_waitcnt vmcnt(20)
	ds_write_b128 v190, v[198:201] offset:55296
	s_waitcnt lgkmcnt(4)
	v_mfma_f32_32x32x16_bf16 v[52:67], v[214:217], v[226:229], v[52:67]
	s_waitcnt vmcnt(19)
	ds_write_b128 v191, v[174:177] offset:18432
	v_mfma_f32_32x32x16_bf16 v[36:51], v[214:217], v[230:233], v[36:51]
	s_waitcnt vmcnt(18)
	ds_write_b128 v191, v[178:181] offset:55296
	v_mfma_f32_32x32x16_bf16 v[20:35], v[218:221], v[226:229], v[20:35]
	s_waitcnt vmcnt(17)
	ds_write_b128 v192, v[242:245] offset:18432
	v_mfma_f32_32x32x16_bf16 v[4:19], v[218:221], v[230:233], v[4:19]
	s_waitcnt vmcnt(16)
	ds_write_b128 v192, v[246:249] offset:55296
	s_waitcnt lgkmcnt(0)
	s_barrier
; #define MFMA(a, b, c) __builtin_amdgcn_mfma_f32_32x32x16_bf16((a), (b), (c), 0, 0, 0)
; template <class Epi, class ColV>
; DI void gemm_tile(const bf16_t* __restrict__ A, int lda, const bf16_t* __restrict__ Bt, int ldb, int K, int m0, int n0, unsigned char* smem, Epi epi, ColV colv, const bf16_t* __restrict__ HYT = nullptr) {
;     ...
;     auto step = [&](int kt, u32x4 (&ldset)[8], const u32x4 (&stset)[8]) {
;         const int buf = kt & 1;
;         if (kt + 2 < nk) gload(ldset, kt + 2);
;         const bf16_t* Ab = As + (buf * 128 + 64 * wr + li) * LS + 8 * lh;
;         const bf16_t* Bb = Bs + (buf * 128 + 64 * wc + li) * LS + 8 * lh;
;         bf16x8 fa[2][2], fb[2][2], ga[2][2], gb[2][2];
; #pragma unroll
;         for (int k2 = 0; k2 < 2; ++k2) { fa[k2][0] = ld8(Ab + 16 * k2); fa[k2][1] = ld8(Ab + 32 * LS + 16 * k2); fb[k2][0] = ld8(Bb + 16 * k2); fb[k2][1] = ld8(Bb + 32 * LS + 16 * k2); }
;         __builtin_amdgcn_sched_barrier(0);
; #pragma unroll
;         for (int k2 = 0; k2 < 2; ++k2) {
;             acc[0][0] = MFMA(fa[k2][0], fb[k2][0], acc[0][0]); acc[0][1] = MFMA(fa[k2][0], fb[k2][1], acc[0][1]);
;             acc[1][0] = MFMA(fa[k2][1], fb[k2][0], acc[1][0]); acc[1][1] = MFMA(fa[k2][1], fb[k2][1], acc[1][1]);
;         }
; #pragma unroll
;         for (int k2 = 0; k2 < 2; ++k2) { const int ks = 2 + k2; ga[k2][0] = ld8(Ab + 16 * ks); ga[k2][1] = ld8(Ab + 32 * LS + 16 * ks); gb[k2][0] = ld8(Bb + 16 * ks); gb[k2][1] = ld8(Bb + 32 * LS + 16 * ks); }
; #pragma unroll
;         for (int k2 = 0; k2 < 2; ++k2) {
;             acc[0][0] = MFMA(ga[k2][0], gb[k2][0], acc[0][0]); acc[0][1] = MFMA(ga[k2][0], gb[k2][1], acc[0][1]);
;             acc[1][0] = MFMA(ga[k2][1], gb[k2][0], acc[1][0]); acc[1][1] = MFMA(ga[k2][1], gb[k2][1], acc[1][1]);
;         }
;         if (kt + 1 < nk) sstore(stset, buf ^ 1, kt + 1);
; #pragma unroll
;         for (int i = 0; i < 8; ++i) { __builtin_amdgcn_sched_group_barrier(0x008, 1, 0); __builtin_amdgcn_sched_group_barrier(0x100, 1, 0); }
; #pragma unroll
;         for (int i = 0; i < 8; ++i) { __builtin_amdgcn_sched_group_barrier(0x008, 1, 0); __builtin_amdgcn_sched_group_barrier(0x200, 1, 0); }
;         __builtin_amdgcn_sched_barrier(0);
;         __syncthreads();
	ds_read_b128 v[202:205], v196
	ds_read_b128 v[218:221], v197 offset:36864
	ds_read_b128 v[226:229], v197 offset:41472
	ds_read_b128 v[210:213], v196 offset:4608
	ds_read_b128 v[206:209], v196 offset:32
	ds_read_b128 v[230:233], v197 offset:41504
	ds_read_b128 v[214:217], v196 offset:4640
	ds_read_b128 v[222:225], v197 offset:36896
	s_waitcnt lgkmcnt(6)
	v_mfma_f32_32x32x16_bf16 v[52:67], v[202:205], v[218:221], v[52:67]
	global_load_dwordx4 v[132:135], v[164:165], off offset:1792
	s_waitcnt lgkmcnt(5)
	v_mfma_f32_32x32x16_bf16 v[36:51], v[202:205], v[226:229], v[36:51]
	global_load_dwordx4 v[136:139], v[162:163], off offset:1792
	s_waitcnt lgkmcnt(4)
	v_mfma_f32_32x32x16_bf16 v[4:19], v[210:213], v[226:229], v[4:19]
	global_load_dwordx4 v[140:143], v[160:161], off offset:1792
	s_waitcnt lgkmcnt(2)
	v_mfma_f32_32x32x16_bf16 v[36:51], v[206:209], v[230:233], v[36:51]
	global_load_dwordx4 v[198:201], v[158:159], off offset:1792
	s_waitcnt lgkmcnt(1)
	v_mfma_f32_32x32x16_bf16 v[4:19], v[214:217], v[230:233], v[4:19]
	global_load_dwordx4 v[174:177], v[156:157], off offset:1792
	ds_read_b128 v[230:233], v197 offset:41568
	ds_read_b128 v[202:205], v196 offset:4672
	v_mfma_f32_32x32x16_bf16 v[20:35], v[210:213], v[218:221], v[20:35]
	global_load_dwordx4 v[178:181], v[154:155], off offset:1792
	ds_read_b128 v[218:221], v196 offset:4704
	ds_read_b128 v[210:213], v196 offset:64
	s_waitcnt lgkmcnt(4)
	v_mfma_f32_32x32x16_bf16 v[52:67], v[206:209], v[222:225], v[52:67]
	global_load_dwordx4 v[242:245], v[152:153], off offset:1792
	ds_read_b128 v[226:229], v197 offset:36960
	ds_read_b128 v[206:209], v197 offset:41536
	v_mfma_f32_32x32x16_bf16 v[20:35], v[214:217], v[222:225], v[20:35]
	global_load_dwordx4 v[246:249], v[146:147], off offset:1792
	ds_read_b128 v[222:225], v197 offset:36928
	ds_read_b128 v[214:217], v196 offset:96
	s_waitcnt lgkmcnt(1)
	v_mfma_f32_32x32x16_bf16 v[52:67], v[210:213], v[222:225], v[52:67]
	s_waitcnt vmcnt(23)
	ds_write_b128 v167, v[68:71]
	v_mfma_f32_32x32x16_bf16 v[36:51], v[210:213], v[206:209], v[36:51]
	s_waitcnt vmcnt(22)
	ds_write_b128 v167, v[72:75] offset:36864
	v_mfma_f32_32x32x16_bf16 v[20:35], v[202:205], v[222:225], v[20:35]
	s_waitcnt vmcnt(21)
	ds_write_b128 v190, v[76:79]
	v_mfma_f32_32x32x16_bf16 v[4:19], v[202:205], v[206:209], v[4:19]
	s_waitcnt vmcnt(20)
	ds_write_b128 v190, v[80:83] offset:36864
	s_waitcnt lgkmcnt(4)
	v_mfma_f32_32x32x16_bf16 v[52:67], v[214:217], v[226:229], v[52:67]
	s_waitcnt vmcnt(19)
	ds_write_b128 v191, v[84:87]
	v_mfma_f32_32x32x16_bf16 v[36:51], v[214:217], v[230:233], v[36:51]
	s_waitcnt vmcnt(18)
	ds_write_b128 v191, v[88:91] offset:36864
	v_mfma_f32_32x32x16_bf16 v[20:35], v[218:221], v[226:229], v[20:35]
	s_waitcnt vmcnt(17)
	ds_write_b128 v192, v[92:95]
	v_mfma_f32_32x32x16_bf16 v[4:19], v[218:221], v[230:233], v[4:19]
	s_waitcnt vmcnt(16)
	ds_write_b128 v192, v[104:107] offset:36864
	s_waitcnt lgkmcnt(0)
	s_barrier
	ds_read_b128 v[202:205], v194
	ds_read_b128 v[218:221], v195 offset:36864
	ds_read_b128 v[226:229], v195 offset:41472
	ds_read_b128 v[210:213], v194 offset:4608
	ds_read_b128 v[206:209], v194 offset:32
	ds_read_b128 v[230:233], v195 offset:41504
	ds_read_b128 v[214:217], v194 offset:4640
	ds_read_b128 v[222:225], v195 offset:36896
	s_waitcnt lgkmcnt(6)
	v_mfma_f32_32x32x16_bf16 v[52:67], v[202:205], v[218:221], v[52:67]
	global_load_dwordx4 v[68:71], v[164:165], off offset:1920
	s_waitcnt lgkmcnt(5)
	v_mfma_f32_32x32x16_bf16 v[36:51], v[202:205], v[226:229], v[36:51]
	global_load_dwordx4 v[72:75], v[162:163], off offset:1920
	s_waitcnt lgkmcnt(4)
	v_mfma_f32_32x32x16_bf16 v[4:19], v[210:213], v[226:229], v[4:19]
	global_load_dwordx4 v[76:79], v[160:161], off offset:1920
	s_waitcnt lgkmcnt(2)
	v_mfma_f32_32x32x16_bf16 v[36:51], v[206:209], v[230:233], v[36:51]
	global_load_dwordx4 v[80:83], v[158:159], off offset:1920
	s_waitcnt lgkmcnt(1)
	v_mfma_f32_32x32x16_bf16 v[4:19], v[214:217], v[230:233], v[4:19]
	global_load_dwordx4 v[84:87], v[156:157], off offset:1920
	ds_read_b128 v[230:233], v195 offset:41568
	ds_read_b128 v[202:205], v194 offset:4672
	v_mfma_f32_32x32x16_bf16 v[20:35], v[210:213], v[218:221], v[20:35]
	global_load_dwordx4 v[88:91], v[154:155], off offset:1920
	ds_read_b128 v[218:221], v194 offset:4704
	ds_read_b128 v[210:213], v194 offset:64
	s_waitcnt lgkmcnt(4)
	v_mfma_f32_32x32x16_bf16 v[52:67], v[206:209], v[222:225], v[52:67]
	global_load_dwordx4 v[92:95], v[152:153], off offset:1920
	ds_read_b128 v[226:229], v195 offset:36960
	ds_read_b128 v[206:209], v195 offset:41536
	v_mfma_f32_32x32x16_bf16 v[20:35], v[214:217], v[222:225], v[20:35]
	global_load_dwordx4 v[104:107], v[146:147], off offset:1920
	ds_read_b128 v[222:225], v195 offset:36928
	ds_read_b128 v[214:217], v194 offset:96
	s_waitcnt lgkmcnt(1)
	v_mfma_f32_32x32x16_bf16 v[52:67], v[210:213], v[222:225], v[52:67]
	s_waitcnt vmcnt(23)
	ds_write_b128 v167, v[96:99] offset:18432
	v_mfma_f32_32x32x16_bf16 v[36:51], v[210:213], v[206:209], v[36:51]
	s_waitcnt vmcnt(22)
	ds_write_b128 v167, v[100:103] offset:55296
	v_mfma_f32_32x32x16_bf16 v[20:35], v[202:205], v[222:225], v[20:35]
	s_waitcnt vmcnt(21)
	ds_write_b128 v190, v[108:111] offset:18432
	v_mfma_f32_32x32x16_bf16 v[4:19], v[202:205], v[206:209], v[4:19]
	s_waitcnt vmcnt(20)
	ds_write_b128 v190, v[112:115] offset:55296
	s_waitcnt lgkmcnt(4)
	v_mfma_f32_32x32x16_bf16 v[52:67], v[214:217], v[226:229], v[52:67]
	s_waitcnt vmcnt(19)
	ds_write_b128 v191, v[116:119] offset:18432
	v_mfma_f32_32x32x16_bf16 v[36:51], v[214:217], v[230:233], v[36:51]
	s_waitcnt vmcnt(18)
	ds_write_b128 v191, v[120:123] offset:55296
	v_mfma_f32_32x32x16_bf16 v[20:35], v[218:221], v[226:229], v[20:35]
	s_waitcnt vmcnt(17)
	ds_write_b128 v192, v[124:127] offset:18432
	v_mfma_f32_32x32x16_bf16 v[4:19], v[218:221], v[230:233], v[4:19]
	s_waitcnt vmcnt(16)
	ds_write_b128 v192, v[128:131] offset:55296
	s_waitcnt lgkmcnt(0)
	s_barrier
; template <class Epi, class ColV>
; DI void gemm_tile(const bf16_t* __restrict__ A, int lda, const bf16_t* __restrict__ Bt, int ldb, int K, int m0, int n0, unsigned char* smem, Epi epi, ColV colv, const bf16_t* __restrict__ HYT = nullptr) {
;     ...
;     auto step = [&](int kt, u32x4 (&ldset)[8], const u32x4 (&stset)[8]) {
;         const int buf = kt & 1;
;         if (kt + 2 < nk) gload(ldset, kt + 2);
;         const bf16_t* Ab = As + (buf * 128 + 64 * wr + li) * LS + 8 * lh;
;         const bf16_t* Bb = Bs + (buf * 128 + 64 * wc + li) * LS + 8 * lh;
;         bf16x8 fa[2][2], fb[2][2], ga[2][2], gb[2][2];
; #pragma unroll
;         for (int k2 = 0; k2 < 2; ++k2) { fa[k2][0] = ld8(Ab + 16 * k2); fa[k2][1] = ld8(Ab + 32 * LS + 16 * k2); fb[k2][0] = ld8(Bb + 16 * k2); fb[k2][1] = ld8(Bb + 32 * LS + 16 * k2); }
;         __builtin_amdgcn_sched_barrier(0);
; #pragma unroll
;         for (int k2 = 0; k2 < 2; ++k2) {
;             acc[0][0] = MFMA(fa[k2][0], fb[k2][0], acc[0][0]); acc[0][1] = MFMA(fa[k2][0], fb[k2][1], acc[0][1]);
;             acc[1][0] = MFMA(fa[k2][1], fb[k2][0], acc[1][0]); acc[1][1] = MFMA(fa[k2][1], fb[k2][1], acc[1][1]);
;         }
; #pragma unroll
;         for (int k2 = 0; k2 < 2; ++k2) { const int ks = 2 + k2; ga[k2][0] = ld8(Ab + 16 * ks); ga[k2][1] = ld8(Ab + 32 * LS + 16 * ks); gb[k2][0] = ld8(Bb + 16 * ks); gb[k2][1] = ld8(Bb + 32 * LS + 16 * ks); }
; #pragma unroll
;         for (int k2 = 0; k2 < 2; ++k2) {
;             acc[0][0] = MFMA(ga[k2][0], gb[k2][0], acc[0][0]); acc[0][1] = MFMA(ga[k2][0], gb[k2][1], acc[0][1]);
;             acc[1][0] = MFMA(ga[k2][1], gb[k2][0], acc[1][0]); acc[1][1] = MFMA(ga[k2][1], gb[k2][1], acc[1][1]);
;         }
;         if (kt + 1 < nk) sstore(stset, buf ^ 1, kt + 1);
; #pragma unroll
;         for (int i = 0; i < 8; ++i) { __builtin_amdgcn_sched_group_barrier(0x008, 1, 0); __builtin_amdgcn_sched_group_barrier(0x100, 1, 0); }
; #pragma unroll
;         for (int i = 0; i < 8; ++i) { __builtin_amdgcn_sched_group_barrier(0x008, 1, 0); __builtin_amdgcn_sched_group_barrier(0x200, 1, 0); }
;         __builtin_amdgcn_sched_barrier(0);
;         __syncthreads();
;     };
;     gload(R0, 0); gload(R1, 1);
;     sstore(R0, 0, 0); __syncthreads();
;     for (int kt = 0; kt < nk; kt += 2) {
;         step(kt, R0, R1);
;         if (kt + 1 < nk) step(kt + 1, R1, R0);
;     }
	ds_read_b128 v[202:205], v196
	ds_read_b128 v[218:221], v197 offset:36864
	ds_read_b128 v[226:229], v197 offset:41472
	ds_read_b128 v[210:213], v196 offset:4608
	ds_read_b128 v[206:209], v196 offset:32
	ds_read_b128 v[230:233], v197 offset:41504
	ds_read_b128 v[214:217], v196 offset:4640
	ds_read_b128 v[222:225], v197 offset:36896
	s_waitcnt lgkmcnt(6)
	v_mfma_f32_32x32x16_bf16 v[52:67], v[202:205], v[218:221], v[52:67]
	s_waitcnt lgkmcnt(5)
	v_mfma_f32_32x32x16_bf16 v[36:51], v[202:205], v[226:229], v[36:51]
	s_waitcnt lgkmcnt(4)
	v_mfma_f32_32x32x16_bf16 v[4:19], v[210:213], v[226:229], v[4:19]
	s_waitcnt lgkmcnt(2)
	v_mfma_f32_32x32x16_bf16 v[36:51], v[206:209], v[230:233], v[36:51]
	s_waitcnt lgkmcnt(1)
	v_mfma_f32_32x32x16_bf16 v[4:19], v[214:217], v[230:233], v[4:19]
	ds_read_b128 v[230:233], v197 offset:41568
	ds_read_b128 v[202:205], v196 offset:4672
	v_mfma_f32_32x32x16_bf16 v[20:35], v[210:213], v[218:221], v[20:35]
	ds_read_b128 v[218:221], v196 offset:4704
	ds_read_b128 v[210:213], v196 offset:64
	s_waitcnt lgkmcnt(4)
	v_mfma_f32_32x32x16_bf16 v[52:67], v[206:209], v[222:225], v[52:67]
	ds_read_b128 v[226:229], v197 offset:36960
	ds_read_b128 v[206:209], v197 offset:41536
	v_mfma_f32_32x32x16_bf16 v[20:35], v[214:217], v[222:225], v[20:35]
	ds_read_b128 v[222:225], v197 offset:36928
	ds_read_b128 v[214:217], v196 offset:96
	s_waitcnt lgkmcnt(1)
	v_mfma_f32_32x32x16_bf16 v[52:67], v[210:213], v[222:225], v[52:67]
	s_waitcnt vmcnt(15)
	ds_write_b128 v167, v[132:135]
	v_mfma_f32_32x32x16_bf16 v[36:51], v[210:213], v[206:209], v[36:51]
	s_waitcnt vmcnt(14)
	ds_write_b128 v167, v[136:139] offset:36864
	v_mfma_f32_32x32x16_bf16 v[20:35], v[202:205], v[222:225], v[20:35]
	s_waitcnt vmcnt(13)
	ds_write_b128 v190, v[140:143]
	v_mfma_f32_32x32x16_bf16 v[4:19], v[202:205], v[206:209], v[4:19]
	s_waitcnt vmcnt(12)
	ds_write_b128 v190, v[198:201] offset:36864
	s_waitcnt lgkmcnt(4)
	v_mfma_f32_32x32x16_bf16 v[52:67], v[214:217], v[226:229], v[52:67]
	s_waitcnt vmcnt(11)
	ds_write_b128 v191, v[174:177]
	v_mfma_f32_32x32x16_bf16 v[36:51], v[214:217], v[230:233], v[36:51]
	s_waitcnt vmcnt(10)
	ds_write_b128 v191, v[178:181] offset:36864
	v_mfma_f32_32x32x16_bf16 v[20:35], v[218:221], v[226:229], v[20:35]
	s_waitcnt vmcnt(9)
	ds_write_b128 v192, v[242:245]
	v_mfma_f32_32x32x16_bf16 v[4:19], v[218:221], v[230:233], v[4:19]
	s_waitcnt vmcnt(8)
	ds_write_b128 v192, v[246:249] offset:36864
	s_waitcnt lgkmcnt(0)
	s_barrier
	ds_read_b128 v[202:205], v194
	ds_read_b128 v[218:221], v195 offset:36864
	ds_read_b128 v[226:229], v195 offset:41472
	ds_read_b128 v[210:213], v194 offset:4608
	ds_read_b128 v[206:209], v194 offset:32
	ds_read_b128 v[230:233], v195 offset:41504
	ds_read_b128 v[214:217], v194 offset:4640
	ds_read_b128 v[222:225], v195 offset:36896
	s_waitcnt lgkmcnt(6)
	v_mfma_f32_32x32x16_bf16 v[52:67], v[202:205], v[218:221], v[52:67]
	s_waitcnt lgkmcnt(5)
	v_mfma_f32_32x32x16_bf16 v[36:51], v[202:205], v[226:229], v[36:51]
	s_waitcnt lgkmcnt(4)
	v_mfma_f32_32x32x16_bf16 v[4:19], v[210:213], v[226:229], v[4:19]
	s_waitcnt lgkmcnt(2)
	v_mfma_f32_32x32x16_bf16 v[36:51], v[206:209], v[230:233], v[36:51]
	s_waitcnt lgkmcnt(1)
	v_mfma_f32_32x32x16_bf16 v[4:19], v[214:217], v[230:233], v[4:19]
	ds_read_b128 v[230:233], v195 offset:41568
	ds_read_b128 v[202:205], v194 offset:4672
	v_mfma_f32_32x32x16_bf16 v[20:35], v[210:213], v[218:221], v[20:35]
	ds_read_b128 v[218:221], v194 offset:4704
	ds_read_b128 v[210:213], v194 offset:64
	s_waitcnt lgkmcnt(4)
	v_mfma_f32_32x32x16_bf16 v[52:67], v[206:209], v[222:225], v[52:67]
	ds_read_b128 v[226:229], v195 offset:36960
	ds_read_b128 v[206:209], v195 offset:41536
	v_mfma_f32_32x32x16_bf16 v[20:35], v[214:217], v[222:225], v[20:35]
	ds_read_b128 v[222:225], v195 offset:36928
	ds_read_b128 v[214:217], v194 offset:96
	s_waitcnt lgkmcnt(1)
	v_mfma_f32_32x32x16_bf16 v[52:67], v[210:213], v[222:225], v[52:67]
	s_waitcnt vmcnt(7)
	ds_write_b128 v167, v[68:71] offset:18432
	v_mfma_f32_32x32x16_bf16 v[36:51], v[210:213], v[206:209], v[36:51]
	s_waitcnt vmcnt(6)
	ds_write_b128 v167, v[72:75] offset:55296
	v_mfma_f32_32x32x16_bf16 v[20:35], v[202:205], v[222:225], v[20:35]
	s_waitcnt vmcnt(5)
	ds_write_b128 v190, v[76:79] offset:18432
	v_mfma_f32_32x32x16_bf16 v[4:19], v[202:205], v[206:209], v[4:19]
	s_waitcnt vmcnt(4)
	ds_write_b128 v190, v[80:83] offset:55296
	s_waitcnt lgkmcnt(4)
	v_mfma_f32_32x32x16_bf16 v[52:67], v[214:217], v[226:229], v[52:67]
	s_waitcnt vmcnt(3)
	ds_write_b128 v191, v[84:87] offset:18432
	v_mfma_f32_32x32x16_bf16 v[36:51], v[214:217], v[230:233], v[36:51]
	s_waitcnt vmcnt(2)
	ds_write_b128 v191, v[88:91] offset:55296
	v_mfma_f32_32x32x16_bf16 v[20:35], v[218:221], v[226:229], v[20:35]
	s_waitcnt vmcnt(1)
	ds_write_b128 v192, v[92:95] offset:18432
	v_mfma_f32_32x32x16_bf16 v[4:19], v[218:221], v[230:233], v[4:19]
	s_waitcnt vmcnt(0)
	ds_write_b128 v192, v[104:107] offset:55296
	s_waitcnt lgkmcnt(0)
	s_barrier
	ds_read_b128 v[202:205], v196
	ds_read_b128 v[218:221], v197 offset:36864
	ds_read_b128 v[226:229], v197 offset:41472
	ds_read_b128 v[210:213], v196 offset:4608
	ds_read_b128 v[206:209], v196 offset:32
	ds_read_b128 v[230:233], v197 offset:41504
	ds_read_b128 v[214:217], v196 offset:4640
	ds_read_b128 v[222:225], v197 offset:36896
	s_waitcnt lgkmcnt(6)
	v_mfma_f32_32x32x16_bf16 v[52:67], v[202:205], v[218:221], v[52:67]
	s_waitcnt lgkmcnt(5)
	v_mfma_f32_32x32x16_bf16 v[36:51], v[202:205], v[226:229], v[36:51]
	s_waitcnt lgkmcnt(4)
	v_mfma_f32_32x32x16_bf16 v[4:19], v[210:213], v[226:229], v[4:19]
	s_waitcnt lgkmcnt(2)
	v_mfma_f32_32x32x16_bf16 v[36:51], v[206:209], v[230:233], v[36:51]
	s_waitcnt lgkmcnt(1)
	v_mfma_f32_32x32x16_bf16 v[4:19], v[214:217], v[230:233], v[4:19]
	ds_read_b128 v[230:233], v197 offset:41568
	ds_read_b128 v[202:205], v196 offset:4672
	v_mfma_f32_32x32x16_bf16 v[20:35], v[210:213], v[218:221], v[20:35]
	ds_read_b128 v[218:221], v196 offset:4704
	ds_read_b128 v[210:213], v196 offset:64
	s_waitcnt lgkmcnt(4)
	v_mfma_f32_32x32x16_bf16 v[52:67], v[206:209], v[222:225], v[52:67]
	ds_read_b128 v[226:229], v197 offset:36960
	ds_read_b128 v[206:209], v197 offset:41536
	v_mfma_f32_32x32x16_bf16 v[20:35], v[214:217], v[222:225], v[20:35]
	ds_read_b128 v[222:225], v197 offset:36928
	ds_read_b128 v[214:217], v196 offset:96
	s_waitcnt lgkmcnt(1)
	v_mfma_f32_32x32x16_bf16 v[52:67], v[210:213], v[222:225], v[52:67]
	v_mfma_f32_32x32x16_bf16 v[36:51], v[210:213], v[206:209], v[36:51]
	v_mfma_f32_32x32x16_bf16 v[20:35], v[202:205], v[222:225], v[20:35]
	v_mfma_f32_32x32x16_bf16 v[4:19], v[202:205], v[206:209], v[4:19]
	s_waitcnt lgkmcnt(0)
	v_mfma_f32_32x32x16_bf16 v[52:67], v[214:217], v[226:229], v[52:67]
	v_mfma_f32_32x32x16_bf16 v[36:51], v[214:217], v[230:233], v[36:51]
	v_mfma_f32_32x32x16_bf16 v[20:35], v[218:221], v[226:229], v[20:35]
	v_mfma_f32_32x32x16_bf16 v[4:19], v[218:221], v[230:233], v[4:19]
	s_waitcnt lgkmcnt(0)
	s_barrier
	s_nop 7
	s_nop 3
	s_branch .LBB0_1555
